# GEMM loops: remaining m0-hazard nops replaced by reordered ds_read / scalar base adds (20 fewer nops over the 8 loops)
# speedup vs baseline: 1.0040x; 1.0009x over previous
.LBB0_96:
	s_add_u32 s0, s40, 0xfffc0080
	s_addc_u32 s1, s41, -1
	s_add_i32 s2, 0, 0x10000
	ds_read_b128 v[156:159], v236
	ds_read_b128 v[160:163], v236 offset:1024
	ds_read_b128 v[164:167], v236 offset:2048
	ds_read_b128 v[168:171], v236 offset:3072
	s_cmp_eq_u32 s72, 12
	s_cselect_b32 s45, s13, s1
	s_cselect_b32 s44, s12, s0
	s_cselect_b32 s1, s15, s11
	s_cselect_b32 s0, s14, s9
	s_add_i32 m0, s17, 0xc000
	ds_read_b128 v[172:175], v155
	ds_read_b128 v[176:179], v155 offset:1024
	ds_read_b128 v[180:183], v155 offset:2048
	ds_read_b128 v[184:187], v155 offset:3072
	ds_read_b128 v[188:191], v155 offset:4096
	ds_read_b128 v[192:195], v155 offset:5120
	ds_read_b128 v[196:199], v155 offset:6144
	global_load_lds_dwordx4 v136, s[40:41]
	s_add_i32 m0, s17, 0xe000
	ds_read_b128 v[200:203], v155 offset:7168
	global_load_lds_dwordx4 v134, s[40:41]
	s_waitcnt lgkmcnt(8)
	s_barrier
	s_waitcnt lgkmcnt(0)
	s_setprio 1
	v_mfma_f32_16x16x32_bf16 v[124:127], v[156:159], v[172:175], v[124:127]
	v_mfma_f32_16x16x32_bf16 v[120:123], v[164:167], v[172:175], v[120:123]
	v_mfma_f32_16x16x32_bf16 v[116:119], v[156:159], v[180:183], v[116:119]
	v_mfma_f32_16x16x32_bf16 v[108:111], v[164:167], v[180:183], v[108:111]
	v_mfma_f32_16x16x32_bf16 v[100:103], v[156:159], v[188:191], v[100:103]
	v_mfma_f32_16x16x32_bf16 v[92:95], v[164:167], v[188:191], v[92:95]
	v_mfma_f32_16x16x32_bf16 v[84:87], v[156:159], v[196:199], v[84:87]
	v_mfma_f32_16x16x32_bf16 v[76:79], v[164:167], v[196:199], v[76:79]
	v_mfma_f32_16x16x32_bf16 v[124:127], v[160:163], v[176:179], v[124:127]
	v_mfma_f32_16x16x32_bf16 v[120:123], v[168:171], v[176:179], v[120:123]
	v_mfma_f32_16x16x32_bf16 v[116:119], v[160:163], v[184:187], v[116:119]
	v_mfma_f32_16x16x32_bf16 v[108:111], v[168:171], v[184:187], v[108:111]
	v_mfma_f32_16x16x32_bf16 v[100:103], v[160:163], v[192:195], v[100:103]
	v_mfma_f32_16x16x32_bf16 v[92:95], v[168:171], v[192:195], v[92:95]
	v_mfma_f32_16x16x32_bf16 v[84:87], v[160:163], v[200:203], v[84:87]
	v_mfma_f32_16x16x32_bf16 v[76:79], v[168:171], v[200:203], v[76:79]
	s_setprio 0
	s_barrier
	s_add_i32 s30, 0, 0x14000
	s_add_i32 s2, s2, s59
	ds_read_b128 v[204:207], v237
	ds_read_b128 v[208:211], v237 offset:1024
	s_mov_b32 m0, s2
	ds_read_b128 v[228:231], v237 offset:2048
	global_load_lds_dwordx4 v140, s[0:1]
	s_add_i32 m0, s2, 0x2000
	ds_read_b128 v[232:235], v237 offset:3072
	global_load_lds_dwordx4 v132, s[0:1]
	s_barrier
	s_waitcnt lgkmcnt(0)
	s_setprio 1
	v_mfma_f32_16x16x32_bf16 v[112:115], v[204:207], v[172:175], v[112:115]
	v_mfma_f32_16x16x32_bf16 v[104:107], v[228:231], v[172:175], v[104:107]
	v_mfma_f32_16x16x32_bf16 v[96:99], v[204:207], v[180:183], v[96:99]
	v_mfma_f32_16x16x32_bf16 v[88:91], v[228:231], v[180:183], v[88:91]
	v_mfma_f32_16x16x32_bf16 v[80:83], v[204:207], v[188:191], v[80:83]
	v_mfma_f32_16x16x32_bf16 v[72:75], v[228:231], v[188:191], v[72:75]
	v_mfma_f32_16x16x32_bf16 v[68:71], v[204:207], v[196:199], v[68:71]
	v_mfma_f32_16x16x32_bf16 v[64:67], v[228:231], v[196:199], v[64:67]
	v_mfma_f32_16x16x32_bf16 v[112:115], v[208:211], v[176:179], v[112:115]
	v_mfma_f32_16x16x32_bf16 v[104:107], v[232:235], v[176:179], v[104:107]
	v_mfma_f32_16x16x32_bf16 v[96:99], v[208:211], v[184:187], v[96:99]
	v_mfma_f32_16x16x32_bf16 v[88:91], v[232:235], v[184:187], v[88:91]
	v_mfma_f32_16x16x32_bf16 v[80:83], v[208:211], v[192:195], v[80:83]
	v_mfma_f32_16x16x32_bf16 v[72:75], v[232:235], v[192:195], v[72:75]
	v_mfma_f32_16x16x32_bf16 v[68:71], v[208:211], v[200:203], v[68:71]
	v_mfma_f32_16x16x32_bf16 v[64:67], v[232:235], v[200:203], v[64:67]
	s_setprio 0
	s_mov_b32 m0, s17
	s_barrier
	ds_read_b128 v[172:175], v155 offset:16384
	ds_read_b128 v[176:179], v155 offset:17408
	ds_read_b128 v[180:183], v155 offset:18432
	ds_read_b128 v[184:187], v155 offset:19456
	ds_read_b128 v[188:191], v155 offset:20480
	ds_read_b128 v[192:195], v155 offset:21504
	ds_read_b128 v[196:199], v155 offset:22528
	global_load_lds_dwordx4 v128, s[44:45]
	s_mov_b32 m0, s64
	ds_read_b128 v[200:203], v155 offset:23552
	global_load_lds_dwordx4 v130, s[44:45]
	s_barrier
	s_waitcnt lgkmcnt(0)
	s_setprio 1
	v_mfma_f32_16x16x32_bf16 v[60:63], v[156:159], v[172:175], v[60:63]
	v_mfma_f32_16x16x32_bf16 v[56:59], v[164:167], v[172:175], v[56:59]
	v_mfma_f32_16x16x32_bf16 v[52:55], v[156:159], v[180:183], v[52:55]
	v_mfma_f32_16x16x32_bf16 v[44:47], v[164:167], v[180:183], v[44:47]
	v_mfma_f32_16x16x32_bf16 v[36:39], v[156:159], v[188:191], v[36:39]
	v_mfma_f32_16x16x32_bf16 v[28:31], v[164:167], v[188:191], v[28:31]
	v_mfma_f32_16x16x32_bf16 v[20:23], v[156:159], v[196:199], v[20:23]
	v_mfma_f32_16x16x32_bf16 v[12:15], v[164:167], v[196:199], v[12:15]
	v_mfma_f32_16x16x32_bf16 v[60:63], v[160:163], v[176:179], v[60:63]
	v_mfma_f32_16x16x32_bf16 v[56:59], v[168:171], v[176:179], v[56:59]
	v_mfma_f32_16x16x32_bf16 v[52:55], v[160:163], v[184:187], v[52:55]
	v_mfma_f32_16x16x32_bf16 v[44:47], v[168:171], v[184:187], v[44:47]
	v_mfma_f32_16x16x32_bf16 v[36:39], v[160:163], v[192:195], v[36:39]
	v_mfma_f32_16x16x32_bf16 v[28:31], v[168:171], v[192:195], v[28:31]
	v_mfma_f32_16x16x32_bf16 v[20:23], v[160:163], v[200:203], v[20:23]
	v_mfma_f32_16x16x32_bf16 v[12:15], v[168:171], v[200:203], v[12:15]
	s_setprio 0
	s_barrier
	s_add_i32 s2, s30, s59
	s_mov_b32 m0, s2
	s_add_u32 s18, s0, 0x40000
	s_addc_u32 s19, s1, 0
	global_load_lds_dwordx4 v140, s[18:19]
	s_add_i32 m0, s2, 0x2000
	s_nop 0
	global_load_lds_dwordx4 v132, s[18:19]
	s_waitcnt vmcnt(6)
	s_barrier
	s_setprio 1
	v_mfma_f32_16x16x32_bf16 v[48:51], v[204:207], v[172:175], v[48:51]
	v_mfma_f32_16x16x32_bf16 v[40:43], v[228:231], v[172:175], v[40:43]
	v_mfma_f32_16x16x32_bf16 v[32:35], v[204:207], v[180:183], v[32:35]
	v_mfma_f32_16x16x32_bf16 v[24:27], v[228:231], v[180:183], v[24:27]
	v_mfma_f32_16x16x32_bf16 v[16:19], v[204:207], v[188:191], v[16:19]
	v_mfma_f32_16x16x32_bf16 v[8:11], v[228:231], v[188:191], v[8:11]
	v_mfma_f32_16x16x32_bf16 v[4:7], v[204:207], v[196:199], v[4:7]
	v_mfma_f32_16x16x32_bf16 v[0:3], v[228:231], v[196:199], v[0:3]
	v_mfma_f32_16x16x32_bf16 v[48:51], v[208:211], v[176:179], v[48:51]
	v_mfma_f32_16x16x32_bf16 v[40:43], v[232:235], v[176:179], v[40:43]
	v_mfma_f32_16x16x32_bf16 v[32:35], v[208:211], v[184:187], v[32:35]
	v_mfma_f32_16x16x32_bf16 v[24:27], v[232:235], v[184:187], v[24:27]
	v_mfma_f32_16x16x32_bf16 v[16:19], v[208:211], v[192:195], v[16:19]
	v_mfma_f32_16x16x32_bf16 v[8:11], v[232:235], v[192:195], v[8:11]
	v_mfma_f32_16x16x32_bf16 v[4:7], v[208:211], v[200:203], v[4:7]
	v_mfma_f32_16x16x32_bf16 v[0:3], v[232:235], v[200:203], v[0:3]
	s_setprio 0
	s_add_i32 s2, 0, 0x18000
	s_barrier
	ds_read_b128 v[156:159], v238
	ds_read_b128 v[160:163], v238 offset:1024
	ds_read_b128 v[164:167], v238 offset:2048
	ds_read_b128 v[168:171], v238 offset:3072
	s_add_u32 s18, s44, 0x40000
	s_addc_u32 s19, s45, 0
	s_mov_b32 m0, s65
	ds_read_b128 v[172:175], v155 offset:32768
	ds_read_b128 v[176:179], v155 offset:33792
	ds_read_b128 v[180:183], v155 offset:34816
	ds_read_b128 v[184:187], v155 offset:35840
	ds_read_b128 v[188:191], v155 offset:36864
	ds_read_b128 v[192:195], v155 offset:37888
	ds_read_b128 v[196:199], v155 offset:38912
	global_load_lds_dwordx4 v128, s[18:19]
	s_mov_b32 m0, s66
	ds_read_b128 v[200:203], v155 offset:39936
	global_load_lds_dwordx4 v130, s[18:19]
	s_waitcnt lgkmcnt(8)
	s_barrier
	s_waitcnt lgkmcnt(0)
	s_setprio 1
	v_mfma_f32_16x16x32_bf16 v[124:127], v[156:159], v[172:175], v[124:127]
	v_mfma_f32_16x16x32_bf16 v[120:123], v[164:167], v[172:175], v[120:123]
	v_mfma_f32_16x16x32_bf16 v[116:119], v[156:159], v[180:183], v[116:119]
	v_mfma_f32_16x16x32_bf16 v[108:111], v[164:167], v[180:183], v[108:111]
	v_mfma_f32_16x16x32_bf16 v[100:103], v[156:159], v[188:191], v[100:103]
	v_mfma_f32_16x16x32_bf16 v[92:95], v[164:167], v[188:191], v[92:95]
	v_mfma_f32_16x16x32_bf16 v[84:87], v[156:159], v[196:199], v[84:87]
	v_mfma_f32_16x16x32_bf16 v[76:79], v[164:167], v[196:199], v[76:79]
	v_mfma_f32_16x16x32_bf16 v[124:127], v[160:163], v[176:179], v[124:127]
	v_mfma_f32_16x16x32_bf16 v[120:123], v[168:171], v[176:179], v[120:123]
	v_mfma_f32_16x16x32_bf16 v[116:119], v[160:163], v[184:187], v[116:119]
	v_mfma_f32_16x16x32_bf16 v[108:111], v[168:171], v[184:187], v[108:111]
	v_mfma_f32_16x16x32_bf16 v[100:103], v[160:163], v[192:195], v[100:103]
	v_mfma_f32_16x16x32_bf16 v[92:95], v[168:171], v[192:195], v[92:95]
	v_mfma_f32_16x16x32_bf16 v[84:87], v[160:163], v[200:203], v[84:87]
	v_mfma_f32_16x16x32_bf16 v[76:79], v[168:171], v[200:203], v[76:79]
	s_setprio 0
	s_barrier
	s_add_i32 s18, 0, 0x1c000
	s_add_i32 s2, s2, s59
	s_mov_b32 m0, s2
	ds_read_b128 v[204:207], v239
	ds_read_b128 v[208:211], v239 offset:1024
	ds_read_b128 v[228:231], v239 offset:2048
	ds_read_b128 v[232:235], v239 offset:3072
	s_add_u32 s100, s0, 0x80
	s_addc_u32 s101, s1, 0
	global_load_lds_dwordx4 v140, s[100:101]
	s_add_i32 m0, s2, 0x2000
	s_nop 0
	global_load_lds_dwordx4 v132, s[100:101]
	s_barrier
	s_waitcnt lgkmcnt(0)
	s_setprio 1
	v_mfma_f32_16x16x32_bf16 v[112:115], v[204:207], v[172:175], v[112:115]
	v_mfma_f32_16x16x32_bf16 v[104:107], v[228:231], v[172:175], v[104:107]
	v_mfma_f32_16x16x32_bf16 v[96:99], v[204:207], v[180:183], v[96:99]
	v_mfma_f32_16x16x32_bf16 v[88:91], v[228:231], v[180:183], v[88:91]
	v_mfma_f32_16x16x32_bf16 v[80:83], v[204:207], v[188:191], v[80:83]
	v_mfma_f32_16x16x32_bf16 v[72:75], v[228:231], v[188:191], v[72:75]
	v_mfma_f32_16x16x32_bf16 v[68:71], v[204:207], v[196:199], v[68:71]
	v_mfma_f32_16x16x32_bf16 v[64:67], v[228:231], v[196:199], v[64:67]
	v_mfma_f32_16x16x32_bf16 v[112:115], v[208:211], v[176:179], v[112:115]
	v_mfma_f32_16x16x32_bf16 v[104:107], v[232:235], v[176:179], v[104:107]
	v_mfma_f32_16x16x32_bf16 v[96:99], v[208:211], v[184:187], v[96:99]
	v_mfma_f32_16x16x32_bf16 v[88:91], v[232:235], v[184:187], v[88:91]
	v_mfma_f32_16x16x32_bf16 v[80:83], v[208:211], v[192:195], v[80:83]
	v_mfma_f32_16x16x32_bf16 v[72:75], v[232:235], v[192:195], v[72:75]
	v_mfma_f32_16x16x32_bf16 v[68:71], v[208:211], v[200:203], v[68:71]
	v_mfma_f32_16x16x32_bf16 v[64:67], v[232:235], v[200:203], v[64:67]
	s_setprio 0
	s_mov_b32 m0, s69
	s_barrier
	ds_read_b128 v[172:175], v155 offset:49152
	ds_read_b128 v[176:179], v155 offset:50176
	ds_read_b128 v[180:183], v155 offset:51200
	ds_read_b128 v[184:187], v155 offset:52224
	ds_read_b128 v[188:191], v155 offset:53248
	ds_read_b128 v[192:195], v155 offset:54272
	ds_read_b128 v[196:199], v155 offset:55296
	ds_read_b128 v[200:203], v155 offset:56320
	s_add_u32 s100, s44, 0x80
	s_addc_u32 s101, s45, 0
	global_load_lds_dwordx4 v128, s[100:101]
	s_mov_b32 m0, s71
	s_nop 0
	global_load_lds_dwordx4 v130, s[100:101]
	s_barrier
	s_waitcnt lgkmcnt(0)
	s_setprio 1
	v_mfma_f32_16x16x32_bf16 v[60:63], v[156:159], v[172:175], v[60:63]
	v_mfma_f32_16x16x32_bf16 v[56:59], v[164:167], v[172:175], v[56:59]
	v_mfma_f32_16x16x32_bf16 v[52:55], v[156:159], v[180:183], v[52:55]
	v_mfma_f32_16x16x32_bf16 v[44:47], v[164:167], v[180:183], v[44:47]
	v_mfma_f32_16x16x32_bf16 v[36:39], v[156:159], v[188:191], v[36:39]
	v_mfma_f32_16x16x32_bf16 v[28:31], v[164:167], v[188:191], v[28:31]
	v_mfma_f32_16x16x32_bf16 v[20:23], v[156:159], v[196:199], v[20:23]
	v_mfma_f32_16x16x32_bf16 v[12:15], v[164:167], v[196:199], v[12:15]
	v_mfma_f32_16x16x32_bf16 v[60:63], v[160:163], v[176:179], v[60:63]
	v_mfma_f32_16x16x32_bf16 v[56:59], v[168:171], v[176:179], v[56:59]
	v_mfma_f32_16x16x32_bf16 v[52:55], v[160:163], v[184:187], v[52:55]
	v_mfma_f32_16x16x32_bf16 v[44:47], v[168:171], v[184:187], v[44:47]
	v_mfma_f32_16x16x32_bf16 v[36:39], v[160:163], v[192:195], v[36:39]
	v_mfma_f32_16x16x32_bf16 v[28:31], v[168:171], v[192:195], v[28:31]
	v_mfma_f32_16x16x32_bf16 v[20:23], v[160:163], v[200:203], v[20:23]
	v_mfma_f32_16x16x32_bf16 v[12:15], v[168:171], v[200:203], v[12:15]
	s_setprio 0
	s_barrier
	s_add_i32 s2, s18, s59
	s_mov_b32 m0, s2
	s_add_u32 s0, s0, 0x40080
	s_addc_u32 s1, s1, 0
	global_load_lds_dwordx4 v140, s[0:1]
	s_add_i32 m0, s2, 0x2000
	s_nop 0
	global_load_lds_dwordx4 v132, s[0:1]
	s_waitcnt vmcnt(6)
	s_barrier
	s_setprio 1
	v_mfma_f32_16x16x32_bf16 v[48:51], v[204:207], v[172:175], v[48:51]
	v_mfma_f32_16x16x32_bf16 v[40:43], v[228:231], v[172:175], v[40:43]
	v_mfma_f32_16x16x32_bf16 v[32:35], v[204:207], v[180:183], v[32:35]
	v_mfma_f32_16x16x32_bf16 v[24:27], v[228:231], v[180:183], v[24:27]
	v_mfma_f32_16x16x32_bf16 v[16:19], v[204:207], v[188:191], v[16:19]
	v_mfma_f32_16x16x32_bf16 v[8:11], v[228:231], v[188:191], v[8:11]
	v_mfma_f32_16x16x32_bf16 v[4:7], v[204:207], v[196:199], v[4:7]
	v_mfma_f32_16x16x32_bf16 v[0:3], v[228:231], v[196:199], v[0:3]
	v_mfma_f32_16x16x32_bf16 v[48:51], v[208:211], v[176:179], v[48:51]
	v_mfma_f32_16x16x32_bf16 v[40:43], v[232:235], v[176:179], v[40:43]
	v_mfma_f32_16x16x32_bf16 v[32:35], v[208:211], v[184:187], v[32:35]
	v_mfma_f32_16x16x32_bf16 v[24:27], v[232:235], v[184:187], v[24:27]
	v_mfma_f32_16x16x32_bf16 v[16:19], v[208:211], v[192:195], v[16:19]
	v_mfma_f32_16x16x32_bf16 v[8:11], v[232:235], v[192:195], v[8:11]
	v_mfma_f32_16x16x32_bf16 v[4:7], v[208:211], v[200:203], v[4:7]
	v_mfma_f32_16x16x32_bf16 v[0:3], v[232:235], v[200:203], v[0:3]
	s_setprio 0
	s_add_i32 s72, s72, 2
	s_add_u32 s9, s9, 0x100
	s_addc_u32 s11, s11, 0
	s_add_u32 s40, s40, 0x100
	s_addc_u32 s41, s41, 0
	s_cmp_gt_u32 s72, 13
	s_barrier
	s_cbranch_scc0 .LBB0_96
	s_lshl_b32 s0, s16, 8
	v_mbcnt_lo_u32_b32 v139, -1, 0
	v_mbcnt_hi_u32_b32 v139, -1, v139
	s_lshl_b32 s1, s21, 8
	v_ashrrev_i32_e32 v138, 1, v139
	s_add_i32 s0, s0, s67
	v_and_b32_e32 v138, -8, v138
	s_or_b32 s1, s1, s68
	v_and_or_b32 v156, v139, 15, s0
	v_add_u32_e32 v138, s1, v138
	v_ashrrev_i32_e32 v157, 31, v156
	v_ashrrev_i32_e32 v139, 31, v138
	v_lshlrev_b64 v[158:159], 11, v[156:157]
	v_lshl_add_u64 v[158:159], s[26:27], 0, v[158:159]
	v_lshlrev_b64 v[160:161], 1, v[138:139]
	v_lshl_add_u64 v[138:139], v[158:159], 0, v[160:161]
	v_cvt_pk_bf16_f32 v60, v60, v61
	v_cvt_pk_bf16_f32 v61, v62, v63
	v_cvt_pk_bf16_f32 v62, v56, v57
	v_add_co_u32_e32 v56, vcc, s31, v138
	v_cvt_pk_bf16_f32 v112, v112, v113
	v_cvt_pk_bf16_f32 v113, v114, v115
	v_cvt_pk_bf16_f32 v114, v104, v105
	v_or_b32_e32 v104, 16, v156
	s_nop 0
	v_addc_co_u32_e32 v57, vcc, 0, v139, vcc
	v_cvt_pk_bf16_f32 v48, v48, v49
	v_cvt_pk_bf16_f32 v49, v50, v51
	v_cvt_pk_bf16_f32 v51, v42, v43
	v_cvt_pk_bf16_f32 v42, v44, v45
	v_add_co_u32_e32 v44, vcc, s42, v138
	v_ashrrev_i32_e32 v105, 31, v104
	v_cvt_pk_bf16_f32 v96, v96, v97
	v_cvt_pk_bf16_f32 v97, v98, v99
	v_cvt_pk_bf16_f32 v98, v88, v89
	v_or_b32_e32 v88, 32, v156
	v_addc_co_u32_e32 v45, vcc, 0, v139, vcc
	v_lshlrev_b64 v[104:105], 11, v[104:105]
	v_ashrrev_i32_e32 v89, 31, v88
	v_cvt_pk_bf16_f32 v80, v80, v81
	v_cvt_pk_bf16_f32 v81, v82, v83
	v_cvt_pk_bf16_f32 v82, v72, v73
	v_or_b32_e32 v72, 48, v156
	s_mov_b64 s[0:1], 0x40000
	v_cvt_pk_bf16_f32 v32, v32, v33
	v_cvt_pk_bf16_f32 v33, v34, v35
	v_cvt_pk_bf16_f32 v35, v26, v27
	v_cvt_pk_bf16_f32 v26, v28, v29
	v_add_co_u32_e32 v28, vcc, s43, v138
	v_lshl_add_u64 v[104:105], s[26:27], 0, v[104:105]
	v_lshlrev_b64 v[88:89], 11, v[88:89]
	v_ashrrev_i32_e32 v73, 31, v72
	v_cvt_pk_bf16_f32 v68, v68, v69
	v_cvt_pk_bf16_f32 v69, v70, v71
	v_cvt_pk_bf16_f32 v70, v64, v65
	v_lshl_add_u64 v[64:65], v[138:139], 0, s[0:1]
	s_mov_b64 s[0:1], 0x48000
	v_addc_co_u32_e32 v29, vcc, 0, v139, vcc
	v_cvt_pk_bf16_f32 v115, v106, v107
	flat_store_dwordx4 v[138:139], v[112:115] offset:256
	v_lshl_add_u64 v[88:89], s[26:27], 0, v[88:89]
	v_lshlrev_b64 v[72:73], 11, v[72:73]
	v_lshl_add_u64 v[112:113], v[104:105], 0, v[160:161]
	v_cvt_pk_bf16_f32 v50, v40, v41
	flat_store_dwordx4 v[64:65], v[48:51] offset:256
	v_cvt_pk_bf16_f32 v16, v16, v17
	v_cvt_pk_bf16_f32 v17, v18, v19
	v_cvt_pk_bf16_f32 v19, v10, v11
	v_cvt_pk_bf16_f32 v10, v12, v13
	v_add_co_u32_e32 v12, vcc, s47, v138
	s_nop 0
	v_lshl_add_u64 v[48:49], v[138:139], 0, s[0:1]
	s_mov_b64 s[0:1], 0x50000
	v_cvt_pk_bf16_f32 v99, v90, v91
	flat_store_dwordx4 v[112:113], v[96:99] offset:256
	v_lshl_add_u64 v[72:73], s[26:27], 0, v[72:73]
	v_cvt_pk_bf16_f32 v34, v24, v25
	flat_store_dwordx4 v[48:49], v[32:35] offset:256
	v_lshl_add_u64 v[96:97], v[88:89], 0, v[160:161]
	v_addc_co_u32_e32 v13, vcc, 0, v139, vcc
	v_lshl_add_u64 v[32:33], v[138:139], 0, s[0:1]
	s_mov_b64 s[0:1], 0x58000
	v_cvt_pk_bf16_f32 v83, v74, v75
	flat_store_dwordx4 v[96:97], v[80:83] offset:256
	v_cvt_pk_bf16_f32 v18, v8, v9
	flat_store_dwordx4 v[32:33], v[16:19] offset:256
	s_and_b64 vcc, exec, s[6:7]
	v_lshl_add_u64 v[80:81], v[72:73], 0, v[160:161]
	v_lshl_add_u64 v[16:17], v[138:139], 0, s[0:1]
	s_mov_b32 s21, s10
	s_mov_b32 s16, s8
	s_mov_b64 s[40:41], s[14:15]
	s_mov_b64 s[0:1], s[12:13]
	v_cvt_pk_bf16_f32 v124, v124, v125
	v_cvt_pk_bf16_f32 v125, v126, v127
	v_cvt_pk_bf16_f32 v126, v120, v121
	v_cvt_pk_bf16_f32 v127, v122, v123
	flat_store_dwordx4 v[138:139], v[124:127]
	v_cvt_pk_bf16_f32 v104, v116, v117
	v_cvt_pk_bf16_f32 v105, v118, v119
	v_cvt_pk_bf16_f32 v106, v108, v109
	v_cvt_pk_bf16_f32 v107, v110, v111
	flat_store_dwordx4 v[112:113], v[104:107]
	v_cvt_pk_bf16_f32 v88, v100, v101
	v_cvt_pk_bf16_f32 v89, v102, v103
	v_cvt_pk_bf16_f32 v90, v92, v93
	v_cvt_pk_bf16_f32 v91, v94, v95
	flat_store_dwordx4 v[96:97], v[88:91]
	v_cvt_pk_bf16_f32 v72, v84, v85
	v_cvt_pk_bf16_f32 v73, v86, v87
	v_cvt_pk_bf16_f32 v74, v76, v77
	v_cvt_pk_bf16_f32 v75, v78, v79
	flat_store_dwordx4 v[80:81], v[72:75]
	v_cvt_pk_bf16_f32 v71, v66, v67
	flat_store_dwordx4 v[80:81], v[68:71] offset:256
	v_cvt_pk_bf16_f32 v63, v58, v59
	flat_store_dwordx4 v[56:57], v[60:63]
	v_cvt_pk_bf16_f32 v40, v52, v53
	v_cvt_pk_bf16_f32 v41, v54, v55
	v_cvt_pk_bf16_f32 v43, v46, v47
	flat_store_dwordx4 v[44:45], v[40:43]
	v_cvt_pk_bf16_f32 v24, v36, v37
	v_cvt_pk_bf16_f32 v25, v38, v39
	v_cvt_pk_bf16_f32 v27, v30, v31
	flat_store_dwordx4 v[28:29], v[24:27]
	v_cvt_pk_bf16_f32 v8, v20, v21
	v_cvt_pk_bf16_f32 v9, v22, v23
	v_cvt_pk_bf16_f32 v11, v14, v15
	flat_store_dwordx4 v[12:13], v[8:11]
	v_cvt_pk_bf16_f32 v4, v4, v5
	v_cvt_pk_bf16_f32 v5, v6, v7
	v_cvt_pk_bf16_f32 v6, v0, v1
	v_cvt_pk_bf16_f32 v7, v2, v3
	flat_store_dwordx4 v[16:17], v[4:7] offset:256
	s_cbranch_vccz .LBB0_89
	s_waitcnt vmcnt(0)
	s_cmpk_gt_u32 s51, 0xff
	s_cbranch_scc1 .LBB0_100
	s_barrier

.LBB0_126:
	s_add_u32 s0, s8, 0xfff80080
	s_addc_u32 s1, s9, -1
	s_add_i32 s2, 0, 0x10000
	v_add_u32_e32 v138, s2, v238
	ds_read_b128 v[154:157], v138
	ds_read_b128 v[158:161], v138 offset:1024
	ds_read_b128 v[162:165], v138 offset:2048
	ds_read_b128 v[166:169], v138 offset:3072
	s_cmp_eq_u32 s20, 28
	s_cselect_b32 s11, s45, s1
	s_cselect_b32 s10, s44, s0
	s_cselect_b32 s1, s67, s15
	s_cselect_b32 s0, s66, s13
	s_add_i32 m0, s17, 0xc000
	ds_read_b128 v[170:173], v239
	ds_read_b128 v[174:177], v239 offset:1024
	ds_read_b128 v[178:181], v239 offset:2048
	ds_read_b128 v[182:185], v239 offset:3072
	ds_read_b128 v[186:189], v239 offset:4096
	ds_read_b128 v[190:193], v239 offset:5120
	ds_read_b128 v[194:197], v239 offset:6144
	global_load_lds_dwordx4 v136, s[8:9]
	s_add_i32 m0, s17, 0xe000
	ds_read_b128 v[198:201], v239 offset:7168
	global_load_lds_dwordx4 v134, s[8:9]
	s_waitcnt lgkmcnt(8)
	s_barrier
	s_waitcnt lgkmcnt(0)
	s_setprio 1
	v_mfma_f32_16x16x32_bf16 v[124:127], v[154:157], v[170:173], v[124:127]
	v_mfma_f32_16x16x32_bf16 v[120:123], v[162:165], v[170:173], v[120:123]
	v_mfma_f32_16x16x32_bf16 v[116:119], v[154:157], v[178:181], v[116:119]
	v_mfma_f32_16x16x32_bf16 v[112:115], v[162:165], v[178:181], v[112:115]
	v_mfma_f32_16x16x32_bf16 v[104:107], v[154:157], v[186:189], v[104:107]
	v_mfma_f32_16x16x32_bf16 v[96:99], v[162:165], v[186:189], v[96:99]
	v_mfma_f32_16x16x32_bf16 v[88:91], v[154:157], v[194:197], v[88:91]
	v_mfma_f32_16x16x32_bf16 v[80:83], v[162:165], v[194:197], v[80:83]
	v_mfma_f32_16x16x32_bf16 v[124:127], v[158:161], v[174:177], v[124:127]
	v_mfma_f32_16x16x32_bf16 v[120:123], v[166:169], v[174:177], v[120:123]
	v_mfma_f32_16x16x32_bf16 v[116:119], v[158:161], v[182:185], v[116:119]
	v_mfma_f32_16x16x32_bf16 v[112:115], v[166:169], v[182:185], v[112:115]
	v_mfma_f32_16x16x32_bf16 v[104:107], v[158:161], v[190:193], v[104:107]
	v_mfma_f32_16x16x32_bf16 v[96:99], v[166:169], v[190:193], v[96:99]
	v_mfma_f32_16x16x32_bf16 v[88:91], v[158:161], v[198:201], v[88:91]
	v_mfma_f32_16x16x32_bf16 v[80:83], v[166:169], v[198:201], v[80:83]
	s_setprio 0
	s_barrier
	s_add_i32 s21, 0, 0x14000
	v_add_u32_e32 v138, s21, v238
	s_add_i32 s2, s2, s58
	ds_read_b128 v[202:205], v138
	ds_read_b128 v[206:209], v138 offset:1024
	s_mov_b32 m0, s2
	ds_read_b128 v[240:243], v138 offset:2048
	global_load_lds_dwordx4 v140, s[0:1]
	s_add_i32 m0, s2, 0x2000
	ds_read_b128 v[244:247], v138 offset:3072
	global_load_lds_dwordx4 v132, s[0:1]
	s_barrier
	s_waitcnt lgkmcnt(0)
	s_setprio 1
	v_mfma_f32_16x16x32_bf16 v[108:111], v[202:205], v[170:173], v[108:111]
	v_mfma_f32_16x16x32_bf16 v[100:103], v[240:243], v[170:173], v[100:103]
	v_mfma_f32_16x16x32_bf16 v[92:95], v[202:205], v[178:181], v[92:95]
	v_mfma_f32_16x16x32_bf16 v[84:87], v[240:243], v[178:181], v[84:87]
	v_mfma_f32_16x16x32_bf16 v[76:79], v[202:205], v[186:189], v[76:79]
	v_mfma_f32_16x16x32_bf16 v[72:75], v[240:243], v[186:189], v[72:75]
	v_mfma_f32_16x16x32_bf16 v[68:71], v[202:205], v[194:197], v[68:71]
	v_mfma_f32_16x16x32_bf16 v[64:67], v[240:243], v[194:197], v[64:67]
	v_mfma_f32_16x16x32_bf16 v[108:111], v[206:209], v[174:177], v[108:111]
	v_mfma_f32_16x16x32_bf16 v[100:103], v[244:247], v[174:177], v[100:103]
	v_mfma_f32_16x16x32_bf16 v[92:95], v[206:209], v[182:185], v[92:95]
	v_mfma_f32_16x16x32_bf16 v[84:87], v[244:247], v[182:185], v[84:87]
	v_mfma_f32_16x16x32_bf16 v[76:79], v[206:209], v[190:193], v[76:79]
	v_mfma_f32_16x16x32_bf16 v[72:75], v[244:247], v[190:193], v[72:75]
	v_mfma_f32_16x16x32_bf16 v[68:71], v[206:209], v[198:201], v[68:71]
	v_mfma_f32_16x16x32_bf16 v[64:67], v[244:247], v[198:201], v[64:67]
	s_setprio 0
	s_mov_b32 m0, s17
	v_lshl_add_u64 v[248:249], s[10:11], 0, v[128:129]
	s_barrier
	ds_read_b128 v[170:173], v239 offset:16384
	ds_read_b128 v[174:177], v239 offset:17408
	ds_read_b128 v[178:181], v239 offset:18432
	ds_read_b128 v[182:185], v239 offset:19456
	ds_read_b128 v[186:189], v239 offset:20480
	ds_read_b128 v[190:193], v239 offset:21504
	ds_read_b128 v[194:197], v239 offset:22528
	ds_read_b128 v[198:201], v239 offset:23552
	global_load_lds_dwordx4 v128, s[10:11]
	v_lshl_add_u64 v[250:251], s[10:11], 0, v[130:131]
	s_mov_b32 m0, s59
	s_nop 0
	global_load_lds_dwordx4 v130, s[10:11]
	s_barrier
	s_waitcnt lgkmcnt(0)
	s_setprio 1
	v_mfma_f32_16x16x32_bf16 v[60:63], v[154:157], v[170:173], v[60:63]
	v_mfma_f32_16x16x32_bf16 v[56:59], v[162:165], v[170:173], v[56:59]
	v_mfma_f32_16x16x32_bf16 v[52:55], v[154:157], v[178:181], v[52:55]
	v_mfma_f32_16x16x32_bf16 v[48:51], v[162:165], v[178:181], v[48:51]
	v_mfma_f32_16x16x32_bf16 v[36:39], v[154:157], v[186:189], v[36:39]
	v_mfma_f32_16x16x32_bf16 v[32:35], v[162:165], v[186:189], v[32:35]
	v_mfma_f32_16x16x32_bf16 v[20:23], v[154:157], v[194:197], v[20:23]
	v_mfma_f32_16x16x32_bf16 v[16:19], v[162:165], v[194:197], v[16:19]
	v_mfma_f32_16x16x32_bf16 v[60:63], v[158:161], v[174:177], v[60:63]
	v_mfma_f32_16x16x32_bf16 v[56:59], v[166:169], v[174:177], v[56:59]
	v_mfma_f32_16x16x32_bf16 v[52:55], v[158:161], v[182:185], v[52:55]
	v_mfma_f32_16x16x32_bf16 v[48:51], v[166:169], v[182:185], v[48:51]
	v_mfma_f32_16x16x32_bf16 v[36:39], v[158:161], v[190:193], v[36:39]
	v_mfma_f32_16x16x32_bf16 v[32:35], v[166:169], v[190:193], v[32:35]
	v_mfma_f32_16x16x32_bf16 v[20:23], v[158:161], v[198:201], v[20:23]
	v_mfma_f32_16x16x32_bf16 v[16:19], v[166:169], v[198:201], v[16:19]
	s_setprio 0
	s_barrier
	s_add_i32 s2, s21, s58
	s_mov_b32 m0, s2
	s_add_u32 s18, s0, 0x100000
	s_addc_u32 s19, s1, 0
	global_load_lds_dwordx4 v140, s[18:19]
	s_add_i32 m0, s2, 0x2000
	s_nop 0
	global_load_lds_dwordx4 v132, s[18:19]
	s_waitcnt vmcnt(6)
	s_barrier
	s_setprio 1
	v_mfma_f32_16x16x32_bf16 v[44:47], v[202:205], v[170:173], v[44:47]
	v_mfma_f32_16x16x32_bf16 v[40:43], v[240:243], v[170:173], v[40:43]
	v_mfma_f32_16x16x32_bf16 v[28:31], v[202:205], v[178:181], v[28:31]
	v_mfma_f32_16x16x32_bf16 v[24:27], v[240:243], v[178:181], v[24:27]
	v_mfma_f32_16x16x32_bf16 v[12:15], v[202:205], v[186:189], v[12:15]
	v_mfma_f32_16x16x32_bf16 v[8:11], v[240:243], v[186:189], v[8:11]
	v_mfma_f32_16x16x32_bf16 v[4:7], v[202:205], v[194:197], v[4:7]
	v_mfma_f32_16x16x32_bf16 v[0:3], v[240:243], v[194:197], v[0:3]
	v_mfma_f32_16x16x32_bf16 v[44:47], v[206:209], v[174:177], v[44:47]
	v_mfma_f32_16x16x32_bf16 v[40:43], v[244:247], v[174:177], v[40:43]
	v_mfma_f32_16x16x32_bf16 v[28:31], v[206:209], v[182:185], v[28:31]
	v_mfma_f32_16x16x32_bf16 v[24:27], v[244:247], v[182:185], v[24:27]
	v_mfma_f32_16x16x32_bf16 v[12:15], v[206:209], v[190:193], v[12:15]
	v_mfma_f32_16x16x32_bf16 v[8:11], v[244:247], v[190:193], v[8:11]
	v_mfma_f32_16x16x32_bf16 v[4:7], v[206:209], v[198:201], v[4:7]
	v_mfma_f32_16x16x32_bf16 v[0:3], v[244:247], v[198:201], v[0:3]
	s_setprio 0
	s_add_i32 s2, 0, 0x18000
	v_add_u32_e32 v166, s2, v238
	s_barrier
	ds_read_b128 v[154:157], v166
	ds_read_b128 v[158:161], v166 offset:1024
	ds_read_b128 v[162:165], v166 offset:2048
	ds_read_b128 v[166:169], v166 offset:3072
	s_add_u32 s10, s10, 0x80000
	s_addc_u32 s11, s11, 0
	s_mov_b32 m0, s65
	ds_read_b128 v[170:173], v239 offset:32768
	ds_read_b128 v[174:177], v239 offset:33792
	ds_read_b128 v[178:181], v239 offset:34816
	ds_read_b128 v[182:185], v239 offset:35840
	ds_read_b128 v[186:189], v239 offset:36864
	ds_read_b128 v[190:193], v239 offset:37888
	ds_read_b128 v[194:197], v239 offset:38912
	global_load_lds_dwordx4 v128, s[10:11]
	s_mov_b32 m0, s72
	ds_read_b128 v[198:201], v239 offset:39936
	global_load_lds_dwordx4 v130, s[10:11]
	s_waitcnt lgkmcnt(8)
	s_barrier
	s_waitcnt lgkmcnt(0)
	s_setprio 1
	v_mfma_f32_16x16x32_bf16 v[124:127], v[154:157], v[170:173], v[124:127]
	v_mfma_f32_16x16x32_bf16 v[120:123], v[162:165], v[170:173], v[120:123]
	v_mfma_f32_16x16x32_bf16 v[116:119], v[154:157], v[178:181], v[116:119]
	v_mfma_f32_16x16x32_bf16 v[112:115], v[162:165], v[178:181], v[112:115]
	v_mfma_f32_16x16x32_bf16 v[104:107], v[154:157], v[186:189], v[104:107]
	v_mfma_f32_16x16x32_bf16 v[96:99], v[162:165], v[186:189], v[96:99]
	v_mfma_f32_16x16x32_bf16 v[88:91], v[154:157], v[194:197], v[88:91]
	v_mfma_f32_16x16x32_bf16 v[80:83], v[162:165], v[194:197], v[80:83]
	v_mfma_f32_16x16x32_bf16 v[124:127], v[158:161], v[174:177], v[124:127]
	v_mfma_f32_16x16x32_bf16 v[120:123], v[166:169], v[174:177], v[120:123]
	v_mfma_f32_16x16x32_bf16 v[116:119], v[158:161], v[182:185], v[116:119]
	v_mfma_f32_16x16x32_bf16 v[112:115], v[166:169], v[182:185], v[112:115]
	v_mfma_f32_16x16x32_bf16 v[104:107], v[158:161], v[190:193], v[104:107]
	v_mfma_f32_16x16x32_bf16 v[96:99], v[166:169], v[190:193], v[96:99]
	v_mfma_f32_16x16x32_bf16 v[88:91], v[158:161], v[198:201], v[88:91]
	v_mfma_f32_16x16x32_bf16 v[80:83], v[166:169], v[198:201], v[80:83]
	s_setprio 0
	s_barrier
	s_add_i32 s10, 0, 0x1c000
	s_add_i32 s2, s2, s58
	v_add_u32_e32 v244, s10, v238
	s_mov_b32 m0, s2
	ds_read_b128 v[202:205], v244
	ds_read_b128 v[206:209], v244 offset:1024
	ds_read_b128 v[240:243], v244 offset:2048
	ds_read_b128 v[244:247], v244 offset:3072
	s_add_u32 s100, s0, 0x80
	s_addc_u32 s101, s1, 0
	global_load_lds_dwordx4 v140, s[100:101]
	s_add_i32 m0, s2, 0x2000
	s_nop 0
	global_load_lds_dwordx4 v132, s[100:101]
	s_barrier
	s_waitcnt lgkmcnt(0)
	s_setprio 1
	v_mfma_f32_16x16x32_bf16 v[108:111], v[202:205], v[170:173], v[108:111]
	v_mfma_f32_16x16x32_bf16 v[100:103], v[240:243], v[170:173], v[100:103]
	v_mfma_f32_16x16x32_bf16 v[92:95], v[202:205], v[178:181], v[92:95]
	v_mfma_f32_16x16x32_bf16 v[84:87], v[240:243], v[178:181], v[84:87]
	v_mfma_f32_16x16x32_bf16 v[76:79], v[202:205], v[186:189], v[76:79]
	v_mfma_f32_16x16x32_bf16 v[72:75], v[240:243], v[186:189], v[72:75]
	v_mfma_f32_16x16x32_bf16 v[68:71], v[202:205], v[194:197], v[68:71]
	v_mfma_f32_16x16x32_bf16 v[64:67], v[240:243], v[194:197], v[64:67]
	v_mfma_f32_16x16x32_bf16 v[108:111], v[206:209], v[174:177], v[108:111]
	v_mfma_f32_16x16x32_bf16 v[100:103], v[244:247], v[174:177], v[100:103]
	v_mfma_f32_16x16x32_bf16 v[92:95], v[206:209], v[182:185], v[92:95]
	v_mfma_f32_16x16x32_bf16 v[84:87], v[244:247], v[182:185], v[84:87]
	v_mfma_f32_16x16x32_bf16 v[76:79], v[206:209], v[190:193], v[76:79]
	v_mfma_f32_16x16x32_bf16 v[72:75], v[244:247], v[190:193], v[72:75]
	v_mfma_f32_16x16x32_bf16 v[68:71], v[206:209], v[198:201], v[68:71]
	v_mfma_f32_16x16x32_bf16 v[64:67], v[244:247], v[198:201], v[64:67]
	s_setprio 0
	s_mov_b32 m0, s75
	v_lshl_add_u64 v[138:139], v[248:249], 0, s[82:83]
	s_barrier
	ds_read_b128 v[170:173], v239 offset:49152
	ds_read_b128 v[174:177], v239 offset:50176
	ds_read_b128 v[178:181], v239 offset:51200
	ds_read_b128 v[182:185], v239 offset:52224
	ds_read_b128 v[186:189], v239 offset:53248
	ds_read_b128 v[190:193], v239 offset:54272
	ds_read_b128 v[194:197], v239 offset:55296
	ds_read_b128 v[198:201], v239 offset:56320
	global_load_lds_dwordx4 v[138:139], off
	v_lshl_add_u64 v[138:139], v[250:251], 0, s[82:83]
	s_mov_b32 m0, s77
	s_nop 0
	global_load_lds_dwordx4 v[138:139], off
	s_barrier
	s_waitcnt lgkmcnt(0)
	s_setprio 1
	v_mfma_f32_16x16x32_bf16 v[60:63], v[154:157], v[170:173], v[60:63]
	v_mfma_f32_16x16x32_bf16 v[56:59], v[162:165], v[170:173], v[56:59]
	v_mfma_f32_16x16x32_bf16 v[52:55], v[154:157], v[178:181], v[52:55]
	v_mfma_f32_16x16x32_bf16 v[48:51], v[162:165], v[178:181], v[48:51]
	v_mfma_f32_16x16x32_bf16 v[36:39], v[154:157], v[186:189], v[36:39]
	v_mfma_f32_16x16x32_bf16 v[32:35], v[162:165], v[186:189], v[32:35]
	v_mfma_f32_16x16x32_bf16 v[20:23], v[154:157], v[194:197], v[20:23]
	v_mfma_f32_16x16x32_bf16 v[16:19], v[162:165], v[194:197], v[16:19]
	v_mfma_f32_16x16x32_bf16 v[60:63], v[158:161], v[174:177], v[60:63]
	v_mfma_f32_16x16x32_bf16 v[56:59], v[166:169], v[174:177], v[56:59]
	v_mfma_f32_16x16x32_bf16 v[52:55], v[158:161], v[182:185], v[52:55]
	v_mfma_f32_16x16x32_bf16 v[48:51], v[166:169], v[182:185], v[48:51]
	v_mfma_f32_16x16x32_bf16 v[36:39], v[158:161], v[190:193], v[36:39]
	v_mfma_f32_16x16x32_bf16 v[32:35], v[166:169], v[190:193], v[32:35]
	v_mfma_f32_16x16x32_bf16 v[20:23], v[158:161], v[198:201], v[20:23]
	v_mfma_f32_16x16x32_bf16 v[16:19], v[166:169], v[198:201], v[16:19]
	s_setprio 0
	s_barrier
	s_add_i32 s2, s10, s58
	s_mov_b32 m0, s2
	s_add_u32 s0, s0, 0x100080
	s_addc_u32 s1, s1, 0
	global_load_lds_dwordx4 v140, s[0:1]
	s_add_i32 m0, s2, 0x2000
	s_nop 0
	global_load_lds_dwordx4 v132, s[0:1]
	s_waitcnt vmcnt(6)
	s_barrier
	s_setprio 1
	v_mfma_f32_16x16x32_bf16 v[44:47], v[202:205], v[170:173], v[44:47]
	v_mfma_f32_16x16x32_bf16 v[40:43], v[240:243], v[170:173], v[40:43]
	v_mfma_f32_16x16x32_bf16 v[28:31], v[202:205], v[178:181], v[28:31]
	v_mfma_f32_16x16x32_bf16 v[24:27], v[240:243], v[178:181], v[24:27]
	v_mfma_f32_16x16x32_bf16 v[12:15], v[202:205], v[186:189], v[12:15]
	v_mfma_f32_16x16x32_bf16 v[8:11], v[240:243], v[186:189], v[8:11]
	v_mfma_f32_16x16x32_bf16 v[4:7], v[202:205], v[194:197], v[4:7]
	v_mfma_f32_16x16x32_bf16 v[0:3], v[240:243], v[194:197], v[0:3]
	v_mfma_f32_16x16x32_bf16 v[44:47], v[206:209], v[174:177], v[44:47]
	v_mfma_f32_16x16x32_bf16 v[40:43], v[244:247], v[174:177], v[40:43]
	v_mfma_f32_16x16x32_bf16 v[28:31], v[206:209], v[182:185], v[28:31]
	v_mfma_f32_16x16x32_bf16 v[24:27], v[244:247], v[182:185], v[24:27]
	v_mfma_f32_16x16x32_bf16 v[12:15], v[206:209], v[190:193], v[12:15]
	v_mfma_f32_16x16x32_bf16 v[8:11], v[244:247], v[190:193], v[8:11]
	v_mfma_f32_16x16x32_bf16 v[4:7], v[206:209], v[198:201], v[4:7]
	v_mfma_f32_16x16x32_bf16 v[0:3], v[244:247], v[198:201], v[0:3]
	s_setprio 0
	s_add_i32 s20, s20, 2
	s_add_u32 s13, s13, 0x100
	s_addc_u32 s15, s15, 0
	s_add_u32 s8, s8, 0x100
	s_addc_u32 s9, s9, 0
	s_cmp_gt_u32 s20, 29
	s_barrier
	s_cbranch_scc0 .LBB0_126
	v_mbcnt_lo_u32_b32 v154, -1, 0
	v_mbcnt_hi_u32_b32 v154, -1, v154
	s_lshl_b32 s0, s16, 8
	v_ashrrev_i32_e32 v138, 2, v154
	s_or_b32 s0, s0, s74
	v_and_b32_e32 v138, -4, v138
	s_lshl_b32 s13, s64, 8
	v_add_u32_e32 v138, s0, v138
	v_and_b32_e32 v240, 15, v154
	s_cmp_gt_i32 s71, 7
	s_mov_b64 s[0:1], -1
	v_ashrrev_i32_e32 v139, 31, v138
	s_cbranch_scc0 .LBB0_145
	s_add_i32 s0, s71, -8
	s_lshl_b32 s52, s0, 10
	s_lshl_b32 s15, s0, 12
	s_lshl_b32 s16, s0, 11
	s_addk_i32 s15, 0x1000
	s_lshl_b64 s[0:1], s[52:53], 2
	v_or_b32_e32 v155, s73, v240
	s_add_u32 s0, s49, s0
	v_add_u32_e32 v206, s13, v155
	s_addc_u32 s1, s76, s1
	v_lshlrev_b64 v[198:199], 2, v[138:139]
	v_add_u32_e32 v156, s16, v206
	v_lshl_add_u64 v[160:161], s[0:1], 0, v[198:199]
	v_ashrrev_i32_e32 v157, 31, v156
	flat_load_dwordx4 v[162:165], v[160:161]
	v_lshlrev_b64 v[158:159], 12, v[156:157]
	v_lshl_add_u64 v[158:159], s[26:27], 0, v[158:159]
	v_lshl_add_u64 v[158:159], v[158:159], 0, v[198:199]
	flat_load_dwordx4 v[166:169], v[158:159] nt
	s_mov_b32 s0, 0x3c800000
	v_and_b32_e32 v155, 1, v154
	v_add_u32_e32 v156, s16, v156
	v_cmp_eq_u32_e64 s[8:9], 0, v155
	v_ashrrev_i32_e32 v157, 31, v156
	v_lshlrev_b64 v[156:157], 11, v[156:157]
	v_sub_u32_e32 v154, s15, v206
	v_lshl_add_u64 v[156:157], s[24:25], 0, v[156:157]
	v_cmp_ne_u32_e32 vcc, 0, v206
	v_lshl_add_u64 v[156:157], v[138:139], 1, v[156:157]
	s_waitcnt vmcnt(0) lgkmcnt(0)
	v_or_b32_e32 v236, 16, v206
	v_add_u32_e32 v236, s16, v236
	v_ashrrev_i32_e32 v237, 31, v236
	v_lshlrev_b64 v[236:237], 12, v[236:237]
	v_lshl_add_u64 v[236:237], s[26:27], 0, v[236:237]
	v_lshl_add_u64 v[236:237], v[236:237], 0, v[198:199]
	global_load_dwordx4 v[232:235], v[236:237], off nt
	v_or_b32_e32 v236, 32, v206
	v_add_u32_e32 v236, s16, v236
	v_ashrrev_i32_e32 v237, 31, v236
	v_lshlrev_b64 v[236:237], 12, v[236:237]
	v_lshl_add_u64 v[236:237], s[26:27], 0, v[236:237]
	v_lshl_add_u64 v[236:237], v[236:237], 0, v[198:199]
	global_load_dwordx4 v[246:249], v[236:237], off nt
	v_pk_mul_f32 v[164:165], v[164:165], s[0:1] op_sel_hi:[1,0]
	v_pk_mul_f32 v[162:163], v[162:163], s[0:1] op_sel_hi:[1,0]
	v_xor_b32_e32 v170, 0x80000000, v164
	v_xor_b32_e32 v171, 0x80000000, v165
	v_xor_b32_e32 v172, 0x80000000, v162
	v_xor_b32_e32 v173, 0x80000000, v163
	v_cndmask_b32_e64 v201, v171, v165, s[8:9]
	v_cndmask_b32_e64 v200, v170, v164, s[8:9]
	v_cndmask_b32_e64 v205, v173, v163, s[8:9]
	v_cndmask_b32_e64 v204, v172, v162, s[8:9]
	v_pk_add_f32 v[162:163], v[168:169], v[200:201]
	v_pk_add_f32 v[164:165], v[166:167], v[204:205]
	v_sub_f32_e32 v155, v162, v126
	v_sub_f32_e32 v167, v163, v127
	v_sub_f32_e32 v166, v164, v124
	v_cvt_pk_bf16_f32 v167, v155, v167
	v_ashrrev_i32_e32 v155, 31, v154
	v_sub_f32_e32 v168, v165, v125
	v_cvt_pk_bf16_f32 v166, v166, v168
	global_store_dwordx2 v[156:157], v[166:167], off
	s_and_saveexec_b64 s[0:1], vcc
	s_cbranch_execz .LBB0_130
	v_pk_add_f32 v[162:163], v[126:127], v[162:163]
	v_pk_add_f32 v[164:165], v[124:125], v[164:165]
	s_nop 0
	v_cvt_pk_bf16_f32 v164, v164, v165
	v_cvt_pk_bf16_f32 v165, v162, v163
	v_lshlrev_b64 v[162:163], 11, v[154:155]
	v_lshl_add_u64 v[162:163], s[24:25], 0, v[162:163]
	v_lshl_add_u64 v[162:163], v[138:139], 1, v[162:163]
	global_store_dwordx2 v[162:163], v[164:165], off

.LBB0_275:
	s_add_u32 s0, s12, 0x100
	s_addc_u32 s1, s13, 0
	s_add_i32 s2, 0, 0x10000
	ds_read_b128 v[156:159], v236
	ds_read_b128 v[160:163], v236 offset:1024
	ds_read_b128 v[164:167], v236 offset:2048
	ds_read_b128 v[168:171], v236 offset:3072
	s_cmp_eq_u32 s65, 40
	s_cselect_b32 s15, s5, s1
	s_cselect_b32 s14, s4, s0
	s_cselect_b32 s11, s9, s64
	s_cselect_b32 s10, s8, s59
	s_add_i32 m0, s40, 0xc000
	ds_read_b128 v[172:175], v155
	ds_read_b128 v[176:179], v155 offset:1024
	ds_read_b128 v[180:183], v155 offset:2048
	ds_read_b128 v[184:187], v155 offset:3072
	ds_read_b128 v[188:191], v155 offset:4096
	ds_read_b128 v[192:195], v155 offset:5120
	ds_read_b128 v[196:199], v155 offset:6144
	global_load_lds_dwordx4 v136, s[12:13]
	s_add_i32 m0, s40, 0xe000
	ds_read_b128 v[200:203], v155 offset:7168
	global_load_lds_dwordx4 v134, s[12:13]
	s_waitcnt lgkmcnt(8)
	s_barrier
	s_waitcnt lgkmcnt(0)
	s_setprio 1
	v_mfma_f32_16x16x32_bf16 v[124:127], v[156:159], v[172:175], v[124:127]
	v_mfma_f32_16x16x32_bf16 v[120:123], v[164:167], v[172:175], v[120:123]
	v_mfma_f32_16x16x32_bf16 v[116:119], v[156:159], v[180:183], v[116:119]
	v_mfma_f32_16x16x32_bf16 v[108:111], v[164:167], v[180:183], v[108:111]
	v_mfma_f32_16x16x32_bf16 v[100:103], v[156:159], v[188:191], v[100:103]
	v_mfma_f32_16x16x32_bf16 v[92:95], v[164:167], v[188:191], v[92:95]
	v_mfma_f32_16x16x32_bf16 v[84:87], v[156:159], v[196:199], v[84:87]
	v_mfma_f32_16x16x32_bf16 v[76:79], v[164:167], v[196:199], v[76:79]
	v_mfma_f32_16x16x32_bf16 v[124:127], v[160:163], v[176:179], v[124:127]
	v_mfma_f32_16x16x32_bf16 v[120:123], v[168:171], v[176:179], v[120:123]
	v_mfma_f32_16x16x32_bf16 v[116:119], v[160:163], v[184:187], v[116:119]
	v_mfma_f32_16x16x32_bf16 v[108:111], v[168:171], v[184:187], v[108:111]
	v_mfma_f32_16x16x32_bf16 v[100:103], v[160:163], v[192:195], v[100:103]
	v_mfma_f32_16x16x32_bf16 v[92:95], v[168:171], v[192:195], v[92:95]
	v_mfma_f32_16x16x32_bf16 v[84:87], v[160:163], v[200:203], v[84:87]
	v_mfma_f32_16x16x32_bf16 v[76:79], v[168:171], v[200:203], v[76:79]
	s_setprio 0
	s_barrier
	s_add_i32 s18, 0, 0x14000
	s_add_i32 s2, s2, s39
	ds_read_b128 v[204:207], v237
	ds_read_b128 v[208:211], v237 offset:1024
	s_mov_b32 m0, s2
	ds_read_b128 v[228:231], v237 offset:2048
	global_load_lds_dwordx4 v140, s[10:11]
	s_add_i32 m0, s2, 0x2000
	ds_read_b128 v[232:235], v237 offset:3072
	global_load_lds_dwordx4 v132, s[10:11]
	s_barrier
	s_waitcnt lgkmcnt(0)
	s_setprio 1
	v_mfma_f32_16x16x32_bf16 v[112:115], v[204:207], v[172:175], v[112:115]
	v_mfma_f32_16x16x32_bf16 v[104:107], v[228:231], v[172:175], v[104:107]
	v_mfma_f32_16x16x32_bf16 v[96:99], v[204:207], v[180:183], v[96:99]
	v_mfma_f32_16x16x32_bf16 v[88:91], v[228:231], v[180:183], v[88:91]
	v_mfma_f32_16x16x32_bf16 v[80:83], v[204:207], v[188:191], v[80:83]
	v_mfma_f32_16x16x32_bf16 v[72:75], v[228:231], v[188:191], v[72:75]
	v_mfma_f32_16x16x32_bf16 v[68:71], v[204:207], v[196:199], v[68:71]
	v_mfma_f32_16x16x32_bf16 v[64:67], v[228:231], v[196:199], v[64:67]
	v_mfma_f32_16x16x32_bf16 v[112:115], v[208:211], v[176:179], v[112:115]
	v_mfma_f32_16x16x32_bf16 v[104:107], v[232:235], v[176:179], v[104:107]
	v_mfma_f32_16x16x32_bf16 v[96:99], v[208:211], v[184:187], v[96:99]
	v_mfma_f32_16x16x32_bf16 v[88:91], v[232:235], v[184:187], v[88:91]
	v_mfma_f32_16x16x32_bf16 v[80:83], v[208:211], v[192:195], v[80:83]
	v_mfma_f32_16x16x32_bf16 v[72:75], v[232:235], v[192:195], v[72:75]
	v_mfma_f32_16x16x32_bf16 v[68:71], v[208:211], v[200:203], v[68:71]
	v_mfma_f32_16x16x32_bf16 v[64:67], v[232:235], v[200:203], v[64:67]
	s_setprio 0
	s_mov_b32 m0, s40
	s_barrier
	ds_read_b128 v[172:175], v155 offset:16384
	ds_read_b128 v[176:179], v155 offset:17408
	ds_read_b128 v[180:183], v155 offset:18432
	ds_read_b128 v[184:187], v155 offset:19456
	ds_read_b128 v[188:191], v155 offset:20480
	ds_read_b128 v[192:195], v155 offset:21504
	ds_read_b128 v[196:199], v155 offset:22528
	global_load_lds_dwordx4 v128, s[14:15]
	s_mov_b32 m0, s41
	ds_read_b128 v[200:203], v155 offset:23552
	global_load_lds_dwordx4 v130, s[14:15]
	s_barrier
	s_waitcnt lgkmcnt(0)
	s_setprio 1
	v_mfma_f32_16x16x32_bf16 v[60:63], v[156:159], v[172:175], v[60:63]
	v_mfma_f32_16x16x32_bf16 v[56:59], v[164:167], v[172:175], v[56:59]
	v_mfma_f32_16x16x32_bf16 v[52:55], v[156:159], v[180:183], v[52:55]
	v_mfma_f32_16x16x32_bf16 v[44:47], v[164:167], v[180:183], v[44:47]
	v_mfma_f32_16x16x32_bf16 v[36:39], v[156:159], v[188:191], v[36:39]
	v_mfma_f32_16x16x32_bf16 v[28:31], v[164:167], v[188:191], v[28:31]
	v_mfma_f32_16x16x32_bf16 v[20:23], v[156:159], v[196:199], v[20:23]
	v_mfma_f32_16x16x32_bf16 v[12:15], v[164:167], v[196:199], v[12:15]
	v_mfma_f32_16x16x32_bf16 v[60:63], v[160:163], v[176:179], v[60:63]
	v_mfma_f32_16x16x32_bf16 v[56:59], v[168:171], v[176:179], v[56:59]
	v_mfma_f32_16x16x32_bf16 v[52:55], v[160:163], v[184:187], v[52:55]
	v_mfma_f32_16x16x32_bf16 v[44:47], v[168:171], v[184:187], v[44:47]
	v_mfma_f32_16x16x32_bf16 v[36:39], v[160:163], v[192:195], v[36:39]
	v_mfma_f32_16x16x32_bf16 v[28:31], v[168:171], v[192:195], v[28:31]
	v_mfma_f32_16x16x32_bf16 v[20:23], v[160:163], v[200:203], v[20:23]
	v_mfma_f32_16x16x32_bf16 v[12:15], v[168:171], v[200:203], v[12:15]
	s_setprio 0
	s_barrier
	s_add_i32 s2, s18, s39
	s_mov_b32 m0, s2
	s_add_u32 s12, s10, 0xb0000
	s_addc_u32 s13, s11, 0
	global_load_lds_dwordx4 v140, s[12:13]
	s_add_i32 m0, s2, 0x2000
	s_nop 0
	global_load_lds_dwordx4 v132, s[12:13]
	s_waitcnt vmcnt(6)
	s_barrier
	s_setprio 1
	v_mfma_f32_16x16x32_bf16 v[48:51], v[204:207], v[172:175], v[48:51]
	v_mfma_f32_16x16x32_bf16 v[40:43], v[228:231], v[172:175], v[40:43]
	v_mfma_f32_16x16x32_bf16 v[32:35], v[204:207], v[180:183], v[32:35]
	v_mfma_f32_16x16x32_bf16 v[24:27], v[228:231], v[180:183], v[24:27]
	v_mfma_f32_16x16x32_bf16 v[16:19], v[204:207], v[188:191], v[16:19]
	v_mfma_f32_16x16x32_bf16 v[8:11], v[228:231], v[188:191], v[8:11]
	v_mfma_f32_16x16x32_bf16 v[4:7], v[204:207], v[196:199], v[4:7]
	v_mfma_f32_16x16x32_bf16 v[0:3], v[228:231], v[196:199], v[0:3]
	v_mfma_f32_16x16x32_bf16 v[48:51], v[208:211], v[176:179], v[48:51]
	v_mfma_f32_16x16x32_bf16 v[40:43], v[232:235], v[176:179], v[40:43]
	v_mfma_f32_16x16x32_bf16 v[32:35], v[208:211], v[184:187], v[32:35]
	v_mfma_f32_16x16x32_bf16 v[24:27], v[232:235], v[184:187], v[24:27]
	v_mfma_f32_16x16x32_bf16 v[16:19], v[208:211], v[192:195], v[16:19]
	v_mfma_f32_16x16x32_bf16 v[8:11], v[232:235], v[192:195], v[8:11]
	v_mfma_f32_16x16x32_bf16 v[4:7], v[208:211], v[200:203], v[4:7]
	v_mfma_f32_16x16x32_bf16 v[0:3], v[232:235], v[200:203], v[0:3]
	s_setprio 0
	s_add_i32 s2, 0, 0x18000
	s_barrier
	ds_read_b128 v[156:159], v238
	ds_read_b128 v[160:163], v238 offset:1024
	ds_read_b128 v[164:167], v238 offset:2048
	ds_read_b128 v[168:171], v238 offset:3072
	s_add_u32 s12, s14, 0xb0000
	s_addc_u32 s13, s15, 0
	s_mov_b32 m0, s44
	ds_read_b128 v[172:175], v155 offset:32768
	ds_read_b128 v[176:179], v155 offset:33792
	ds_read_b128 v[180:183], v155 offset:34816
	ds_read_b128 v[184:187], v155 offset:35840
	ds_read_b128 v[188:191], v155 offset:36864
	ds_read_b128 v[192:195], v155 offset:37888
	ds_read_b128 v[196:199], v155 offset:38912
	global_load_lds_dwordx4 v128, s[12:13]
	s_mov_b32 m0, s45
	ds_read_b128 v[200:203], v155 offset:39936
	global_load_lds_dwordx4 v130, s[12:13]
	s_waitcnt lgkmcnt(8)
	s_barrier
	s_waitcnt lgkmcnt(0)
	s_setprio 1
	v_mfma_f32_16x16x32_bf16 v[124:127], v[156:159], v[172:175], v[124:127]
	v_mfma_f32_16x16x32_bf16 v[120:123], v[164:167], v[172:175], v[120:123]
	v_mfma_f32_16x16x32_bf16 v[116:119], v[156:159], v[180:183], v[116:119]
	v_mfma_f32_16x16x32_bf16 v[108:111], v[164:167], v[180:183], v[108:111]
	v_mfma_f32_16x16x32_bf16 v[100:103], v[156:159], v[188:191], v[100:103]
	v_mfma_f32_16x16x32_bf16 v[92:95], v[164:167], v[188:191], v[92:95]
	v_mfma_f32_16x16x32_bf16 v[84:87], v[156:159], v[196:199], v[84:87]
	v_mfma_f32_16x16x32_bf16 v[76:79], v[164:167], v[196:199], v[76:79]
	v_mfma_f32_16x16x32_bf16 v[124:127], v[160:163], v[176:179], v[124:127]
	v_mfma_f32_16x16x32_bf16 v[120:123], v[168:171], v[176:179], v[120:123]
	v_mfma_f32_16x16x32_bf16 v[116:119], v[160:163], v[184:187], v[116:119]
	v_mfma_f32_16x16x32_bf16 v[108:111], v[168:171], v[184:187], v[108:111]
	v_mfma_f32_16x16x32_bf16 v[100:103], v[160:163], v[192:195], v[100:103]
	v_mfma_f32_16x16x32_bf16 v[92:95], v[168:171], v[192:195], v[92:95]
	v_mfma_f32_16x16x32_bf16 v[84:87], v[160:163], v[200:203], v[84:87]
	v_mfma_f32_16x16x32_bf16 v[76:79], v[168:171], v[200:203], v[76:79]
	s_setprio 0
	s_barrier
	s_add_i32 s12, 0, 0x1c000
	s_add_i32 s2, s2, s39
	s_mov_b32 m0, s2
	ds_read_b128 v[204:207], v239
	ds_read_b128 v[208:211], v239 offset:1024
	ds_read_b128 v[228:231], v239 offset:2048
	ds_read_b128 v[232:235], v239 offset:3072
	s_add_u32 s100, s10, 0x80
	s_addc_u32 s101, s11, 0
	global_load_lds_dwordx4 v140, s[100:101]
	s_add_i32 m0, s2, 0x2000
	s_nop 0
	global_load_lds_dwordx4 v132, s[100:101]
	s_barrier
	s_waitcnt lgkmcnt(0)
	s_setprio 1
	v_mfma_f32_16x16x32_bf16 v[112:115], v[204:207], v[172:175], v[112:115]
	v_mfma_f32_16x16x32_bf16 v[104:107], v[228:231], v[172:175], v[104:107]
	v_mfma_f32_16x16x32_bf16 v[96:99], v[204:207], v[180:183], v[96:99]
	v_mfma_f32_16x16x32_bf16 v[88:91], v[228:231], v[180:183], v[88:91]
	v_mfma_f32_16x16x32_bf16 v[80:83], v[204:207], v[188:191], v[80:83]
	v_mfma_f32_16x16x32_bf16 v[72:75], v[228:231], v[188:191], v[72:75]
	v_mfma_f32_16x16x32_bf16 v[68:71], v[204:207], v[196:199], v[68:71]
	v_mfma_f32_16x16x32_bf16 v[64:67], v[228:231], v[196:199], v[64:67]
	v_mfma_f32_16x16x32_bf16 v[112:115], v[208:211], v[176:179], v[112:115]
	v_mfma_f32_16x16x32_bf16 v[104:107], v[232:235], v[176:179], v[104:107]
	v_mfma_f32_16x16x32_bf16 v[96:99], v[208:211], v[184:187], v[96:99]
	v_mfma_f32_16x16x32_bf16 v[88:91], v[232:235], v[184:187], v[88:91]
	v_mfma_f32_16x16x32_bf16 v[80:83], v[208:211], v[192:195], v[80:83]
	v_mfma_f32_16x16x32_bf16 v[72:75], v[232:235], v[192:195], v[72:75]
	v_mfma_f32_16x16x32_bf16 v[68:71], v[208:211], v[200:203], v[68:71]
	v_mfma_f32_16x16x32_bf16 v[64:67], v[232:235], v[200:203], v[64:67]
	s_setprio 0
	s_mov_b32 m0, s49
	s_barrier
	ds_read_b128 v[172:175], v155 offset:49152
	ds_read_b128 v[176:179], v155 offset:50176
	ds_read_b128 v[180:183], v155 offset:51200
	ds_read_b128 v[184:187], v155 offset:52224
	ds_read_b128 v[188:191], v155 offset:53248
	ds_read_b128 v[192:195], v155 offset:54272
	ds_read_b128 v[196:199], v155 offset:55296
	ds_read_b128 v[200:203], v155 offset:56320
	s_add_u32 s100, s14, 0x80
	s_addc_u32 s101, s15, 0
	global_load_lds_dwordx4 v128, s[100:101]
	s_mov_b32 m0, s20
	s_nop 0
	global_load_lds_dwordx4 v130, s[100:101]
	s_barrier
	s_waitcnt lgkmcnt(0)
	s_setprio 1
	v_mfma_f32_16x16x32_bf16 v[60:63], v[156:159], v[172:175], v[60:63]
	v_mfma_f32_16x16x32_bf16 v[56:59], v[164:167], v[172:175], v[56:59]
	v_mfma_f32_16x16x32_bf16 v[52:55], v[156:159], v[180:183], v[52:55]
	v_mfma_f32_16x16x32_bf16 v[44:47], v[164:167], v[180:183], v[44:47]
	v_mfma_f32_16x16x32_bf16 v[36:39], v[156:159], v[188:191], v[36:39]
	v_mfma_f32_16x16x32_bf16 v[28:31], v[164:167], v[188:191], v[28:31]
	v_mfma_f32_16x16x32_bf16 v[20:23], v[156:159], v[196:199], v[20:23]
	v_mfma_f32_16x16x32_bf16 v[12:15], v[164:167], v[196:199], v[12:15]
	v_mfma_f32_16x16x32_bf16 v[60:63], v[160:163], v[176:179], v[60:63]
	v_mfma_f32_16x16x32_bf16 v[56:59], v[168:171], v[176:179], v[56:59]
	v_mfma_f32_16x16x32_bf16 v[52:55], v[160:163], v[184:187], v[52:55]
	v_mfma_f32_16x16x32_bf16 v[44:47], v[168:171], v[184:187], v[44:47]
	v_mfma_f32_16x16x32_bf16 v[36:39], v[160:163], v[192:195], v[36:39]
	v_mfma_f32_16x16x32_bf16 v[28:31], v[168:171], v[192:195], v[28:31]
	v_mfma_f32_16x16x32_bf16 v[20:23], v[160:163], v[200:203], v[20:23]
	v_mfma_f32_16x16x32_bf16 v[12:15], v[168:171], v[200:203], v[12:15]
	s_setprio 0
	s_barrier
	s_add_i32 s2, s12, s39
	s_mov_b32 m0, s2
	s_add_u32 s10, s10, 0xb0080
	s_addc_u32 s11, s11, 0
	global_load_lds_dwordx4 v140, s[10:11]
	s_add_i32 m0, s2, 0x2000
	s_nop 0
	global_load_lds_dwordx4 v132, s[10:11]
	s_waitcnt vmcnt(6)
	s_barrier
	s_setprio 1
	v_mfma_f32_16x16x32_bf16 v[48:51], v[204:207], v[172:175], v[48:51]
	v_mfma_f32_16x16x32_bf16 v[40:43], v[228:231], v[172:175], v[40:43]
	v_mfma_f32_16x16x32_bf16 v[32:35], v[204:207], v[180:183], v[32:35]
	v_mfma_f32_16x16x32_bf16 v[24:27], v[228:231], v[180:183], v[24:27]
	v_mfma_f32_16x16x32_bf16 v[16:19], v[204:207], v[188:191], v[16:19]
	v_mfma_f32_16x16x32_bf16 v[8:11], v[228:231], v[188:191], v[8:11]
	v_mfma_f32_16x16x32_bf16 v[4:7], v[204:207], v[196:199], v[4:7]
	v_mfma_f32_16x16x32_bf16 v[0:3], v[228:231], v[196:199], v[0:3]
	v_mfma_f32_16x16x32_bf16 v[48:51], v[208:211], v[176:179], v[48:51]
	v_mfma_f32_16x16x32_bf16 v[40:43], v[232:235], v[176:179], v[40:43]
	v_mfma_f32_16x16x32_bf16 v[32:35], v[208:211], v[184:187], v[32:35]
	v_mfma_f32_16x16x32_bf16 v[24:27], v[232:235], v[184:187], v[24:27]
	v_mfma_f32_16x16x32_bf16 v[16:19], v[208:211], v[192:195], v[16:19]
	v_mfma_f32_16x16x32_bf16 v[8:11], v[232:235], v[192:195], v[8:11]
	v_mfma_f32_16x16x32_bf16 v[4:7], v[208:211], v[200:203], v[4:7]
	v_mfma_f32_16x16x32_bf16 v[0:3], v[232:235], v[200:203], v[0:3]
	s_setprio 0
	s_add_i32 s65, s65, 2
	s_add_u32 s59, s59, 0x100
	s_addc_u32 s64, s64, 0
	s_cmp_gt_u32 s65, 41
	s_mov_b64 s[12:13], s[0:1]
	s_barrier
	s_cbranch_scc0 .LBB0_275
	s_lshl_b32 s0, s57, 8
	v_mbcnt_lo_u32_b32 v139, -1, 0
	v_mbcnt_hi_u32_b32 v139, -1, v139
	s_lshl_b32 s1, s58, 8
	v_ashrrev_i32_e32 v138, 1, v139
	s_add_i32 s0, s0, s46
	v_and_b32_e32 v138, -8, v138
	s_or_b32 s1, s1, s48
	v_and_or_b32 v156, v139, 15, s0
	v_add_u32_e32 v138, s1, v138
	v_ashrrev_i32_e32 v157, 31, v156
	v_ashrrev_i32_e32 v139, 31, v138
	v_lshlrev_b64 v[158:159], 11, v[156:157]
	v_lshl_add_u64 v[158:159], s[24:25], 0, v[158:159]
	v_lshlrev_b64 v[160:161], 1, v[138:139]
	v_lshl_add_u64 v[138:139], v[158:159], 0, v[160:161]
	v_cvt_pk_bf16_f32 v60, v60, v61
	v_cvt_pk_bf16_f32 v61, v62, v63
	v_cvt_pk_bf16_f32 v62, v56, v57
	v_add_co_u32_e32 v56, vcc, s19, v138
	v_cvt_pk_bf16_f32 v112, v112, v113
	v_cvt_pk_bf16_f32 v113, v114, v115
	v_cvt_pk_bf16_f32 v114, v104, v105
	v_or_b32_e32 v104, 16, v156
	s_nop 0
	v_addc_co_u32_e32 v57, vcc, 0, v139, vcc
	v_cvt_pk_bf16_f32 v48, v48, v49
	v_cvt_pk_bf16_f32 v49, v50, v51
	v_cvt_pk_bf16_f32 v51, v42, v43
	v_cvt_pk_bf16_f32 v42, v44, v45
	v_add_co_u32_e32 v44, vcc, s30, v138
	v_ashrrev_i32_e32 v105, 31, v104
	v_cvt_pk_bf16_f32 v96, v96, v97
	v_cvt_pk_bf16_f32 v97, v98, v99
	v_cvt_pk_bf16_f32 v98, v88, v89
	v_or_b32_e32 v88, 32, v156
	v_addc_co_u32_e32 v45, vcc, 0, v139, vcc
	v_lshlrev_b64 v[104:105], 11, v[104:105]
	v_ashrrev_i32_e32 v89, 31, v88
	v_cvt_pk_bf16_f32 v80, v80, v81
	v_cvt_pk_bf16_f32 v81, v82, v83
	v_cvt_pk_bf16_f32 v82, v72, v73
	v_or_b32_e32 v72, 48, v156
	s_mov_b64 s[0:1], 0x40000
	v_cvt_pk_bf16_f32 v32, v32, v33
	v_cvt_pk_bf16_f32 v33, v34, v35
	v_cvt_pk_bf16_f32 v35, v26, v27
	v_cvt_pk_bf16_f32 v26, v28, v29
	v_add_co_u32_e32 v28, vcc, s31, v138
	v_lshl_add_u64 v[104:105], s[24:25], 0, v[104:105]
	v_lshlrev_b64 v[88:89], 11, v[88:89]
	v_ashrrev_i32_e32 v73, 31, v72
	v_cvt_pk_bf16_f32 v68, v68, v69
	v_cvt_pk_bf16_f32 v69, v70, v71
	v_cvt_pk_bf16_f32 v70, v64, v65
	v_lshl_add_u64 v[64:65], v[138:139], 0, s[0:1]
	s_mov_b64 s[0:1], 0x48000
	v_addc_co_u32_e32 v29, vcc, 0, v139, vcc
	v_cvt_pk_bf16_f32 v115, v106, v107
	flat_store_dwordx4 v[138:139], v[112:115] offset:256
	v_lshl_add_u64 v[88:89], s[24:25], 0, v[88:89]
	v_lshlrev_b64 v[72:73], 11, v[72:73]
	v_lshl_add_u64 v[112:113], v[104:105], 0, v[160:161]
	v_cvt_pk_bf16_f32 v50, v40, v41
	flat_store_dwordx4 v[64:65], v[48:51] offset:256
	v_cvt_pk_bf16_f32 v16, v16, v17
	v_cvt_pk_bf16_f32 v17, v18, v19
	v_cvt_pk_bf16_f32 v19, v10, v11
	v_cvt_pk_bf16_f32 v10, v12, v13
	v_add_co_u32_e32 v12, vcc, s42, v138
	s_nop 0
	v_lshl_add_u64 v[48:49], v[138:139], 0, s[0:1]
	s_mov_b64 s[0:1], 0x50000
	v_cvt_pk_bf16_f32 v99, v90, v91
	flat_store_dwordx4 v[112:113], v[96:99] offset:256
	v_lshl_add_u64 v[72:73], s[24:25], 0, v[72:73]
	v_cvt_pk_bf16_f32 v34, v24, v25
	flat_store_dwordx4 v[48:49], v[32:35] offset:256
	v_lshl_add_u64 v[96:97], v[88:89], 0, v[160:161]
	v_addc_co_u32_e32 v13, vcc, 0, v139, vcc
	v_lshl_add_u64 v[32:33], v[138:139], 0, s[0:1]
	s_mov_b64 s[0:1], 0x58000
	v_cvt_pk_bf16_f32 v83, v74, v75
	flat_store_dwordx4 v[96:97], v[80:83] offset:256
	v_cvt_pk_bf16_f32 v18, v8, v9
	flat_store_dwordx4 v[32:33], v[16:19] offset:256
	s_and_b64 vcc, exec, s[6:7]
	v_lshl_add_u64 v[80:81], v[72:73], 0, v[160:161]
	v_lshl_add_u64 v[16:17], v[138:139], 0, s[0:1]
	s_mov_b32 s58, s52
	s_mov_b32 s57, s51
	s_mov_b64 s[0:1], s[8:9]
	s_mov_b64 s[12:13], s[4:5]
	v_cvt_pk_bf16_f32 v124, v124, v125
	v_cvt_pk_bf16_f32 v125, v126, v127
	v_cvt_pk_bf16_f32 v126, v120, v121
	v_cvt_pk_bf16_f32 v127, v122, v123
	flat_store_dwordx4 v[138:139], v[124:127]
	v_cvt_pk_bf16_f32 v104, v116, v117
	v_cvt_pk_bf16_f32 v105, v118, v119
	v_cvt_pk_bf16_f32 v106, v108, v109
	v_cvt_pk_bf16_f32 v107, v110, v111
	flat_store_dwordx4 v[112:113], v[104:107]
	v_cvt_pk_bf16_f32 v88, v100, v101
	v_cvt_pk_bf16_f32 v89, v102, v103
	v_cvt_pk_bf16_f32 v90, v92, v93
	v_cvt_pk_bf16_f32 v91, v94, v95
	flat_store_dwordx4 v[96:97], v[88:91]
	v_cvt_pk_bf16_f32 v72, v84, v85
	v_cvt_pk_bf16_f32 v73, v86, v87
	v_cvt_pk_bf16_f32 v74, v76, v77
	v_cvt_pk_bf16_f32 v75, v78, v79
	flat_store_dwordx4 v[80:81], v[72:75]
	v_cvt_pk_bf16_f32 v71, v66, v67
	flat_store_dwordx4 v[80:81], v[68:71] offset:256
	v_cvt_pk_bf16_f32 v63, v58, v59
	flat_store_dwordx4 v[56:57], v[60:63]
	v_cvt_pk_bf16_f32 v40, v52, v53
	v_cvt_pk_bf16_f32 v41, v54, v55
	v_cvt_pk_bf16_f32 v43, v46, v47
	flat_store_dwordx4 v[44:45], v[40:43]
	v_cvt_pk_bf16_f32 v24, v36, v37
	v_cvt_pk_bf16_f32 v25, v38, v39
	v_cvt_pk_bf16_f32 v27, v30, v31
	flat_store_dwordx4 v[28:29], v[24:27]
	v_cvt_pk_bf16_f32 v8, v20, v21
	v_cvt_pk_bf16_f32 v9, v22, v23
	v_cvt_pk_bf16_f32 v11, v14, v15
	flat_store_dwordx4 v[12:13], v[8:11]
	v_cvt_pk_bf16_f32 v4, v4, v5
	v_cvt_pk_bf16_f32 v5, v6, v7
	v_cvt_pk_bf16_f32 v6, v0, v1
	v_cvt_pk_bf16_f32 v7, v2, v3
	flat_store_dwordx4 v[16:17], v[4:7] offset:256
	s_cbranch_vccz .LBB0_264
	s_waitcnt vmcnt(0)
	s_cmpk_gt_u32 s17, 0xff
	s_cbranch_scc1 .LBB0_279
	s_barrier

.LBB0_289:
	s_add_u32 s0, s16, 0xfffc0080
	s_addc_u32 s1, s17, -1
	s_add_i32 s2, 0, 0x10000
	ds_read_b128 v[156:159], v236
	ds_read_b128 v[160:163], v236 offset:1024
	ds_read_b128 v[164:167], v236 offset:2048
	ds_read_b128 v[168:171], v236 offset:3072
	s_cmp_eq_u32 s21, 12
	s_cselect_b32 s37, s11, s1
	s_cselect_b32 s36, s10, s0
	s_cselect_b32 s1, s13, s9
	s_cselect_b32 s0, s12, s5
	s_add_i32 m0, s15, 0xc000
	ds_read_b128 v[172:175], v155
	ds_read_b128 v[176:179], v155 offset:1024
	ds_read_b128 v[180:183], v155 offset:2048
	ds_read_b128 v[184:187], v155 offset:3072
	ds_read_b128 v[188:191], v155 offset:4096
	ds_read_b128 v[192:195], v155 offset:5120
	ds_read_b128 v[196:199], v155 offset:6144
	global_load_lds_dwordx4 v136, s[16:17]
	s_add_i32 m0, s15, 0xe000
	ds_read_b128 v[200:203], v155 offset:7168
	global_load_lds_dwordx4 v134, s[16:17]
	s_waitcnt lgkmcnt(8)
	s_barrier
	s_waitcnt lgkmcnt(0)
	s_setprio 1
	v_mfma_f32_16x16x32_bf16 v[124:127], v[156:159], v[172:175], v[124:127]
	v_mfma_f32_16x16x32_bf16 v[120:123], v[164:167], v[172:175], v[120:123]
	v_mfma_f32_16x16x32_bf16 v[108:111], v[156:159], v[180:183], v[108:111]
	v_mfma_f32_16x16x32_bf16 v[104:107], v[164:167], v[180:183], v[104:107]
	v_mfma_f32_16x16x32_bf16 v[92:95], v[156:159], v[188:191], v[92:95]
	v_mfma_f32_16x16x32_bf16 v[88:91], v[164:167], v[188:191], v[88:91]
	v_mfma_f32_16x16x32_bf16 v[76:79], v[156:159], v[196:199], v[76:79]
	v_mfma_f32_16x16x32_bf16 v[72:75], v[164:167], v[196:199], v[72:75]
	v_mfma_f32_16x16x32_bf16 v[124:127], v[160:163], v[176:179], v[124:127]
	v_mfma_f32_16x16x32_bf16 v[120:123], v[168:171], v[176:179], v[120:123]
	v_mfma_f32_16x16x32_bf16 v[108:111], v[160:163], v[184:187], v[108:111]
	v_mfma_f32_16x16x32_bf16 v[104:107], v[168:171], v[184:187], v[104:107]
	v_mfma_f32_16x16x32_bf16 v[92:95], v[160:163], v[192:195], v[92:95]
	v_mfma_f32_16x16x32_bf16 v[88:91], v[168:171], v[192:195], v[88:91]
	v_mfma_f32_16x16x32_bf16 v[76:79], v[160:163], v[200:203], v[76:79]
	v_mfma_f32_16x16x32_bf16 v[72:75], v[168:171], v[200:203], v[72:75]
	s_setprio 0
	s_barrier
	s_add_i32 s30, 0, 0x14000
	s_add_i32 s2, s2, s44
	ds_read_b128 v[204:207], v237
	ds_read_b128 v[208:211], v237 offset:1024
	s_mov_b32 m0, s2
	ds_read_b128 v[228:231], v237 offset:2048
	global_load_lds_dwordx4 v140, s[0:1]
	s_add_i32 m0, s2, 0x2000
	ds_read_b128 v[232:235], v237 offset:3072
	global_load_lds_dwordx4 v128, s[0:1]
	s_barrier
	s_waitcnt lgkmcnt(0)
	s_setprio 1
	v_mfma_f32_16x16x32_bf16 v[116:119], v[204:207], v[172:175], v[116:119]
	v_mfma_f32_16x16x32_bf16 v[112:115], v[228:231], v[172:175], v[112:115]
	v_mfma_f32_16x16x32_bf16 v[100:103], v[204:207], v[180:183], v[100:103]
	v_mfma_f32_16x16x32_bf16 v[96:99], v[228:231], v[180:183], v[96:99]
	v_mfma_f32_16x16x32_bf16 v[84:87], v[204:207], v[188:191], v[84:87]
	v_mfma_f32_16x16x32_bf16 v[80:83], v[228:231], v[188:191], v[80:83]
	v_mfma_f32_16x16x32_bf16 v[68:71], v[204:207], v[196:199], v[68:71]
	v_mfma_f32_16x16x32_bf16 v[64:67], v[228:231], v[196:199], v[64:67]
	v_mfma_f32_16x16x32_bf16 v[116:119], v[208:211], v[176:179], v[116:119]
	v_mfma_f32_16x16x32_bf16 v[112:115], v[232:235], v[176:179], v[112:115]
	v_mfma_f32_16x16x32_bf16 v[100:103], v[208:211], v[184:187], v[100:103]
	v_mfma_f32_16x16x32_bf16 v[96:99], v[232:235], v[184:187], v[96:99]
	v_mfma_f32_16x16x32_bf16 v[84:87], v[208:211], v[192:195], v[84:87]
	v_mfma_f32_16x16x32_bf16 v[80:83], v[232:235], v[192:195], v[80:83]
	v_mfma_f32_16x16x32_bf16 v[68:71], v[208:211], v[200:203], v[68:71]
	v_mfma_f32_16x16x32_bf16 v[64:67], v[232:235], v[200:203], v[64:67]
	s_setprio 0
	s_mov_b32 m0, s15
	s_barrier
	ds_read_b128 v[172:175], v155 offset:16384
	ds_read_b128 v[176:179], v155 offset:17408
	ds_read_b128 v[180:183], v155 offset:18432
	ds_read_b128 v[184:187], v155 offset:19456
	ds_read_b128 v[188:191], v155 offset:20480
	ds_read_b128 v[192:195], v155 offset:21504
	ds_read_b128 v[196:199], v155 offset:22528
	global_load_lds_dwordx4 v132, s[36:37]
	s_mov_b32 m0, s45
	ds_read_b128 v[200:203], v155 offset:23552
	global_load_lds_dwordx4 v130, s[36:37]
	s_barrier
	s_waitcnt lgkmcnt(0)
	s_setprio 1
	v_mfma_f32_16x16x32_bf16 v[60:63], v[156:159], v[172:175], v[60:63]
	v_mfma_f32_16x16x32_bf16 v[56:59], v[164:167], v[172:175], v[56:59]
	v_mfma_f32_16x16x32_bf16 v[44:47], v[156:159], v[180:183], v[44:47]
	v_mfma_f32_16x16x32_bf16 v[40:43], v[164:167], v[180:183], v[40:43]
	v_mfma_f32_16x16x32_bf16 v[28:31], v[156:159], v[188:191], v[28:31]
	v_mfma_f32_16x16x32_bf16 v[24:27], v[164:167], v[188:191], v[24:27]
	v_mfma_f32_16x16x32_bf16 v[12:15], v[156:159], v[196:199], v[12:15]
	v_mfma_f32_16x16x32_bf16 v[8:11], v[164:167], v[196:199], v[8:11]
	v_mfma_f32_16x16x32_bf16 v[60:63], v[160:163], v[176:179], v[60:63]
	v_mfma_f32_16x16x32_bf16 v[56:59], v[168:171], v[176:179], v[56:59]
	v_mfma_f32_16x16x32_bf16 v[44:47], v[160:163], v[184:187], v[44:47]
	v_mfma_f32_16x16x32_bf16 v[40:43], v[168:171], v[184:187], v[40:43]
	v_mfma_f32_16x16x32_bf16 v[28:31], v[160:163], v[192:195], v[28:31]
	v_mfma_f32_16x16x32_bf16 v[24:27], v[168:171], v[192:195], v[24:27]
	v_mfma_f32_16x16x32_bf16 v[12:15], v[160:163], v[200:203], v[12:15]
	v_mfma_f32_16x16x32_bf16 v[8:11], v[168:171], v[200:203], v[8:11]
	s_setprio 0
	s_barrier
	s_add_i32 s2, s30, s44
	s_mov_b32 m0, s2
	s_add_u32 s18, s0, 0x40000
	s_addc_u32 s19, s1, 0
	global_load_lds_dwordx4 v140, s[18:19]
	s_add_i32 m0, s2, 0x2000
	s_nop 0
	global_load_lds_dwordx4 v128, s[18:19]
	s_waitcnt vmcnt(6)
	s_barrier
	s_setprio 1
	v_mfma_f32_16x16x32_bf16 v[52:55], v[204:207], v[172:175], v[52:55]
	v_mfma_f32_16x16x32_bf16 v[48:51], v[228:231], v[172:175], v[48:51]
	v_mfma_f32_16x16x32_bf16 v[36:39], v[204:207], v[180:183], v[36:39]
	v_mfma_f32_16x16x32_bf16 v[32:35], v[228:231], v[180:183], v[32:35]
	v_mfma_f32_16x16x32_bf16 v[20:23], v[204:207], v[188:191], v[20:23]
	v_mfma_f32_16x16x32_bf16 v[16:19], v[228:231], v[188:191], v[16:19]
	v_mfma_f32_16x16x32_bf16 v[4:7], v[204:207], v[196:199], v[4:7]
	v_mfma_f32_16x16x32_bf16 v[0:3], v[228:231], v[196:199], v[0:3]
	v_mfma_f32_16x16x32_bf16 v[52:55], v[208:211], v[176:179], v[52:55]
	v_mfma_f32_16x16x32_bf16 v[48:51], v[232:235], v[176:179], v[48:51]
	v_mfma_f32_16x16x32_bf16 v[36:39], v[208:211], v[184:187], v[36:39]
	v_mfma_f32_16x16x32_bf16 v[32:35], v[232:235], v[184:187], v[32:35]
	v_mfma_f32_16x16x32_bf16 v[20:23], v[208:211], v[192:195], v[20:23]
	v_mfma_f32_16x16x32_bf16 v[16:19], v[232:235], v[192:195], v[16:19]
	v_mfma_f32_16x16x32_bf16 v[4:7], v[208:211], v[200:203], v[4:7]
	v_mfma_f32_16x16x32_bf16 v[0:3], v[232:235], v[200:203], v[0:3]
	s_setprio 0
	s_add_i32 s2, 0, 0x18000
	s_barrier
	ds_read_b128 v[156:159], v238
	ds_read_b128 v[160:163], v238 offset:1024
	ds_read_b128 v[164:167], v238 offset:2048
	ds_read_b128 v[168:171], v238 offset:3072
	s_add_u32 s18, s36, 0x40000
	s_addc_u32 s19, s37, 0
	s_mov_b32 m0, s46
	ds_read_b128 v[172:175], v155 offset:32768
	ds_read_b128 v[176:179], v155 offset:33792
	ds_read_b128 v[180:183], v155 offset:34816
	ds_read_b128 v[184:187], v155 offset:35840
	ds_read_b128 v[188:191], v155 offset:36864
	ds_read_b128 v[192:195], v155 offset:37888
	ds_read_b128 v[196:199], v155 offset:38912
	global_load_lds_dwordx4 v132, s[18:19]
	s_mov_b32 m0, s48
	ds_read_b128 v[200:203], v155 offset:39936
	global_load_lds_dwordx4 v130, s[18:19]
	s_waitcnt lgkmcnt(8)
	s_barrier
	s_waitcnt lgkmcnt(0)
	s_setprio 1
	v_mfma_f32_16x16x32_bf16 v[124:127], v[156:159], v[172:175], v[124:127]
	v_mfma_f32_16x16x32_bf16 v[120:123], v[164:167], v[172:175], v[120:123]
	v_mfma_f32_16x16x32_bf16 v[108:111], v[156:159], v[180:183], v[108:111]
	v_mfma_f32_16x16x32_bf16 v[104:107], v[164:167], v[180:183], v[104:107]
	v_mfma_f32_16x16x32_bf16 v[92:95], v[156:159], v[188:191], v[92:95]
	v_mfma_f32_16x16x32_bf16 v[88:91], v[164:167], v[188:191], v[88:91]
	v_mfma_f32_16x16x32_bf16 v[76:79], v[156:159], v[196:199], v[76:79]
	v_mfma_f32_16x16x32_bf16 v[72:75], v[164:167], v[196:199], v[72:75]
	v_mfma_f32_16x16x32_bf16 v[124:127], v[160:163], v[176:179], v[124:127]
	v_mfma_f32_16x16x32_bf16 v[120:123], v[168:171], v[176:179], v[120:123]
	v_mfma_f32_16x16x32_bf16 v[108:111], v[160:163], v[184:187], v[108:111]
	v_mfma_f32_16x16x32_bf16 v[104:107], v[168:171], v[184:187], v[104:107]
	v_mfma_f32_16x16x32_bf16 v[92:95], v[160:163], v[192:195], v[92:95]
	v_mfma_f32_16x16x32_bf16 v[88:91], v[168:171], v[192:195], v[88:91]
	v_mfma_f32_16x16x32_bf16 v[76:79], v[160:163], v[200:203], v[76:79]
	v_mfma_f32_16x16x32_bf16 v[72:75], v[168:171], v[200:203], v[72:75]
	s_setprio 0
	s_barrier
	s_add_i32 s18, 0, 0x1c000
	s_add_i32 s2, s2, s44
	s_mov_b32 m0, s2
	ds_read_b128 v[204:207], v239
	ds_read_b128 v[208:211], v239 offset:1024
	ds_read_b128 v[228:231], v239 offset:2048
	ds_read_b128 v[232:235], v239 offset:3072
	s_add_u32 s100, s0, 0x80
	s_addc_u32 s101, s1, 0
	global_load_lds_dwordx4 v140, s[100:101]
	s_add_i32 m0, s2, 0x2000
	s_nop 0
	global_load_lds_dwordx4 v128, s[100:101]
	s_barrier
	s_waitcnt lgkmcnt(0)
	s_setprio 1
	v_mfma_f32_16x16x32_bf16 v[116:119], v[204:207], v[172:175], v[116:119]
	v_mfma_f32_16x16x32_bf16 v[112:115], v[228:231], v[172:175], v[112:115]
	v_mfma_f32_16x16x32_bf16 v[100:103], v[204:207], v[180:183], v[100:103]
	v_mfma_f32_16x16x32_bf16 v[96:99], v[228:231], v[180:183], v[96:99]
	v_mfma_f32_16x16x32_bf16 v[84:87], v[204:207], v[188:191], v[84:87]
	v_mfma_f32_16x16x32_bf16 v[80:83], v[228:231], v[188:191], v[80:83]
	v_mfma_f32_16x16x32_bf16 v[68:71], v[204:207], v[196:199], v[68:71]
	v_mfma_f32_16x16x32_bf16 v[64:67], v[228:231], v[196:199], v[64:67]
	v_mfma_f32_16x16x32_bf16 v[116:119], v[208:211], v[176:179], v[116:119]
	v_mfma_f32_16x16x32_bf16 v[112:115], v[232:235], v[176:179], v[112:115]
	v_mfma_f32_16x16x32_bf16 v[100:103], v[208:211], v[184:187], v[100:103]
	v_mfma_f32_16x16x32_bf16 v[96:99], v[232:235], v[184:187], v[96:99]
	v_mfma_f32_16x16x32_bf16 v[84:87], v[208:211], v[192:195], v[84:87]
	v_mfma_f32_16x16x32_bf16 v[80:83], v[232:235], v[192:195], v[80:83]
	v_mfma_f32_16x16x32_bf16 v[68:71], v[208:211], v[200:203], v[68:71]
	v_mfma_f32_16x16x32_bf16 v[64:67], v[232:235], v[200:203], v[64:67]
	s_setprio 0
	s_mov_b32 m0, s57
	s_barrier
	ds_read_b128 v[172:175], v155 offset:49152
	ds_read_b128 v[176:179], v155 offset:50176
	ds_read_b128 v[180:183], v155 offset:51200
	ds_read_b128 v[184:187], v155 offset:52224
	ds_read_b128 v[188:191], v155 offset:53248
	ds_read_b128 v[192:195], v155 offset:54272
	ds_read_b128 v[196:199], v155 offset:55296
	ds_read_b128 v[200:203], v155 offset:56320
	s_add_u32 s100, s36, 0x80
	s_addc_u32 s101, s37, 0
	global_load_lds_dwordx4 v132, s[100:101]
	s_mov_b32 m0, s58
	s_nop 0
	global_load_lds_dwordx4 v130, s[100:101]
	s_barrier
	s_waitcnt lgkmcnt(0)
	s_setprio 1
	v_mfma_f32_16x16x32_bf16 v[60:63], v[156:159], v[172:175], v[60:63]
	v_mfma_f32_16x16x32_bf16 v[56:59], v[164:167], v[172:175], v[56:59]
	v_mfma_f32_16x16x32_bf16 v[44:47], v[156:159], v[180:183], v[44:47]
	v_mfma_f32_16x16x32_bf16 v[40:43], v[164:167], v[180:183], v[40:43]
	v_mfma_f32_16x16x32_bf16 v[28:31], v[156:159], v[188:191], v[28:31]
	v_mfma_f32_16x16x32_bf16 v[24:27], v[164:167], v[188:191], v[24:27]
	v_mfma_f32_16x16x32_bf16 v[12:15], v[156:159], v[196:199], v[12:15]
	v_mfma_f32_16x16x32_bf16 v[8:11], v[164:167], v[196:199], v[8:11]
	v_mfma_f32_16x16x32_bf16 v[60:63], v[160:163], v[176:179], v[60:63]
	v_mfma_f32_16x16x32_bf16 v[56:59], v[168:171], v[176:179], v[56:59]
	v_mfma_f32_16x16x32_bf16 v[44:47], v[160:163], v[184:187], v[44:47]
	v_mfma_f32_16x16x32_bf16 v[40:43], v[168:171], v[184:187], v[40:43]
	v_mfma_f32_16x16x32_bf16 v[28:31], v[160:163], v[192:195], v[28:31]
	v_mfma_f32_16x16x32_bf16 v[24:27], v[168:171], v[192:195], v[24:27]
	v_mfma_f32_16x16x32_bf16 v[12:15], v[160:163], v[200:203], v[12:15]
	v_mfma_f32_16x16x32_bf16 v[8:11], v[168:171], v[200:203], v[8:11]
	s_setprio 0
	s_barrier
	s_add_i32 s2, s18, s44
	s_mov_b32 m0, s2
	s_add_u32 s0, s0, 0x40080
	s_addc_u32 s1, s1, 0
	global_load_lds_dwordx4 v140, s[0:1]
	s_add_i32 m0, s2, 0x2000
	s_nop 0
	global_load_lds_dwordx4 v128, s[0:1]
	s_waitcnt vmcnt(6)
	s_barrier
	s_setprio 1
	v_mfma_f32_16x16x32_bf16 v[52:55], v[204:207], v[172:175], v[52:55]
	v_mfma_f32_16x16x32_bf16 v[48:51], v[228:231], v[172:175], v[48:51]
	v_mfma_f32_16x16x32_bf16 v[36:39], v[204:207], v[180:183], v[36:39]
	v_mfma_f32_16x16x32_bf16 v[32:35], v[228:231], v[180:183], v[32:35]
	v_mfma_f32_16x16x32_bf16 v[20:23], v[204:207], v[188:191], v[20:23]
	v_mfma_f32_16x16x32_bf16 v[16:19], v[228:231], v[188:191], v[16:19]
	v_mfma_f32_16x16x32_bf16 v[4:7], v[204:207], v[196:199], v[4:7]
	v_mfma_f32_16x16x32_bf16 v[0:3], v[228:231], v[196:199], v[0:3]
	v_mfma_f32_16x16x32_bf16 v[52:55], v[208:211], v[176:179], v[52:55]
	v_mfma_f32_16x16x32_bf16 v[48:51], v[232:235], v[176:179], v[48:51]
	v_mfma_f32_16x16x32_bf16 v[36:39], v[208:211], v[184:187], v[36:39]
	v_mfma_f32_16x16x32_bf16 v[32:35], v[232:235], v[184:187], v[32:35]
	v_mfma_f32_16x16x32_bf16 v[20:23], v[208:211], v[192:195], v[20:23]
	v_mfma_f32_16x16x32_bf16 v[16:19], v[232:235], v[192:195], v[16:19]
	v_mfma_f32_16x16x32_bf16 v[4:7], v[208:211], v[200:203], v[4:7]
	v_mfma_f32_16x16x32_bf16 v[0:3], v[232:235], v[200:203], v[0:3]
	s_setprio 0
	s_add_i32 s21, s21, 2
	s_add_u32 s5, s5, 0x100
	s_addc_u32 s9, s9, 0
	s_add_u32 s16, s16, 0x100
	s_addc_u32 s17, s17, 0
	s_cmp_gt_u32 s21, 13
	s_barrier
	s_cbranch_scc0 .LBB0_289
	v_mul_f32_e32 v161, 0xbfb8aa3b, v124
	v_exp_f32_e32 v161, v161
	v_mul_f32_e32 v162, 0xbfb8aa3b, v125
	v_exp_f32_e32 v162, v162
	v_mul_f32_e32 v163, 0xbfb8aa3b, v126
	v_exp_f32_e32 v163, v163
	v_mul_f32_e32 v164, 0xbfb8aa3b, v127
	v_exp_f32_e32 v164, v164
	v_mul_f32_e32 v165, 0xbfb8aa3b, v120
	v_exp_f32_e32 v165, v165
	v_mul_f32_e32 v166, 0xbfb8aa3b, v121
	v_add_f32_e32 v161, 1.0, v161
	v_exp_f32_e32 v166, v166
	v_mul_f32_e32 v167, 0xbfb8aa3b, v122
	v_rcp_f32_e32 v161, v161
	v_add_f32_e32 v162, 1.0, v162
	v_exp_f32_e32 v167, v167
	v_mul_f32_e32 v168, 0xbfb8aa3b, v123
	v_rcp_f32_e32 v162, v162
	v_add_f32_e32 v163, 1.0, v163
	v_exp_f32_e32 v168, v168
	v_rcp_f32_e32 v163, v163
	v_add_f32_e32 v164, 1.0, v164
	v_rcp_f32_e32 v164, v164
	v_add_f32_e32 v165, 1.0, v165
	v_rcp_f32_e32 v165, v165
	v_add_f32_e32 v166, 1.0, v166
	v_mul_f32_e32 v124, v124, v161
	v_rcp_f32_e32 v166, v166
	v_add_f32_e32 v167, 1.0, v167
	v_mul_f32_e32 v116, v124, v116
	v_mul_f32_e32 v124, v125, v162
	s_lshl_b32 s0, s14, 8
	v_rcp_f32_e32 v167, v167
	v_add_f32_e32 v168, 1.0, v168
	v_mul_f32_e32 v117, v124, v117
	v_mul_f32_e32 v124, v126, v163
	v_mbcnt_lo_u32_b32 v138, -1, 0
	v_mbcnt_hi_u32_b32 v138, -1, v138
	s_add_i32 s0, s0, s51
	v_rcp_f32_e32 v168, v168
	v_mul_f32_e32 v124, v124, v118
	v_mul_f32_e32 v118, v127, v164
	v_and_or_b32 v160, v138, 15, s0
	s_lshl_b32 s0, s20, 7
	v_ashrrev_i32_e32 v138, 1, v138
	v_mul_f32_e32 v125, v118, v119
	v_mul_f32_e32 v118, v120, v165
	s_or_b32 s0, s0, s52
	v_and_b32_e32 v138, -8, v138
	v_mul_f32_e32 v120, v118, v112
	v_mul_f32_e32 v112, v121, v166
	v_add_u32_e32 v156, s0, v138
	v_mul_f32_e32 v121, v112, v113
	v_mul_f32_e32 v112, v122, v167
	v_ashrrev_i32_e32 v157, 31, v156
	v_mov_b64_e32 v[138:139], s[34:35]
	v_mul_f32_e32 v122, v112, v114
	v_mul_f32_e32 v112, v123, v168
	v_mad_i64_i32 v[158:159], s[0:1], v160, s33, v[138:139]
	v_mul_f32_e32 v123, v112, v115
	v_lshlrev_b64 v[112:113], 1, v[156:157]
	v_lshl_add_u64 v[118:119], v[158:159], 0, v[112:113]
	v_cvt_pk_bf16_f32 v114, v116, v117
	v_cvt_pk_bf16_f32 v116, v120, v121
	v_cvt_pk_bf16_f32 v115, v124, v125
	v_cvt_pk_bf16_f32 v117, v122, v123
	flat_store_dwordx4 v[118:119], v[114:117]
	v_mul_f32_e32 v118, 0xbfb8aa3b, v110
	v_exp_f32_e32 v118, v118
	v_mul_f32_e32 v116, 0xbfb8aa3b, v108
	v_exp_f32_e32 v116, v116
	v_mul_f32_e32 v117, 0xbfb8aa3b, v109
	v_exp_f32_e32 v117, v117
	v_mul_f32_e32 v119, 0xbfb8aa3b, v111
	v_exp_f32_e32 v119, v119
	v_mul_f32_e32 v120, 0xbfb8aa3b, v104
	v_exp_f32_e32 v120, v120
	v_mul_f32_e32 v121, 0xbfb8aa3b, v105
	v_add_f32_e32 v116, 1.0, v116
	v_exp_f32_e32 v121, v121
	v_mul_f32_e32 v122, 0xbfb8aa3b, v106
	v_rcp_f32_e32 v116, v116
	v_add_f32_e32 v117, 1.0, v117
	v_exp_f32_e32 v122, v122
	v_mul_f32_e32 v123, 0xbfb8aa3b, v107
	v_rcp_f32_e32 v117, v117
	v_add_f32_e32 v118, 1.0, v118
	v_exp_f32_e32 v123, v123
	v_rcp_f32_e32 v118, v118
	v_add_f32_e32 v119, 1.0, v119
	v_rcp_f32_e32 v119, v119
	v_add_f32_e32 v120, 1.0, v120
	v_rcp_f32_e32 v120, v120
	v_add_f32_e32 v121, 1.0, v121
	v_mul_f32_e32 v108, v108, v116
	v_rcp_f32_e32 v121, v121
	v_add_f32_e32 v122, 1.0, v122
	v_mul_f32_e32 v108, v108, v100
	v_mul_f32_e32 v100, v109, v117
	v_rcp_f32_e32 v122, v122
	v_add_f32_e32 v123, 1.0, v123
	v_mul_f32_e32 v109, v100, v101
	v_mul_f32_e32 v100, v110, v118
	v_rcp_f32_e32 v123, v123
	v_mul_f32_e32 v102, v100, v102
	v_mul_f32_e32 v100, v111, v119
	v_mul_f32_e32 v103, v100, v103
	v_mul_f32_e32 v100, v104, v120
	v_mul_f32_e32 v104, v100, v96
	v_mul_f32_e32 v96, v105, v121
	v_or_b32_e32 v114, 16, v160
	v_mul_f32_e32 v105, v96, v97
	v_mul_f32_e32 v96, v106, v122
	v_mad_i64_i32 v[114:115], s[0:1], v114, s33, v[138:139]
	v_mul_f32_e32 v106, v96, v98
	v_mul_f32_e32 v96, v107, v123
	v_mul_f32_e32 v99, v96, v99
	v_lshl_add_u64 v[100:101], v[114:115], 0, v[112:113]
	v_cvt_pk_bf16_f32 v98, v104, v105
	v_cvt_pk_bf16_f32 v96, v108, v109
	v_cvt_pk_bf16_f32 v97, v102, v103
	v_cvt_pk_bf16_f32 v99, v106, v99
	flat_store_dwordx4 v[100:101], v[96:99]
	v_mul_f32_e32 v100, 0xbfb8aa3b, v94
	v_exp_f32_e32 v100, v100
	v_mul_f32_e32 v98, 0xbfb8aa3b, v92
	v_exp_f32_e32 v98, v98
	v_mul_f32_e32 v99, 0xbfb8aa3b, v93
	v_exp_f32_e32 v99, v99
	v_mul_f32_e32 v101, 0xbfb8aa3b, v95
	v_exp_f32_e32 v101, v101
	v_mul_f32_e32 v102, 0xbfb8aa3b, v88
	v_exp_f32_e32 v102, v102
	v_mul_f32_e32 v103, 0xbfb8aa3b, v89
	v_add_f32_e32 v98, 1.0, v98
	v_exp_f32_e32 v103, v103
	v_mul_f32_e32 v104, 0xbfb8aa3b, v90
	v_rcp_f32_e32 v98, v98
	v_add_f32_e32 v99, 1.0, v99
	v_exp_f32_e32 v104, v104
	v_mul_f32_e32 v105, 0xbfb8aa3b, v91
	v_rcp_f32_e32 v99, v99
	v_add_f32_e32 v100, 1.0, v100
	v_exp_f32_e32 v105, v105
	v_rcp_f32_e32 v100, v100
	v_add_f32_e32 v101, 1.0, v101
	v_rcp_f32_e32 v101, v101
	v_add_f32_e32 v102, 1.0, v102
	v_rcp_f32_e32 v102, v102
	v_add_f32_e32 v103, 1.0, v103
	v_mul_f32_e32 v92, v92, v98
	v_rcp_f32_e32 v103, v103
	v_add_f32_e32 v104, 1.0, v104
	v_mul_f32_e32 v92, v92, v84
	v_mul_f32_e32 v84, v93, v99
	v_rcp_f32_e32 v104, v104
	v_add_f32_e32 v105, 1.0, v105
	v_mul_f32_e32 v93, v84, v85
	v_mul_f32_e32 v84, v94, v100
	v_rcp_f32_e32 v105, v105
	v_mul_f32_e32 v86, v84, v86
	v_mul_f32_e32 v84, v95, v101
	v_mul_f32_e32 v87, v84, v87
	v_mul_f32_e32 v84, v88, v102
	v_mul_f32_e32 v88, v84, v80
	v_mul_f32_e32 v80, v89, v103
	v_or_b32_e32 v96, 32, v160
	v_mul_f32_e32 v89, v80, v81
	v_mul_f32_e32 v80, v90, v104
	v_mad_i64_i32 v[96:97], s[0:1], v96, s33, v[138:139]
	v_mul_f32_e32 v90, v80, v82
	v_mul_f32_e32 v80, v91, v105
	v_mul_f32_e32 v83, v80, v83
	v_lshl_add_u64 v[84:85], v[96:97], 0, v[112:113]
	v_cvt_pk_bf16_f32 v82, v88, v89
	v_cvt_pk_bf16_f32 v80, v92, v93
	v_cvt_pk_bf16_f32 v81, v86, v87
	v_cvt_pk_bf16_f32 v83, v90, v83
	flat_store_dwordx4 v[84:85], v[80:83]
	v_mul_f32_e32 v84, 0xbfb8aa3b, v78
	v_exp_f32_e32 v84, v84
	v_mul_f32_e32 v82, 0xbfb8aa3b, v76
	v_exp_f32_e32 v82, v82
	v_mul_f32_e32 v83, 0xbfb8aa3b, v77
	v_exp_f32_e32 v83, v83
	v_mul_f32_e32 v85, 0xbfb8aa3b, v79
	v_exp_f32_e32 v85, v85
	v_mul_f32_e32 v86, 0xbfb8aa3b, v72
	v_exp_f32_e32 v86, v86
	v_mul_f32_e32 v87, 0xbfb8aa3b, v73
	v_add_f32_e32 v82, 1.0, v82
	v_exp_f32_e32 v87, v87
	v_mul_f32_e32 v88, 0xbfb8aa3b, v74
	v_rcp_f32_e32 v82, v82
	v_add_f32_e32 v83, 1.0, v83
	v_exp_f32_e32 v88, v88
	v_mul_f32_e32 v89, 0xbfb8aa3b, v75
	v_rcp_f32_e32 v83, v83
	v_add_f32_e32 v84, 1.0, v84
	v_exp_f32_e32 v89, v89
	v_rcp_f32_e32 v84, v84
	v_add_f32_e32 v85, 1.0, v85
	v_rcp_f32_e32 v85, v85
	v_add_f32_e32 v86, 1.0, v86
	v_rcp_f32_e32 v86, v86
	v_add_f32_e32 v87, 1.0, v87
	v_mul_f32_e32 v76, v76, v82
	v_rcp_f32_e32 v87, v87
	v_add_f32_e32 v88, 1.0, v88
	v_mul_f32_e32 v76, v76, v68
	v_mul_f32_e32 v68, v77, v83
	v_rcp_f32_e32 v88, v88
	v_add_f32_e32 v89, 1.0, v89
	v_mul_f32_e32 v77, v68, v69
	v_mul_f32_e32 v68, v78, v84
	v_rcp_f32_e32 v89, v89
	v_mul_f32_e32 v70, v68, v70
	v_mul_f32_e32 v68, v79, v85
	v_mul_f32_e32 v71, v68, v71
	v_mul_f32_e32 v68, v72, v86
	v_mul_f32_e32 v72, v68, v64
	v_mul_f32_e32 v64, v73, v87
	v_or_b32_e32 v80, 48, v160
	v_mul_f32_e32 v73, v64, v65
	v_mul_f32_e32 v64, v74, v88
	v_mad_i64_i32 v[80:81], s[0:1], v80, s33, v[138:139]
	v_mul_f32_e32 v74, v64, v66
	v_mul_f32_e32 v64, v75, v89
	v_mul_f32_e32 v67, v64, v67
	v_lshl_add_u64 v[68:69], v[80:81], 0, v[112:113]
	v_cvt_pk_bf16_f32 v66, v72, v73
	v_cvt_pk_bf16_f32 v64, v76, v77
	v_cvt_pk_bf16_f32 v65, v70, v71
	v_cvt_pk_bf16_f32 v67, v74, v67
	flat_store_dwordx4 v[68:69], v[64:67]
	v_mul_f32_e32 v68, 0xbfb8aa3b, v62
	v_exp_f32_e32 v68, v68
	v_mul_f32_e32 v66, 0xbfb8aa3b, v60
	v_exp_f32_e32 v66, v66
	v_mul_f32_e32 v67, 0xbfb8aa3b, v61
	v_exp_f32_e32 v67, v67
	v_mul_f32_e32 v69, 0xbfb8aa3b, v63
	v_exp_f32_e32 v69, v69
	v_mul_f32_e32 v70, 0xbfb8aa3b, v56
	v_exp_f32_e32 v70, v70
	v_mul_f32_e32 v71, 0xbfb8aa3b, v57
	v_add_f32_e32 v66, 1.0, v66
	v_exp_f32_e32 v71, v71
	v_mul_f32_e32 v72, 0xbfb8aa3b, v58
	v_rcp_f32_e32 v66, v66
	v_add_f32_e32 v67, 1.0, v67
	v_exp_f32_e32 v72, v72
	v_mul_f32_e32 v73, 0xbfb8aa3b, v59
	v_rcp_f32_e32 v67, v67
	v_add_f32_e32 v68, 1.0, v68
	v_exp_f32_e32 v73, v73
	v_rcp_f32_e32 v68, v68
	v_add_f32_e32 v69, 1.0, v69
	v_rcp_f32_e32 v69, v69
	v_add_f32_e32 v70, 1.0, v70
	v_rcp_f32_e32 v70, v70
	v_add_f32_e32 v71, 1.0, v71
	v_mul_f32_e32 v60, v60, v66
	v_rcp_f32_e32 v71, v71
	v_add_f32_e32 v72, 1.0, v72
	v_mul_f32_e32 v60, v60, v52
	v_mul_f32_e32 v52, v61, v67
	v_rcp_f32_e32 v72, v72
	v_add_f32_e32 v73, 1.0, v73
	v_mul_f32_e32 v61, v52, v53
	v_mul_f32_e32 v52, v62, v68
	v_rcp_f32_e32 v73, v73
	v_mul_f32_e32 v54, v52, v54
	v_mul_f32_e32 v52, v63, v69
	v_mul_f32_e32 v55, v52, v55
	v_mul_f32_e32 v52, v56, v70
	v_mul_f32_e32 v56, v52, v48
	v_mul_f32_e32 v48, v57, v71
	v_add_u32_e32 v64, 0x80, v160
	v_mul_f32_e32 v57, v48, v49
	v_mul_f32_e32 v48, v58, v72
	v_mad_i64_i32 v[64:65], s[0:1], v64, s33, v[138:139]
	v_mul_f32_e32 v58, v48, v50
	v_mul_f32_e32 v48, v59, v73
	v_mul_f32_e32 v51, v48, v51
	v_lshl_add_u64 v[52:53], v[64:65], 0, v[112:113]
	v_cvt_pk_bf16_f32 v50, v56, v57
	v_cvt_pk_bf16_f32 v48, v60, v61
	v_cvt_pk_bf16_f32 v49, v54, v55
	v_cvt_pk_bf16_f32 v51, v58, v51
	flat_store_dwordx4 v[52:53], v[48:51]
	v_mul_f32_e32 v52, 0xbfb8aa3b, v46
	v_exp_f32_e32 v52, v52
	v_mul_f32_e32 v50, 0xbfb8aa3b, v44
	v_exp_f32_e32 v50, v50
	v_mul_f32_e32 v51, 0xbfb8aa3b, v45
	v_exp_f32_e32 v51, v51
	v_mul_f32_e32 v53, 0xbfb8aa3b, v47
	v_exp_f32_e32 v53, v53
	v_mul_f32_e32 v54, 0xbfb8aa3b, v40
	v_exp_f32_e32 v54, v54
	v_mul_f32_e32 v55, 0xbfb8aa3b, v41
	v_add_f32_e32 v50, 1.0, v50
	v_exp_f32_e32 v55, v55
	v_mul_f32_e32 v56, 0xbfb8aa3b, v42
	v_rcp_f32_e32 v50, v50
	v_add_f32_e32 v51, 1.0, v51
	v_exp_f32_e32 v56, v56
	v_mul_f32_e32 v57, 0xbfb8aa3b, v43
	v_rcp_f32_e32 v51, v51
	v_add_f32_e32 v52, 1.0, v52
	v_exp_f32_e32 v57, v57
	v_rcp_f32_e32 v52, v52
	v_add_f32_e32 v53, 1.0, v53
	v_rcp_f32_e32 v53, v53
	v_add_f32_e32 v54, 1.0, v54
	v_rcp_f32_e32 v54, v54
	v_add_f32_e32 v55, 1.0, v55
	v_mul_f32_e32 v44, v44, v50
	v_rcp_f32_e32 v55, v55
	v_add_f32_e32 v56, 1.0, v56
	v_mul_f32_e32 v44, v44, v36
	v_mul_f32_e32 v36, v45, v51
	v_rcp_f32_e32 v56, v56
	v_add_f32_e32 v57, 1.0, v57
	v_mul_f32_e32 v45, v36, v37
	v_mul_f32_e32 v36, v46, v52
	v_rcp_f32_e32 v57, v57
	v_mul_f32_e32 v38, v36, v38
	v_mul_f32_e32 v36, v47, v53
	v_mul_f32_e32 v39, v36, v39
	v_mul_f32_e32 v36, v40, v54
	v_mul_f32_e32 v40, v36, v32
	v_mul_f32_e32 v32, v41, v55
	v_add_u32_e32 v48, 0x90, v160
	v_mul_f32_e32 v41, v32, v33
	v_mul_f32_e32 v32, v42, v56
	v_mad_i64_i32 v[48:49], s[0:1], v48, s33, v[138:139]
	v_mul_f32_e32 v42, v32, v34
	v_mul_f32_e32 v32, v43, v57
	v_mul_f32_e32 v35, v32, v35
	v_lshl_add_u64 v[36:37], v[48:49], 0, v[112:113]
	v_cvt_pk_bf16_f32 v34, v40, v41
	v_cvt_pk_bf16_f32 v32, v44, v45
	v_cvt_pk_bf16_f32 v33, v38, v39
	v_cvt_pk_bf16_f32 v35, v42, v35
	flat_store_dwordx4 v[36:37], v[32:35]
	v_mul_f32_e32 v36, 0xbfb8aa3b, v30
	v_exp_f32_e32 v36, v36
	v_mul_f32_e32 v34, 0xbfb8aa3b, v28
	v_exp_f32_e32 v34, v34
	v_mul_f32_e32 v35, 0xbfb8aa3b, v29
	v_exp_f32_e32 v35, v35
	v_mul_f32_e32 v37, 0xbfb8aa3b, v31
	v_exp_f32_e32 v37, v37
	v_mul_f32_e32 v38, 0xbfb8aa3b, v24
	v_exp_f32_e32 v38, v38
	v_mul_f32_e32 v39, 0xbfb8aa3b, v25
	v_add_f32_e32 v34, 1.0, v34
	v_exp_f32_e32 v39, v39
	v_mul_f32_e32 v40, 0xbfb8aa3b, v26
	v_rcp_f32_e32 v34, v34
	v_add_f32_e32 v35, 1.0, v35
	v_exp_f32_e32 v40, v40
	v_mul_f32_e32 v41, 0xbfb8aa3b, v27
	v_rcp_f32_e32 v35, v35
	v_add_f32_e32 v36, 1.0, v36
	v_exp_f32_e32 v41, v41
	v_rcp_f32_e32 v36, v36
	v_add_f32_e32 v37, 1.0, v37
	v_rcp_f32_e32 v37, v37
	v_add_f32_e32 v38, 1.0, v38
	v_rcp_f32_e32 v38, v38
	v_add_f32_e32 v39, 1.0, v39
	v_mul_f32_e32 v28, v28, v34
	v_rcp_f32_e32 v39, v39
	v_add_f32_e32 v40, 1.0, v40
	v_mul_f32_e32 v28, v28, v20
	v_mul_f32_e32 v20, v29, v35
	v_rcp_f32_e32 v40, v40
	v_add_f32_e32 v41, 1.0, v41
	v_mul_f32_e32 v29, v20, v21
	v_mul_f32_e32 v20, v30, v36
	v_rcp_f32_e32 v41, v41
	v_mul_f32_e32 v22, v20, v22
	v_mul_f32_e32 v20, v31, v37
	v_mul_f32_e32 v23, v20, v23
	v_mul_f32_e32 v20, v24, v38
	v_mul_f32_e32 v24, v20, v16
	v_mul_f32_e32 v16, v25, v39
	v_add_u32_e32 v32, 0xa0, v160
	v_mul_f32_e32 v25, v16, v17
	v_mul_f32_e32 v16, v26, v40
	v_mad_i64_i32 v[32:33], s[0:1], v32, s33, v[138:139]
	v_mul_f32_e32 v26, v16, v18
	v_mul_f32_e32 v16, v27, v41
	v_mul_f32_e32 v19, v16, v19
	v_lshl_add_u64 v[20:21], v[32:33], 0, v[112:113]
	v_cvt_pk_bf16_f32 v18, v24, v25
	v_cvt_pk_bf16_f32 v16, v28, v29
	v_cvt_pk_bf16_f32 v17, v22, v23
	v_cvt_pk_bf16_f32 v19, v26, v19
	flat_store_dwordx4 v[20:21], v[16:19]
	v_mul_f32_e32 v20, 0xbfb8aa3b, v14
	v_exp_f32_e32 v20, v20
	v_mul_f32_e32 v18, 0xbfb8aa3b, v12
	v_exp_f32_e32 v18, v18
	v_mul_f32_e32 v19, 0xbfb8aa3b, v13
	v_exp_f32_e32 v19, v19
	v_mul_f32_e32 v21, 0xbfb8aa3b, v15
	v_exp_f32_e32 v21, v21
	v_mul_f32_e32 v22, 0xbfb8aa3b, v8
	v_exp_f32_e32 v22, v22
	v_mul_f32_e32 v23, 0xbfb8aa3b, v9
	v_add_f32_e32 v18, 1.0, v18
	v_exp_f32_e32 v23, v23
	v_mul_f32_e32 v24, 0xbfb8aa3b, v10
	v_rcp_f32_e32 v18, v18
	v_add_f32_e32 v19, 1.0, v19
	v_exp_f32_e32 v24, v24
	v_mul_f32_e32 v25, 0xbfb8aa3b, v11
	v_rcp_f32_e32 v19, v19
	v_add_f32_e32 v20, 1.0, v20
	v_exp_f32_e32 v25, v25
	v_rcp_f32_e32 v20, v20
	v_add_f32_e32 v21, 1.0, v21
	v_rcp_f32_e32 v21, v21
	v_add_f32_e32 v22, 1.0, v22
	v_rcp_f32_e32 v22, v22
	v_add_f32_e32 v23, 1.0, v23
	v_mul_f32_e32 v12, v12, v18
	v_rcp_f32_e32 v23, v23
	v_add_f32_e32 v24, 1.0, v24
	v_mul_f32_e32 v12, v12, v4
	v_mul_f32_e32 v4, v13, v19
	v_rcp_f32_e32 v24, v24
	v_add_f32_e32 v25, 1.0, v25
	v_mul_f32_e32 v13, v4, v5
	v_mul_f32_e32 v4, v14, v20
	v_rcp_f32_e32 v25, v25
	v_mul_f32_e32 v6, v4, v6
	v_mul_f32_e32 v4, v15, v21
	v_mul_f32_e32 v7, v4, v7
	v_mul_f32_e32 v4, v8, v22
	v_mul_f32_e32 v8, v4, v0
	v_mul_f32_e32 v0, v9, v23
	v_add_u32_e32 v16, 0xb0, v160
	v_mul_f32_e32 v9, v0, v1
	v_mul_f32_e32 v0, v10, v24
	v_mad_i64_i32 v[16:17], s[0:1], v16, s33, v[138:139]
	v_mul_f32_e32 v10, v0, v2
	v_mul_f32_e32 v0, v11, v25
	v_mul_f32_e32 v3, v0, v3
	v_lshl_add_u64 v[4:5], v[16:17], 0, v[112:113]
	s_and_b64 vcc, exec, s[6:7]
	s_mov_b32 s20, s8
	s_mov_b32 s14, s4
	s_mov_b64 s[16:17], s[12:13]
	s_mov_b64 s[0:1], s[10:11]
	v_cvt_pk_bf16_f32 v0, v12, v13
	v_cvt_pk_bf16_f32 v1, v6, v7
	v_cvt_pk_bf16_f32 v2, v8, v9
	v_cvt_pk_bf16_f32 v3, v10, v3
	flat_store_dwordx4 v[4:5], v[0:3]
	s_cbranch_vccz .LBB0_286
	s_waitcnt vmcnt(0)
	s_cmpk_gt_u32 s39, 0xff
	v_readlane_b32 s51, v252, 10
	s_cbranch_scc1 .LBB0_293
	s_barrier

.LBB0_321:
	s_add_u32 s0, s16, 0xfffc0080
	s_addc_u32 s1, s17, -1
	s_add_i32 s2, 0, 0x10000
	ds_read_b128 v[156:159], v236
	ds_read_b128 v[160:163], v236 offset:1024
	ds_read_b128 v[164:167], v236 offset:2048
	ds_read_b128 v[168:171], v236 offset:3072
	s_cmp_eq_u32 s59, 12
	s_cselect_b32 s41, s11, s1
	s_cselect_b32 s40, s10, s0
	s_cselect_b32 s1, s13, s9
	s_cselect_b32 s0, s12, s5
	s_add_i32 m0, s15, 0xc000
	ds_read_b128 v[172:175], v155
	ds_read_b128 v[176:179], v155 offset:1024
	ds_read_b128 v[180:183], v155 offset:2048
	ds_read_b128 v[184:187], v155 offset:3072
	ds_read_b128 v[188:191], v155 offset:4096
	ds_read_b128 v[192:195], v155 offset:5120
	ds_read_b128 v[196:199], v155 offset:6144
	global_load_lds_dwordx4 v136, s[16:17]
	s_add_i32 m0, s15, 0xe000
	ds_read_b128 v[200:203], v155 offset:7168
	global_load_lds_dwordx4 v134, s[16:17]
	s_waitcnt lgkmcnt(8)
	s_barrier
	s_waitcnt lgkmcnt(0)
	s_setprio 1
	v_mfma_f32_16x16x32_bf16 v[124:127], v[156:159], v[172:175], v[124:127]
	v_mfma_f32_16x16x32_bf16 v[120:123], v[164:167], v[172:175], v[120:123]
	v_mfma_f32_16x16x32_bf16 v[116:119], v[156:159], v[180:183], v[116:119]
	v_mfma_f32_16x16x32_bf16 v[108:111], v[164:167], v[180:183], v[108:111]
	v_mfma_f32_16x16x32_bf16 v[100:103], v[156:159], v[188:191], v[100:103]
	v_mfma_f32_16x16x32_bf16 v[92:95], v[164:167], v[188:191], v[92:95]
	v_mfma_f32_16x16x32_bf16 v[84:87], v[156:159], v[196:199], v[84:87]
	v_mfma_f32_16x16x32_bf16 v[76:79], v[164:167], v[196:199], v[76:79]
	v_mfma_f32_16x16x32_bf16 v[124:127], v[160:163], v[176:179], v[124:127]
	v_mfma_f32_16x16x32_bf16 v[120:123], v[168:171], v[176:179], v[120:123]
	v_mfma_f32_16x16x32_bf16 v[116:119], v[160:163], v[184:187], v[116:119]
	v_mfma_f32_16x16x32_bf16 v[108:111], v[168:171], v[184:187], v[108:111]
	v_mfma_f32_16x16x32_bf16 v[100:103], v[160:163], v[192:195], v[100:103]
	v_mfma_f32_16x16x32_bf16 v[92:95], v[168:171], v[192:195], v[92:95]
	v_mfma_f32_16x16x32_bf16 v[84:87], v[160:163], v[200:203], v[84:87]
	v_mfma_f32_16x16x32_bf16 v[76:79], v[168:171], v[200:203], v[76:79]
	s_setprio 0
	s_barrier
	s_add_i32 s30, 0, 0x14000
	s_add_i32 s2, s2, s45
	ds_read_b128 v[204:207], v237
	ds_read_b128 v[208:211], v237 offset:1024
	s_mov_b32 m0, s2
	ds_read_b128 v[228:231], v237 offset:2048
	global_load_lds_dwordx4 v140, s[0:1]
	s_add_i32 m0, s2, 0x2000
	ds_read_b128 v[232:235], v237 offset:3072
	global_load_lds_dwordx4 v132, s[0:1]
	s_barrier
	s_waitcnt lgkmcnt(0)
	s_setprio 1
	v_mfma_f32_16x16x32_bf16 v[112:115], v[204:207], v[172:175], v[112:115]
	v_mfma_f32_16x16x32_bf16 v[104:107], v[228:231], v[172:175], v[104:107]
	v_mfma_f32_16x16x32_bf16 v[96:99], v[204:207], v[180:183], v[96:99]
	v_mfma_f32_16x16x32_bf16 v[88:91], v[228:231], v[180:183], v[88:91]
	v_mfma_f32_16x16x32_bf16 v[80:83], v[204:207], v[188:191], v[80:83]
	v_mfma_f32_16x16x32_bf16 v[72:75], v[228:231], v[188:191], v[72:75]
	v_mfma_f32_16x16x32_bf16 v[68:71], v[204:207], v[196:199], v[68:71]
	v_mfma_f32_16x16x32_bf16 v[64:67], v[228:231], v[196:199], v[64:67]
	v_mfma_f32_16x16x32_bf16 v[112:115], v[208:211], v[176:179], v[112:115]
	v_mfma_f32_16x16x32_bf16 v[104:107], v[232:235], v[176:179], v[104:107]
	v_mfma_f32_16x16x32_bf16 v[96:99], v[208:211], v[184:187], v[96:99]
	v_mfma_f32_16x16x32_bf16 v[88:91], v[232:235], v[184:187], v[88:91]
	v_mfma_f32_16x16x32_bf16 v[80:83], v[208:211], v[192:195], v[80:83]
	v_mfma_f32_16x16x32_bf16 v[72:75], v[232:235], v[192:195], v[72:75]
	v_mfma_f32_16x16x32_bf16 v[68:71], v[208:211], v[200:203], v[68:71]
	v_mfma_f32_16x16x32_bf16 v[64:67], v[232:235], v[200:203], v[64:67]
	s_setprio 0
	s_mov_b32 m0, s15
	s_barrier
	ds_read_b128 v[172:175], v155 offset:16384
	ds_read_b128 v[176:179], v155 offset:17408
	ds_read_b128 v[180:183], v155 offset:18432
	ds_read_b128 v[184:187], v155 offset:19456
	ds_read_b128 v[188:191], v155 offset:20480
	ds_read_b128 v[192:195], v155 offset:21504
	ds_read_b128 v[196:199], v155 offset:22528
	global_load_lds_dwordx4 v128, s[40:41]
	s_mov_b32 m0, s46
	ds_read_b128 v[200:203], v155 offset:23552
	global_load_lds_dwordx4 v130, s[40:41]
	s_barrier
	s_waitcnt lgkmcnt(0)
	s_setprio 1
	v_mfma_f32_16x16x32_bf16 v[60:63], v[156:159], v[172:175], v[60:63]
	v_mfma_f32_16x16x32_bf16 v[56:59], v[164:167], v[172:175], v[56:59]
	v_mfma_f32_16x16x32_bf16 v[52:55], v[156:159], v[180:183], v[52:55]
	v_mfma_f32_16x16x32_bf16 v[44:47], v[164:167], v[180:183], v[44:47]
	v_mfma_f32_16x16x32_bf16 v[36:39], v[156:159], v[188:191], v[36:39]
	v_mfma_f32_16x16x32_bf16 v[28:31], v[164:167], v[188:191], v[28:31]
	v_mfma_f32_16x16x32_bf16 v[20:23], v[156:159], v[196:199], v[20:23]
	v_mfma_f32_16x16x32_bf16 v[12:15], v[164:167], v[196:199], v[12:15]
	v_mfma_f32_16x16x32_bf16 v[60:63], v[160:163], v[176:179], v[60:63]
	v_mfma_f32_16x16x32_bf16 v[56:59], v[168:171], v[176:179], v[56:59]
	v_mfma_f32_16x16x32_bf16 v[52:55], v[160:163], v[184:187], v[52:55]
	v_mfma_f32_16x16x32_bf16 v[44:47], v[168:171], v[184:187], v[44:47]
	v_mfma_f32_16x16x32_bf16 v[36:39], v[160:163], v[192:195], v[36:39]
	v_mfma_f32_16x16x32_bf16 v[28:31], v[168:171], v[192:195], v[28:31]
	v_mfma_f32_16x16x32_bf16 v[20:23], v[160:163], v[200:203], v[20:23]
	v_mfma_f32_16x16x32_bf16 v[12:15], v[168:171], v[200:203], v[12:15]
	s_setprio 0
	s_barrier
	s_add_i32 s2, s30, s45
	s_mov_b32 m0, s2
	s_add_u32 s18, s0, 0x40000
	s_addc_u32 s19, s1, 0
	global_load_lds_dwordx4 v140, s[18:19]
	s_add_i32 m0, s2, 0x2000
	s_nop 0
	global_load_lds_dwordx4 v132, s[18:19]
	s_waitcnt vmcnt(6)
	s_barrier
	s_setprio 1
	v_mfma_f32_16x16x32_bf16 v[48:51], v[204:207], v[172:175], v[48:51]
	v_mfma_f32_16x16x32_bf16 v[40:43], v[228:231], v[172:175], v[40:43]
	v_mfma_f32_16x16x32_bf16 v[32:35], v[204:207], v[180:183], v[32:35]
	v_mfma_f32_16x16x32_bf16 v[24:27], v[228:231], v[180:183], v[24:27]
	v_mfma_f32_16x16x32_bf16 v[16:19], v[204:207], v[188:191], v[16:19]
	v_mfma_f32_16x16x32_bf16 v[8:11], v[228:231], v[188:191], v[8:11]
	v_mfma_f32_16x16x32_bf16 v[4:7], v[204:207], v[196:199], v[4:7]
	v_mfma_f32_16x16x32_bf16 v[0:3], v[228:231], v[196:199], v[0:3]
	v_mfma_f32_16x16x32_bf16 v[48:51], v[208:211], v[176:179], v[48:51]
	v_mfma_f32_16x16x32_bf16 v[40:43], v[232:235], v[176:179], v[40:43]
	v_mfma_f32_16x16x32_bf16 v[32:35], v[208:211], v[184:187], v[32:35]
	v_mfma_f32_16x16x32_bf16 v[24:27], v[232:235], v[184:187], v[24:27]
	v_mfma_f32_16x16x32_bf16 v[16:19], v[208:211], v[192:195], v[16:19]
	v_mfma_f32_16x16x32_bf16 v[8:11], v[232:235], v[192:195], v[8:11]
	v_mfma_f32_16x16x32_bf16 v[4:7], v[208:211], v[200:203], v[4:7]
	v_mfma_f32_16x16x32_bf16 v[0:3], v[232:235], v[200:203], v[0:3]
	s_setprio 0
	s_add_i32 s2, 0, 0x18000
	s_barrier
	ds_read_b128 v[156:159], v238
	ds_read_b128 v[160:163], v238 offset:1024
	ds_read_b128 v[164:167], v238 offset:2048
	ds_read_b128 v[168:171], v238 offset:3072
	s_add_u32 s18, s40, 0x40000
	s_addc_u32 s19, s41, 0
	s_mov_b32 m0, s48
	ds_read_b128 v[172:175], v155 offset:32768
	ds_read_b128 v[176:179], v155 offset:33792
	ds_read_b128 v[180:183], v155 offset:34816
	ds_read_b128 v[184:187], v155 offset:35840
	ds_read_b128 v[188:191], v155 offset:36864
	ds_read_b128 v[192:195], v155 offset:37888
	ds_read_b128 v[196:199], v155 offset:38912
	global_load_lds_dwordx4 v128, s[18:19]
	s_mov_b32 m0, s49
	ds_read_b128 v[200:203], v155 offset:39936
	global_load_lds_dwordx4 v130, s[18:19]
	s_waitcnt lgkmcnt(8)
	s_barrier
	s_waitcnt lgkmcnt(0)
	s_setprio 1
	v_mfma_f32_16x16x32_bf16 v[124:127], v[156:159], v[172:175], v[124:127]
	v_mfma_f32_16x16x32_bf16 v[120:123], v[164:167], v[172:175], v[120:123]
	v_mfma_f32_16x16x32_bf16 v[116:119], v[156:159], v[180:183], v[116:119]
	v_mfma_f32_16x16x32_bf16 v[108:111], v[164:167], v[180:183], v[108:111]
	v_mfma_f32_16x16x32_bf16 v[100:103], v[156:159], v[188:191], v[100:103]
	v_mfma_f32_16x16x32_bf16 v[92:95], v[164:167], v[188:191], v[92:95]
	v_mfma_f32_16x16x32_bf16 v[84:87], v[156:159], v[196:199], v[84:87]
	v_mfma_f32_16x16x32_bf16 v[76:79], v[164:167], v[196:199], v[76:79]
	v_mfma_f32_16x16x32_bf16 v[124:127], v[160:163], v[176:179], v[124:127]
	v_mfma_f32_16x16x32_bf16 v[120:123], v[168:171], v[176:179], v[120:123]
	v_mfma_f32_16x16x32_bf16 v[116:119], v[160:163], v[184:187], v[116:119]
	v_mfma_f32_16x16x32_bf16 v[108:111], v[168:171], v[184:187], v[108:111]
	v_mfma_f32_16x16x32_bf16 v[100:103], v[160:163], v[192:195], v[100:103]
	v_mfma_f32_16x16x32_bf16 v[92:95], v[168:171], v[192:195], v[92:95]
	v_mfma_f32_16x16x32_bf16 v[84:87], v[160:163], v[200:203], v[84:87]
	v_mfma_f32_16x16x32_bf16 v[76:79], v[168:171], v[200:203], v[76:79]
	s_setprio 0
	s_barrier
	s_add_i32 s18, 0, 0x1c000
	s_add_i32 s2, s2, s45
	s_mov_b32 m0, s2
	ds_read_b128 v[204:207], v239
	ds_read_b128 v[208:211], v239 offset:1024
	ds_read_b128 v[228:231], v239 offset:2048
	ds_read_b128 v[232:235], v239 offset:3072
	s_add_u32 s100, s0, 0x80
	s_addc_u32 s101, s1, 0
	global_load_lds_dwordx4 v140, s[100:101]
	s_add_i32 m0, s2, 0x2000
	s_nop 0
	global_load_lds_dwordx4 v132, s[100:101]
	s_barrier
	s_waitcnt lgkmcnt(0)
	s_setprio 1
	v_mfma_f32_16x16x32_bf16 v[112:115], v[204:207], v[172:175], v[112:115]
	v_mfma_f32_16x16x32_bf16 v[104:107], v[228:231], v[172:175], v[104:107]
	v_mfma_f32_16x16x32_bf16 v[96:99], v[204:207], v[180:183], v[96:99]
	v_mfma_f32_16x16x32_bf16 v[88:91], v[228:231], v[180:183], v[88:91]
	v_mfma_f32_16x16x32_bf16 v[80:83], v[204:207], v[188:191], v[80:83]
	v_mfma_f32_16x16x32_bf16 v[72:75], v[228:231], v[188:191], v[72:75]
	v_mfma_f32_16x16x32_bf16 v[68:71], v[204:207], v[196:199], v[68:71]
	v_mfma_f32_16x16x32_bf16 v[64:67], v[228:231], v[196:199], v[64:67]
	v_mfma_f32_16x16x32_bf16 v[112:115], v[208:211], v[176:179], v[112:115]
	v_mfma_f32_16x16x32_bf16 v[104:107], v[232:235], v[176:179], v[104:107]
	v_mfma_f32_16x16x32_bf16 v[96:99], v[208:211], v[184:187], v[96:99]
	v_mfma_f32_16x16x32_bf16 v[88:91], v[232:235], v[184:187], v[88:91]
	v_mfma_f32_16x16x32_bf16 v[80:83], v[208:211], v[192:195], v[80:83]
	v_mfma_f32_16x16x32_bf16 v[72:75], v[232:235], v[192:195], v[72:75]
	v_mfma_f32_16x16x32_bf16 v[68:71], v[208:211], v[200:203], v[68:71]
	v_mfma_f32_16x16x32_bf16 v[64:67], v[232:235], v[200:203], v[64:67]
	s_setprio 0
	s_mov_b32 m0, s57
	s_barrier
	ds_read_b128 v[172:175], v155 offset:49152
	ds_read_b128 v[176:179], v155 offset:50176
	ds_read_b128 v[180:183], v155 offset:51200
	ds_read_b128 v[184:187], v155 offset:52224
	ds_read_b128 v[188:191], v155 offset:53248
	ds_read_b128 v[192:195], v155 offset:54272
	ds_read_b128 v[196:199], v155 offset:55296
	ds_read_b128 v[200:203], v155 offset:56320
	s_add_u32 s100, s40, 0x80
	s_addc_u32 s101, s41, 0
	global_load_lds_dwordx4 v128, s[100:101]
	s_mov_b32 m0, s58
	s_nop 0
	global_load_lds_dwordx4 v130, s[100:101]
	s_barrier
	s_waitcnt lgkmcnt(0)
	s_setprio 1
	v_mfma_f32_16x16x32_bf16 v[60:63], v[156:159], v[172:175], v[60:63]
	v_mfma_f32_16x16x32_bf16 v[56:59], v[164:167], v[172:175], v[56:59]
	v_mfma_f32_16x16x32_bf16 v[52:55], v[156:159], v[180:183], v[52:55]
	v_mfma_f32_16x16x32_bf16 v[44:47], v[164:167], v[180:183], v[44:47]
	v_mfma_f32_16x16x32_bf16 v[36:39], v[156:159], v[188:191], v[36:39]
	v_mfma_f32_16x16x32_bf16 v[28:31], v[164:167], v[188:191], v[28:31]
	v_mfma_f32_16x16x32_bf16 v[20:23], v[156:159], v[196:199], v[20:23]
	v_mfma_f32_16x16x32_bf16 v[12:15], v[164:167], v[196:199], v[12:15]
	v_mfma_f32_16x16x32_bf16 v[60:63], v[160:163], v[176:179], v[60:63]
	v_mfma_f32_16x16x32_bf16 v[56:59], v[168:171], v[176:179], v[56:59]
	v_mfma_f32_16x16x32_bf16 v[52:55], v[160:163], v[184:187], v[52:55]
	v_mfma_f32_16x16x32_bf16 v[44:47], v[168:171], v[184:187], v[44:47]
	v_mfma_f32_16x16x32_bf16 v[36:39], v[160:163], v[192:195], v[36:39]
	v_mfma_f32_16x16x32_bf16 v[28:31], v[168:171], v[192:195], v[28:31]
	v_mfma_f32_16x16x32_bf16 v[20:23], v[160:163], v[200:203], v[20:23]
	v_mfma_f32_16x16x32_bf16 v[12:15], v[168:171], v[200:203], v[12:15]
	s_setprio 0
	s_barrier
	s_add_i32 s2, s18, s45
	s_mov_b32 m0, s2
	s_add_u32 s0, s0, 0x40080
	s_addc_u32 s1, s1, 0
	global_load_lds_dwordx4 v140, s[0:1]
	s_add_i32 m0, s2, 0x2000
	s_nop 0
	global_load_lds_dwordx4 v132, s[0:1]
	s_waitcnt vmcnt(6)
	s_barrier
	s_setprio 1
	v_mfma_f32_16x16x32_bf16 v[48:51], v[204:207], v[172:175], v[48:51]
	v_mfma_f32_16x16x32_bf16 v[40:43], v[228:231], v[172:175], v[40:43]
	v_mfma_f32_16x16x32_bf16 v[32:35], v[204:207], v[180:183], v[32:35]
	v_mfma_f32_16x16x32_bf16 v[24:27], v[228:231], v[180:183], v[24:27]
	v_mfma_f32_16x16x32_bf16 v[16:19], v[204:207], v[188:191], v[16:19]
	v_mfma_f32_16x16x32_bf16 v[8:11], v[228:231], v[188:191], v[8:11]
	v_mfma_f32_16x16x32_bf16 v[4:7], v[204:207], v[196:199], v[4:7]
	v_mfma_f32_16x16x32_bf16 v[0:3], v[228:231], v[196:199], v[0:3]
	v_mfma_f32_16x16x32_bf16 v[48:51], v[208:211], v[176:179], v[48:51]
	v_mfma_f32_16x16x32_bf16 v[40:43], v[232:235], v[176:179], v[40:43]
	v_mfma_f32_16x16x32_bf16 v[32:35], v[208:211], v[184:187], v[32:35]
	v_mfma_f32_16x16x32_bf16 v[24:27], v[232:235], v[184:187], v[24:27]
	v_mfma_f32_16x16x32_bf16 v[16:19], v[208:211], v[192:195], v[16:19]
	v_mfma_f32_16x16x32_bf16 v[8:11], v[232:235], v[192:195], v[8:11]
	v_mfma_f32_16x16x32_bf16 v[4:7], v[208:211], v[200:203], v[4:7]
	v_mfma_f32_16x16x32_bf16 v[0:3], v[232:235], v[200:203], v[0:3]
	s_setprio 0
	s_add_i32 s59, s59, 2
	s_add_u32 s5, s5, 0x100
	s_addc_u32 s9, s9, 0
	s_add_u32 s16, s16, 0x100
	s_addc_u32 s17, s17, 0
	s_cmp_gt_u32 s59, 13
	s_barrier
	s_cbranch_scc0 .LBB0_321
	s_lshl_b32 s0, s14, 8
	v_mbcnt_lo_u32_b32 v139, -1, 0
	v_mbcnt_hi_u32_b32 v139, -1, v139
	s_lshl_b32 s1, s21, 8
	v_ashrrev_i32_e32 v138, 1, v139
	s_add_i32 s0, s0, s51
	v_and_b32_e32 v138, -8, v138
	s_or_b32 s1, s1, s52
	v_and_or_b32 v156, v139, 15, s0
	v_add_u32_e32 v138, s1, v138
	v_ashrrev_i32_e32 v157, 31, v156
	v_ashrrev_i32_e32 v139, 31, v138
	v_lshlrev_b64 v[158:159], 11, v[156:157]
	v_lshl_add_u64 v[158:159], s[26:27], 0, v[158:159]
	v_lshlrev_b64 v[160:161], 1, v[138:139]
	v_lshl_add_u64 v[138:139], v[158:159], 0, v[160:161]
	v_cvt_pk_bf16_f32 v60, v60, v61
	v_cvt_pk_bf16_f32 v61, v62, v63
	v_cvt_pk_bf16_f32 v62, v56, v57
	v_add_co_u32_e32 v56, vcc, s31, v138
	v_cvt_pk_bf16_f32 v112, v112, v113
	v_cvt_pk_bf16_f32 v113, v114, v115
	v_cvt_pk_bf16_f32 v114, v104, v105
	v_or_b32_e32 v104, 16, v156
	s_nop 0
	v_addc_co_u32_e32 v57, vcc, 0, v139, vcc
	v_cvt_pk_bf16_f32 v48, v48, v49
	v_cvt_pk_bf16_f32 v49, v50, v51
	v_cvt_pk_bf16_f32 v51, v42, v43
	v_cvt_pk_bf16_f32 v42, v44, v45
	v_add_co_u32_e32 v44, vcc, s42, v138
	v_ashrrev_i32_e32 v105, 31, v104
	v_cvt_pk_bf16_f32 v96, v96, v97
	v_cvt_pk_bf16_f32 v97, v98, v99
	v_cvt_pk_bf16_f32 v98, v88, v89
	v_or_b32_e32 v88, 32, v156
	v_addc_co_u32_e32 v45, vcc, 0, v139, vcc
	v_lshlrev_b64 v[104:105], 11, v[104:105]
	v_ashrrev_i32_e32 v89, 31, v88
	v_cvt_pk_bf16_f32 v80, v80, v81
	v_cvt_pk_bf16_f32 v81, v82, v83
	v_cvt_pk_bf16_f32 v82, v72, v73
	v_or_b32_e32 v72, 48, v156
	s_mov_b64 s[0:1], 0x40000
	v_cvt_pk_bf16_f32 v32, v32, v33
	v_cvt_pk_bf16_f32 v33, v34, v35
	v_cvt_pk_bf16_f32 v35, v26, v27
	v_cvt_pk_bf16_f32 v26, v28, v29
	v_add_co_u32_e32 v28, vcc, s43, v138
	v_lshl_add_u64 v[104:105], s[26:27], 0, v[104:105]
	v_lshlrev_b64 v[88:89], 11, v[88:89]
	v_ashrrev_i32_e32 v73, 31, v72
	v_cvt_pk_bf16_f32 v68, v68, v69
	v_cvt_pk_bf16_f32 v69, v70, v71
	v_cvt_pk_bf16_f32 v70, v64, v65
	v_lshl_add_u64 v[64:65], v[138:139], 0, s[0:1]
	s_mov_b64 s[0:1], 0x48000
	v_addc_co_u32_e32 v29, vcc, 0, v139, vcc
	v_cvt_pk_bf16_f32 v115, v106, v107
	flat_store_dwordx4 v[138:139], v[112:115] offset:256
	v_lshl_add_u64 v[88:89], s[26:27], 0, v[88:89]
	v_lshlrev_b64 v[72:73], 11, v[72:73]
	v_lshl_add_u64 v[112:113], v[104:105], 0, v[160:161]
	v_cvt_pk_bf16_f32 v50, v40, v41
	flat_store_dwordx4 v[64:65], v[48:51] offset:256
	v_cvt_pk_bf16_f32 v16, v16, v17
	v_cvt_pk_bf16_f32 v17, v18, v19
	v_cvt_pk_bf16_f32 v19, v10, v11
	v_cvt_pk_bf16_f32 v10, v12, v13
	v_add_co_u32_e32 v12, vcc, s47, v138
	s_nop 0
	v_lshl_add_u64 v[48:49], v[138:139], 0, s[0:1]
	s_mov_b64 s[0:1], 0x50000
	v_cvt_pk_bf16_f32 v99, v90, v91
	flat_store_dwordx4 v[112:113], v[96:99] offset:256
	v_lshl_add_u64 v[72:73], s[26:27], 0, v[72:73]
	v_cvt_pk_bf16_f32 v34, v24, v25
	flat_store_dwordx4 v[48:49], v[32:35] offset:256
	v_lshl_add_u64 v[96:97], v[88:89], 0, v[160:161]
	v_addc_co_u32_e32 v13, vcc, 0, v139, vcc
	v_lshl_add_u64 v[32:33], v[138:139], 0, s[0:1]
	s_mov_b64 s[0:1], 0x58000
	v_cvt_pk_bf16_f32 v83, v74, v75
	flat_store_dwordx4 v[96:97], v[80:83] offset:256
	v_cvt_pk_bf16_f32 v18, v8, v9
	flat_store_dwordx4 v[32:33], v[16:19] offset:256
	s_and_b64 vcc, exec, s[6:7]
	v_lshl_add_u64 v[80:81], v[72:73], 0, v[160:161]
	v_lshl_add_u64 v[16:17], v[138:139], 0, s[0:1]
	s_mov_b32 s21, s8
	s_mov_b32 s14, s4
	s_mov_b64 s[16:17], s[12:13]
	s_mov_b64 s[0:1], s[10:11]
	v_cvt_pk_bf16_f32 v124, v124, v125
	v_cvt_pk_bf16_f32 v125, v126, v127
	v_cvt_pk_bf16_f32 v126, v120, v121
	v_cvt_pk_bf16_f32 v127, v122, v123
	flat_store_dwordx4 v[138:139], v[124:127]
	v_cvt_pk_bf16_f32 v104, v116, v117
	v_cvt_pk_bf16_f32 v105, v118, v119
	v_cvt_pk_bf16_f32 v106, v108, v109
	v_cvt_pk_bf16_f32 v107, v110, v111
	flat_store_dwordx4 v[112:113], v[104:107]
	v_cvt_pk_bf16_f32 v88, v100, v101
	v_cvt_pk_bf16_f32 v89, v102, v103
	v_cvt_pk_bf16_f32 v90, v92, v93
	v_cvt_pk_bf16_f32 v91, v94, v95
	flat_store_dwordx4 v[96:97], v[88:91]
	v_cvt_pk_bf16_f32 v72, v84, v85
	v_cvt_pk_bf16_f32 v73, v86, v87
	v_cvt_pk_bf16_f32 v74, v76, v77
	v_cvt_pk_bf16_f32 v75, v78, v79
	flat_store_dwordx4 v[80:81], v[72:75]
	v_cvt_pk_bf16_f32 v71, v66, v67
	flat_store_dwordx4 v[80:81], v[68:71] offset:256
	v_cvt_pk_bf16_f32 v63, v58, v59
	flat_store_dwordx4 v[56:57], v[60:63]
	v_cvt_pk_bf16_f32 v40, v52, v53
	v_cvt_pk_bf16_f32 v41, v54, v55
	v_cvt_pk_bf16_f32 v43, v46, v47
	flat_store_dwordx4 v[44:45], v[40:43]
	v_cvt_pk_bf16_f32 v24, v36, v37
	v_cvt_pk_bf16_f32 v25, v38, v39
	v_cvt_pk_bf16_f32 v27, v30, v31
	flat_store_dwordx4 v[28:29], v[24:27]
	v_cvt_pk_bf16_f32 v8, v20, v21
	v_cvt_pk_bf16_f32 v9, v22, v23
	v_cvt_pk_bf16_f32 v11, v14, v15
	flat_store_dwordx4 v[12:13], v[8:11]
	v_cvt_pk_bf16_f32 v4, v4, v5
	v_cvt_pk_bf16_f32 v5, v6, v7
	v_cvt_pk_bf16_f32 v6, v0, v1
	v_cvt_pk_bf16_f32 v7, v2, v3
	flat_store_dwordx4 v[16:17], v[4:7] offset:256
	s_cbranch_vccz .LBB0_314
	s_waitcnt vmcnt(0)
	s_cmpk_gt_u32 s37, 0xff
	s_cbranch_scc1 .LBB0_325
	s_barrier

.LBB0_405:
	s_add_i32 s21, s0, 2
	s_add_u32 s1, vcc_lo, 0xfffe0080
	s_addc_u32 s2, vcc_hi, -1
	s_add_i32 s18, 0, 0x10000
	v_add_u32_e32 v164, s18, v178
	ds_read_b128 v[128:131], v164
	ds_read_b128 v[132:135], v164 offset:1024
	ds_read_b128 v[136:139], v164 offset:2048
	ds_read_b128 v[164:167], v164 offset:3072
	s_cmp_eq_u32 s5, s0
	s_cselect_b32 s0, s10, s17
	s_cselect_b32 s89, s9, s2
	s_cselect_b32 s88, s8, s1
	s_cselect_b32 s1, s11, s20
	v_lshl_add_u64 v[176:177], vcc, 0, v[162:163]
	s_add_i32 m0, s97, 0xc000
	ds_read_b128 v[168:171], v179
	ds_read_b128 v[172:175], v179 offset:1024
	ds_read_b128 v[180:183], v179 offset:2048
	ds_read_b128 v[184:187], v179 offset:3072
	ds_read_b128 v[188:191], v179 offset:4096
	ds_read_b128 v[192:195], v179 offset:5120
	ds_read_b128 v[196:199], v179 offset:6144
	ds_read_b128 v[200:203], v179 offset:7168
	global_load_lds_dwordx4 v[176:177], off
	v_lshl_add_u64 v[176:177], vcc, 0, v[160:161]
	s_add_i32 m0, s97, 0xe000
	s_nop 0
	global_load_lds_dwordx4 v[176:177], off
	s_waitcnt lgkmcnt(8)
	s_barrier
	s_waitcnt lgkmcnt(0)
	s_setprio 1
	v_mfma_f32_16x16x32_bf16 v[120:123], v[128:131], v[168:171], v[120:123]
	v_mfma_f32_16x16x32_bf16 v[68:71], v[136:139], v[168:171], v[68:71]
	v_mfma_f32_16x16x32_bf16 v[116:119], v[128:131], v[180:183], v[116:119]
	v_mfma_f32_16x16x32_bf16 v[60:63], v[136:139], v[180:183], v[60:63]
	v_mfma_f32_16x16x32_bf16 v[108:111], v[128:131], v[188:191], v[108:111]
	v_mfma_f32_16x16x32_bf16 v[44:47], v[136:139], v[188:191], v[44:47]
	v_mfma_f32_16x16x32_bf16 v[100:103], v[128:131], v[196:199], v[100:103]
	v_mfma_f32_16x16x32_bf16 v[36:39], v[136:139], v[196:199], v[36:39]
	v_mfma_f32_16x16x32_bf16 v[120:123], v[132:135], v[172:175], v[120:123]
	v_mfma_f32_16x16x32_bf16 v[68:71], v[164:167], v[172:175], v[68:71]
	v_mfma_f32_16x16x32_bf16 v[116:119], v[132:135], v[184:187], v[116:119]
	v_mfma_f32_16x16x32_bf16 v[60:63], v[164:167], v[184:187], v[60:63]
	v_mfma_f32_16x16x32_bf16 v[108:111], v[132:135], v[192:195], v[108:111]
	v_mfma_f32_16x16x32_bf16 v[44:47], v[164:167], v[192:195], v[44:47]
	v_mfma_f32_16x16x32_bf16 v[100:103], v[132:135], v[200:203], v[100:103]
	v_mfma_f32_16x16x32_bf16 v[36:39], v[164:167], v[200:203], v[36:39]
	s_setprio 0
	s_barrier
	s_add_i32 s2, 0, 0x14000
	v_add_u32_e32 v176, s2, v178
	s_add_i32 s18, s18, s59
	ds_read_b128 v[204:207], v176
	ds_read_b128 v[208:211], v176 offset:1024
	s_mov_b32 m0, s18
	ds_read_b128 v[228:231], v176 offset:2048
	global_load_lds_dwordx4 v140, s[0:1]
	s_add_i32 m0, s18, 0x2000
	ds_read_b128 v[232:235], v176 offset:3072
	global_load_lds_dwordx4 v158, s[0:1]
	s_barrier
	s_waitcnt lgkmcnt(0)
	s_setprio 1
	v_mfma_f32_16x16x32_bf16 v[124:127], v[204:207], v[168:171], v[124:127]
	v_mfma_f32_16x16x32_bf16 v[64:67], v[228:231], v[168:171], v[64:67]
	v_mfma_f32_16x16x32_bf16 v[112:115], v[204:207], v[180:183], v[112:115]
	v_mfma_f32_16x16x32_bf16 v[56:59], v[228:231], v[180:183], v[56:59]
	v_mfma_f32_16x16x32_bf16 v[104:107], v[204:207], v[188:191], v[104:107]
	v_mfma_f32_16x16x32_bf16 v[40:43], v[228:231], v[188:191], v[40:43]
	v_mfma_f32_16x16x32_bf16 v[96:99], v[204:207], v[196:199], v[96:99]
	v_mfma_f32_16x16x32_bf16 v[32:35], v[228:231], v[196:199], v[32:35]
	v_mfma_f32_16x16x32_bf16 v[124:127], v[208:211], v[172:175], v[124:127]
	v_mfma_f32_16x16x32_bf16 v[64:67], v[232:235], v[172:175], v[64:67]
	v_mfma_f32_16x16x32_bf16 v[112:115], v[208:211], v[184:187], v[112:115]
	v_mfma_f32_16x16x32_bf16 v[56:59], v[232:235], v[184:187], v[56:59]
	v_mfma_f32_16x16x32_bf16 v[104:107], v[208:211], v[192:195], v[104:107]
	v_mfma_f32_16x16x32_bf16 v[40:43], v[232:235], v[192:195], v[40:43]
	v_mfma_f32_16x16x32_bf16 v[96:99], v[208:211], v[200:203], v[96:99]
	v_mfma_f32_16x16x32_bf16 v[32:35], v[232:235], v[200:203], v[32:35]
	s_setprio 0
	s_mov_b32 m0, s97
	s_barrier
	ds_read_b128 v[168:171], v179 offset:16384
	ds_read_b128 v[172:175], v179 offset:17408
	ds_read_b128 v[180:183], v179 offset:18432
	ds_read_b128 v[184:187], v179 offset:19456
	ds_read_b128 v[188:191], v179 offset:20480
	ds_read_b128 v[192:195], v179 offset:21504
	ds_read_b128 v[196:199], v179 offset:22528
	global_load_lds_dwordx4 v154, s[88:89]
	s_mov_b32 m0, s74
	ds_read_b128 v[200:203], v179 offset:23552
	global_load_lds_dwordx4 v156, s[88:89]
	s_barrier
	s_waitcnt lgkmcnt(0)
	s_setprio 1
	v_mfma_f32_16x16x32_bf16 v[92:95], v[128:131], v[168:171], v[92:95]
	v_mfma_f32_16x16x32_bf16 v[28:31], v[136:139], v[168:171], v[28:31]
	v_mfma_f32_16x16x32_bf16 v[84:87], v[128:131], v[180:183], v[84:87]
	v_mfma_f32_16x16x32_bf16 v[20:23], v[136:139], v[180:183], v[20:23]
	v_mfma_f32_16x16x32_bf16 v[76:79], v[128:131], v[188:191], v[76:79]
	v_mfma_f32_16x16x32_bf16 v[12:15], v[136:139], v[188:191], v[12:15]
	v_mfma_f32_16x16x32_bf16 v[52:55], v[128:131], v[196:199], v[52:55]
	v_mfma_f32_16x16x32_bf16 v[4:7], v[136:139], v[196:199], v[4:7]
	v_mfma_f32_16x16x32_bf16 v[92:95], v[132:135], v[172:175], v[92:95]
	v_mfma_f32_16x16x32_bf16 v[28:31], v[164:167], v[172:175], v[28:31]
	v_mfma_f32_16x16x32_bf16 v[84:87], v[132:135], v[184:187], v[84:87]
	v_mfma_f32_16x16x32_bf16 v[20:23], v[164:167], v[184:187], v[20:23]
	v_mfma_f32_16x16x32_bf16 v[76:79], v[132:135], v[192:195], v[76:79]
	v_mfma_f32_16x16x32_bf16 v[12:15], v[164:167], v[192:195], v[12:15]
	v_mfma_f32_16x16x32_bf16 v[52:55], v[132:135], v[200:203], v[52:55]
	v_mfma_f32_16x16x32_bf16 v[4:7], v[164:167], v[200:203], v[4:7]
	s_setprio 0
	s_barrier
	s_add_i32 s2, s2, s59
	s_mov_b32 m0, s2
	s_add_u32 s18, s0, 0x10000
	s_addc_u32 s19, s1, 0
	global_load_lds_dwordx4 v140, s[18:19]
	s_add_i32 m0, s2, 0x2000
	s_nop 0
	global_load_lds_dwordx4 v158, s[18:19]
	s_waitcnt vmcnt(6)
	s_barrier
	s_setprio 1
	v_mfma_f32_16x16x32_bf16 v[88:91], v[204:207], v[168:171], v[88:91]
	v_mfma_f32_16x16x32_bf16 v[24:27], v[228:231], v[168:171], v[24:27]
	v_mfma_f32_16x16x32_bf16 v[80:83], v[204:207], v[180:183], v[80:83]
	v_mfma_f32_16x16x32_bf16 v[16:19], v[228:231], v[180:183], v[16:19]
	v_mfma_f32_16x16x32_bf16 v[72:75], v[204:207], v[188:191], v[72:75]
	v_mfma_f32_16x16x32_bf16 v[8:11], v[228:231], v[188:191], v[8:11]
	v_mfma_f32_16x16x32_bf16 v[48:51], v[204:207], v[196:199], v[48:51]
	v_mfma_f32_16x16x32_bf16 v[0:3], v[228:231], v[196:199], v[0:3]
	v_mfma_f32_16x16x32_bf16 v[88:91], v[208:211], v[172:175], v[88:91]
	v_mfma_f32_16x16x32_bf16 v[24:27], v[232:235], v[172:175], v[24:27]
	v_mfma_f32_16x16x32_bf16 v[80:83], v[208:211], v[184:187], v[80:83]
	v_mfma_f32_16x16x32_bf16 v[16:19], v[232:235], v[184:187], v[16:19]
	v_mfma_f32_16x16x32_bf16 v[72:75], v[208:211], v[192:195], v[72:75]
	v_mfma_f32_16x16x32_bf16 v[8:11], v[232:235], v[192:195], v[8:11]
	v_mfma_f32_16x16x32_bf16 v[48:51], v[208:211], v[200:203], v[48:51]
	v_mfma_f32_16x16x32_bf16 v[0:3], v[232:235], v[200:203], v[0:3]
	s_setprio 0
	s_add_i32 s2, 0, 0x18000
	v_add_u32_e32 v164, s2, v178
	s_barrier
	ds_read_b128 v[128:131], v164
	ds_read_b128 v[132:135], v164 offset:1024
	ds_read_b128 v[136:139], v164 offset:2048
	ds_read_b128 v[164:167], v164 offset:3072
	s_add_u32 s18, s88, 0x20000
	s_addc_u32 s19, s89, 0
	s_mov_b32 m0, s75
	ds_read_b128 v[168:171], v179 offset:32768
	ds_read_b128 v[172:175], v179 offset:33792
	ds_read_b128 v[180:183], v179 offset:34816
	ds_read_b128 v[184:187], v179 offset:35840
	ds_read_b128 v[188:191], v179 offset:36864
	ds_read_b128 v[192:195], v179 offset:37888
	ds_read_b128 v[196:199], v179 offset:38912
	global_load_lds_dwordx4 v154, s[18:19]
	s_mov_b32 m0, s72
	ds_read_b128 v[200:203], v179 offset:39936
	global_load_lds_dwordx4 v156, s[18:19]
	s_waitcnt lgkmcnt(8)
	s_barrier
	s_waitcnt lgkmcnt(0)
	s_setprio 1
	v_mfma_f32_16x16x32_bf16 v[120:123], v[128:131], v[168:171], v[120:123]
	v_mfma_f32_16x16x32_bf16 v[68:71], v[136:139], v[168:171], v[68:71]
	v_mfma_f32_16x16x32_bf16 v[116:119], v[128:131], v[180:183], v[116:119]
	v_mfma_f32_16x16x32_bf16 v[60:63], v[136:139], v[180:183], v[60:63]
	v_mfma_f32_16x16x32_bf16 v[108:111], v[128:131], v[188:191], v[108:111]
	v_mfma_f32_16x16x32_bf16 v[44:47], v[136:139], v[188:191], v[44:47]
	v_mfma_f32_16x16x32_bf16 v[100:103], v[128:131], v[196:199], v[100:103]
	v_mfma_f32_16x16x32_bf16 v[36:39], v[136:139], v[196:199], v[36:39]
	v_mfma_f32_16x16x32_bf16 v[120:123], v[132:135], v[172:175], v[120:123]
	v_mfma_f32_16x16x32_bf16 v[68:71], v[164:167], v[172:175], v[68:71]
	v_mfma_f32_16x16x32_bf16 v[116:119], v[132:135], v[184:187], v[116:119]
	v_mfma_f32_16x16x32_bf16 v[60:63], v[164:167], v[184:187], v[60:63]
	v_mfma_f32_16x16x32_bf16 v[108:111], v[132:135], v[192:195], v[108:111]
	v_mfma_f32_16x16x32_bf16 v[44:47], v[164:167], v[192:195], v[44:47]
	v_mfma_f32_16x16x32_bf16 v[100:103], v[132:135], v[200:203], v[100:103]
	v_mfma_f32_16x16x32_bf16 v[36:39], v[164:167], v[200:203], v[36:39]
	s_setprio 0
	s_barrier
	s_add_i32 s18, 0, 0x1c000
	s_add_i32 s2, s2, s59
	v_add_u32_e32 v232, s18, v178
	s_mov_b32 m0, s2
	ds_read_b128 v[204:207], v232
	ds_read_b128 v[208:211], v232 offset:1024
	ds_read_b128 v[228:231], v232 offset:2048
	ds_read_b128 v[232:235], v232 offset:3072
	s_add_u32 s100, s0, 0x80
	s_addc_u32 s101, s1, 0
	global_load_lds_dwordx4 v140, s[100:101]
	s_add_i32 m0, s2, 0x2000
	s_nop 0
	global_load_lds_dwordx4 v158, s[100:101]
	s_barrier
	s_waitcnt lgkmcnt(0)
	s_setprio 1
	v_mfma_f32_16x16x32_bf16 v[124:127], v[204:207], v[168:171], v[124:127]
	v_mfma_f32_16x16x32_bf16 v[64:67], v[228:231], v[168:171], v[64:67]
	v_mfma_f32_16x16x32_bf16 v[112:115], v[204:207], v[180:183], v[112:115]
	v_mfma_f32_16x16x32_bf16 v[56:59], v[228:231], v[180:183], v[56:59]
	v_mfma_f32_16x16x32_bf16 v[104:107], v[204:207], v[188:191], v[104:107]
	v_mfma_f32_16x16x32_bf16 v[40:43], v[228:231], v[188:191], v[40:43]
	v_mfma_f32_16x16x32_bf16 v[96:99], v[204:207], v[196:199], v[96:99]
	v_mfma_f32_16x16x32_bf16 v[32:35], v[228:231], v[196:199], v[32:35]
	v_mfma_f32_16x16x32_bf16 v[124:127], v[208:211], v[172:175], v[124:127]
	v_mfma_f32_16x16x32_bf16 v[64:67], v[232:235], v[172:175], v[64:67]
	v_mfma_f32_16x16x32_bf16 v[112:115], v[208:211], v[184:187], v[112:115]
	v_mfma_f32_16x16x32_bf16 v[56:59], v[232:235], v[184:187], v[56:59]
	v_mfma_f32_16x16x32_bf16 v[104:107], v[208:211], v[192:195], v[104:107]
	v_mfma_f32_16x16x32_bf16 v[40:43], v[232:235], v[192:195], v[40:43]
	v_mfma_f32_16x16x32_bf16 v[96:99], v[208:211], v[200:203], v[96:99]
	v_mfma_f32_16x16x32_bf16 v[32:35], v[232:235], v[200:203], v[32:35]
	s_setprio 0
	s_mov_b32 m0, s38
	s_barrier
	ds_read_b128 v[168:171], v179 offset:49152
	ds_read_b128 v[172:175], v179 offset:50176
	ds_read_b128 v[180:183], v179 offset:51200
	ds_read_b128 v[184:187], v179 offset:52224
	ds_read_b128 v[188:191], v179 offset:53248
	ds_read_b128 v[192:195], v179 offset:54272
	ds_read_b128 v[196:199], v179 offset:55296
	ds_read_b128 v[200:203], v179 offset:56320
	s_add_u32 s100, s88, 0x80
	s_addc_u32 s101, s89, 0
	global_load_lds_dwordx4 v154, s[100:101]
	s_mov_b32 m0, s39
	s_nop 0
	global_load_lds_dwordx4 v156, s[100:101]
	s_barrier
	s_waitcnt lgkmcnt(0)
	s_setprio 1
	v_mfma_f32_16x16x32_bf16 v[92:95], v[128:131], v[168:171], v[92:95]
	v_mfma_f32_16x16x32_bf16 v[28:31], v[136:139], v[168:171], v[28:31]
	v_mfma_f32_16x16x32_bf16 v[84:87], v[128:131], v[180:183], v[84:87]
	v_mfma_f32_16x16x32_bf16 v[20:23], v[136:139], v[180:183], v[20:23]
	v_mfma_f32_16x16x32_bf16 v[76:79], v[128:131], v[188:191], v[76:79]
	v_mfma_f32_16x16x32_bf16 v[12:15], v[136:139], v[188:191], v[12:15]
	v_mfma_f32_16x16x32_bf16 v[52:55], v[128:131], v[196:199], v[52:55]
	v_mfma_f32_16x16x32_bf16 v[4:7], v[136:139], v[196:199], v[4:7]
	v_mfma_f32_16x16x32_bf16 v[92:95], v[132:135], v[172:175], v[92:95]
	v_mfma_f32_16x16x32_bf16 v[28:31], v[164:167], v[172:175], v[28:31]
	v_mfma_f32_16x16x32_bf16 v[84:87], v[132:135], v[184:187], v[84:87]
	v_mfma_f32_16x16x32_bf16 v[20:23], v[164:167], v[184:187], v[20:23]
	v_mfma_f32_16x16x32_bf16 v[76:79], v[132:135], v[192:195], v[76:79]
	v_mfma_f32_16x16x32_bf16 v[12:15], v[164:167], v[192:195], v[12:15]
	v_mfma_f32_16x16x32_bf16 v[52:55], v[132:135], v[200:203], v[52:55]
	v_mfma_f32_16x16x32_bf16 v[4:7], v[164:167], v[200:203], v[4:7]
	s_setprio 0
	s_barrier
	s_add_i32 s2, s18, s59
	s_mov_b32 m0, s2
	s_add_u32 s0, s0, 0x10080
	s_addc_u32 s1, s1, 0
	global_load_lds_dwordx4 v140, s[0:1]
	s_add_i32 m0, s2, 0x2000
	s_nop 0
	global_load_lds_dwordx4 v158, s[0:1]
	s_waitcnt vmcnt(6)
	s_barrier
	s_setprio 1
	v_mfma_f32_16x16x32_bf16 v[88:91], v[204:207], v[168:171], v[88:91]
	v_mfma_f32_16x16x32_bf16 v[24:27], v[228:231], v[168:171], v[24:27]
	v_mfma_f32_16x16x32_bf16 v[80:83], v[204:207], v[180:183], v[80:83]
	v_mfma_f32_16x16x32_bf16 v[16:19], v[228:231], v[180:183], v[16:19]
	v_mfma_f32_16x16x32_bf16 v[72:75], v[204:207], v[188:191], v[72:75]
	v_mfma_f32_16x16x32_bf16 v[8:11], v[228:231], v[188:191], v[8:11]
	v_mfma_f32_16x16x32_bf16 v[48:51], v[204:207], v[196:199], v[48:51]
	v_mfma_f32_16x16x32_bf16 v[0:3], v[228:231], v[196:199], v[0:3]
	v_mfma_f32_16x16x32_bf16 v[88:91], v[208:211], v[172:175], v[88:91]
	v_mfma_f32_16x16x32_bf16 v[24:27], v[232:235], v[172:175], v[24:27]
	v_mfma_f32_16x16x32_bf16 v[80:83], v[208:211], v[184:187], v[80:83]
	v_mfma_f32_16x16x32_bf16 v[16:19], v[232:235], v[184:187], v[16:19]
	v_mfma_f32_16x16x32_bf16 v[72:75], v[208:211], v[192:195], v[72:75]
	v_mfma_f32_16x16x32_bf16 v[8:11], v[232:235], v[192:195], v[8:11]
	v_mfma_f32_16x16x32_bf16 v[48:51], v[208:211], v[200:203], v[48:51]
	v_mfma_f32_16x16x32_bf16 v[0:3], v[232:235], v[200:203], v[0:3]
	s_setprio 0
	s_add_u32 s17, s17, 0x100
	s_addc_u32 s20, s20, 0
	s_add_u32 vcc_lo, vcc_lo, 0x100
	s_addc_u32 vcc_hi, vcc_hi, 0
	s_cmp_ge_i32 s21, s36
	s_mov_b32 s0, s21
	s_barrier
	s_cbranch_scc0 .LBB0_405
	s_branch .LBB0_392

.LBB0_507:
	s_add_u32 s0, s8, 0xfffc0080
	s_addc_u32 s1, s9, -1
	s_add_i32 s2, 0, 0x10000
	v_add_u32_e32 v140, s2, v168
	ds_read_b128 v[154:157], v140
	ds_read_b128 v[158:161], v140 offset:1024
	ds_read_b128 v[162:165], v140 offset:2048
	ds_read_b128 v[170:173], v140 offset:3072
	s_cmp_eq_u32 s21, 12
	s_cselect_b32 s31, s29, s1
	s_cselect_b32 s30, s28, s0
	s_cselect_b32 s1, s11, s19
	s_cselect_b32 s0, s10, s17
	s_add_i32 m0, s36, 0xc000
	ds_read_b128 v[174:177], v169
	ds_read_b128 v[178:181], v169 offset:1024
	ds_read_b128 v[182:185], v169 offset:2048
	ds_read_b128 v[186:189], v169 offset:3072
	ds_read_b128 v[190:193], v169 offset:4096
	ds_read_b128 v[194:197], v169 offset:5120
	ds_read_b128 v[198:201], v169 offset:6144
	global_load_lds_dwordx4 v138, s[8:9]
	s_add_i32 m0, s36, 0xe000
	ds_read_b128 v[202:205], v169 offset:7168
	global_load_lds_dwordx4 v136, s[8:9]
	s_waitcnt lgkmcnt(8)
	s_barrier
	s_waitcnt lgkmcnt(0)
	s_setprio 1
	v_mfma_f32_16x16x32_bf16 v[124:127], v[154:157], v[174:177], v[124:127]
	v_mfma_f32_16x16x32_bf16 v[120:123], v[162:165], v[174:177], v[120:123]
	v_mfma_f32_16x16x32_bf16 v[112:115], v[154:157], v[182:185], v[112:115]
	v_mfma_f32_16x16x32_bf16 v[104:107], v[162:165], v[182:185], v[104:107]
	v_mfma_f32_16x16x32_bf16 v[96:99], v[154:157], v[190:193], v[96:99]
	v_mfma_f32_16x16x32_bf16 v[88:91], v[162:165], v[190:193], v[88:91]
	v_mfma_f32_16x16x32_bf16 v[80:83], v[154:157], v[198:201], v[80:83]
	v_mfma_f32_16x16x32_bf16 v[72:75], v[162:165], v[198:201], v[72:75]
	v_mfma_f32_16x16x32_bf16 v[124:127], v[158:161], v[178:181], v[124:127]
	v_mfma_f32_16x16x32_bf16 v[120:123], v[170:173], v[178:181], v[120:123]
	v_mfma_f32_16x16x32_bf16 v[112:115], v[158:161], v[186:189], v[112:115]
	v_mfma_f32_16x16x32_bf16 v[104:107], v[170:173], v[186:189], v[104:107]
	v_mfma_f32_16x16x32_bf16 v[96:99], v[158:161], v[194:197], v[96:99]
	v_mfma_f32_16x16x32_bf16 v[88:91], v[170:173], v[194:197], v[88:91]
	v_mfma_f32_16x16x32_bf16 v[80:83], v[158:161], v[202:205], v[80:83]
	v_mfma_f32_16x16x32_bf16 v[72:75], v[170:173], v[202:205], v[72:75]
	s_setprio 0
	s_barrier
	s_add_i32 s49, 0, 0x14000
	s_add_i32 s2, s2, s35
	v_add_u32_e32 v140, s49, v168
	s_mov_b32 m0, s2
	ds_read_b128 v[206:209], v140
	ds_read_b128 v[228:231], v140 offset:1024
	ds_read_b128 v[232:235], v140 offset:2048
	global_load_lds_dwordx4 v130, s[0:1]
	s_add_i32 m0, s2, 0x2000
	ds_read_b128 v[236:239], v140 offset:3072
	global_load_lds_dwordx4 v134, s[0:1]
	s_barrier
	s_waitcnt lgkmcnt(0)
	s_setprio 1
	v_mfma_f32_16x16x32_bf16 v[116:119], v[206:209], v[174:177], v[116:119]
	v_mfma_f32_16x16x32_bf16 v[108:111], v[232:235], v[174:177], v[108:111]
	v_mfma_f32_16x16x32_bf16 v[100:103], v[206:209], v[182:185], v[100:103]
	v_mfma_f32_16x16x32_bf16 v[92:95], v[232:235], v[182:185], v[92:95]
	v_mfma_f32_16x16x32_bf16 v[84:87], v[206:209], v[190:193], v[84:87]
	v_mfma_f32_16x16x32_bf16 v[76:79], v[232:235], v[190:193], v[76:79]
	v_mfma_f32_16x16x32_bf16 v[68:71], v[206:209], v[198:201], v[68:71]
	v_mfma_f32_16x16x32_bf16 v[64:67], v[232:235], v[198:201], v[64:67]
	v_mfma_f32_16x16x32_bf16 v[116:119], v[228:231], v[178:181], v[116:119]
	v_mfma_f32_16x16x32_bf16 v[108:111], v[236:239], v[178:181], v[108:111]
	v_mfma_f32_16x16x32_bf16 v[100:103], v[228:231], v[186:189], v[100:103]
	v_mfma_f32_16x16x32_bf16 v[92:95], v[236:239], v[186:189], v[92:95]
	v_mfma_f32_16x16x32_bf16 v[84:87], v[228:231], v[194:197], v[84:87]
	v_mfma_f32_16x16x32_bf16 v[76:79], v[236:239], v[194:197], v[76:79]
	v_mfma_f32_16x16x32_bf16 v[68:71], v[228:231], v[202:205], v[68:71]
	v_mfma_f32_16x16x32_bf16 v[64:67], v[236:239], v[202:205], v[64:67]
	s_setprio 0
	s_mov_b32 m0, s36
	v_lshl_add_u64 v[240:241], s[30:31], 0, v[128:129]
	s_barrier
	ds_read_b128 v[174:177], v169 offset:16384
	ds_read_b128 v[178:181], v169 offset:17408
	ds_read_b128 v[182:185], v169 offset:18432
	ds_read_b128 v[186:189], v169 offset:19456
	ds_read_b128 v[190:193], v169 offset:20480
	ds_read_b128 v[194:197], v169 offset:21504
	ds_read_b128 v[198:201], v169 offset:22528
	ds_read_b128 v[202:205], v169 offset:23552
	global_load_lds_dwordx4 v128, s[30:31]
	v_lshl_add_u64 v[242:243], s[30:31], 0, v[132:133]
	s_mov_b32 m0, s37
	s_nop 0
	global_load_lds_dwordx4 v132, s[30:31]
	s_barrier
	s_waitcnt lgkmcnt(0)
	s_setprio 1
	v_mfma_f32_16x16x32_bf16 v[60:63], v[154:157], v[174:177], v[60:63]
	v_mfma_f32_16x16x32_bf16 v[56:59], v[162:165], v[174:177], v[56:59]
	v_mfma_f32_16x16x32_bf16 v[48:51], v[154:157], v[182:185], v[48:51]
	v_mfma_f32_16x16x32_bf16 v[40:43], v[162:165], v[182:185], v[40:43]
	v_mfma_f32_16x16x32_bf16 v[32:35], v[154:157], v[190:193], v[32:35]
	v_mfma_f32_16x16x32_bf16 v[24:27], v[162:165], v[190:193], v[24:27]
	v_mfma_f32_16x16x32_bf16 v[16:19], v[154:157], v[198:201], v[16:19]
	v_mfma_f32_16x16x32_bf16 v[8:11], v[162:165], v[198:201], v[8:11]
	v_mfma_f32_16x16x32_bf16 v[60:63], v[158:161], v[178:181], v[60:63]
	v_mfma_f32_16x16x32_bf16 v[56:59], v[170:173], v[178:181], v[56:59]
	v_mfma_f32_16x16x32_bf16 v[48:51], v[158:161], v[186:189], v[48:51]
	v_mfma_f32_16x16x32_bf16 v[40:43], v[170:173], v[186:189], v[40:43]
	v_mfma_f32_16x16x32_bf16 v[32:35], v[158:161], v[194:197], v[32:35]
	v_mfma_f32_16x16x32_bf16 v[24:27], v[170:173], v[194:197], v[24:27]
	v_mfma_f32_16x16x32_bf16 v[16:19], v[158:161], v[202:205], v[16:19]
	v_mfma_f32_16x16x32_bf16 v[8:11], v[170:173], v[202:205], v[8:11]
	s_setprio 0
	s_barrier
	s_add_i32 s2, s49, s35
	s_mov_b32 m0, s2
	s_add_u32 s42, s0, 0x40000
	s_addc_u32 s43, s1, 0
	global_load_lds_dwordx4 v130, s[42:43]
	s_add_i32 m0, s2, 0x2000
	s_nop 0
	global_load_lds_dwordx4 v134, s[42:43]
	s_waitcnt vmcnt(6)
	s_barrier
	s_setprio 1
	v_mfma_f32_16x16x32_bf16 v[52:55], v[206:209], v[174:177], v[52:55]
	v_mfma_f32_16x16x32_bf16 v[44:47], v[232:235], v[174:177], v[44:47]
	v_mfma_f32_16x16x32_bf16 v[36:39], v[206:209], v[182:185], v[36:39]
	v_mfma_f32_16x16x32_bf16 v[28:31], v[232:235], v[182:185], v[28:31]
	v_mfma_f32_16x16x32_bf16 v[20:23], v[206:209], v[190:193], v[20:23]
	v_mfma_f32_16x16x32_bf16 v[12:15], v[232:235], v[190:193], v[12:15]
	v_mfma_f32_16x16x32_bf16 v[4:7], v[206:209], v[198:201], v[4:7]
	v_mfma_f32_16x16x32_bf16 v[0:3], v[232:235], v[198:201], v[0:3]
	v_mfma_f32_16x16x32_bf16 v[52:55], v[228:231], v[178:181], v[52:55]
	v_mfma_f32_16x16x32_bf16 v[44:47], v[236:239], v[178:181], v[44:47]
	v_mfma_f32_16x16x32_bf16 v[36:39], v[228:231], v[186:189], v[36:39]
	v_mfma_f32_16x16x32_bf16 v[28:31], v[236:239], v[186:189], v[28:31]
	v_mfma_f32_16x16x32_bf16 v[20:23], v[228:231], v[194:197], v[20:23]
	v_mfma_f32_16x16x32_bf16 v[12:15], v[236:239], v[194:197], v[12:15]
	v_mfma_f32_16x16x32_bf16 v[4:7], v[228:231], v[202:205], v[4:7]
	v_mfma_f32_16x16x32_bf16 v[0:3], v[236:239], v[202:205], v[0:3]
	s_setprio 0
	s_add_i32 s2, 0, 0x18000
	v_add_u32_e32 v140, s2, v168
	s_barrier
	ds_read_b128 v[154:157], v140
	ds_read_b128 v[158:161], v140 offset:1024
	ds_read_b128 v[162:165], v140 offset:2048
	ds_read_b128 v[170:173], v140 offset:3072
	s_add_u32 s30, s30, 0x40000
	s_addc_u32 s31, s31, 0
	s_mov_b32 m0, s38
	ds_read_b128 v[174:177], v169 offset:32768
	ds_read_b128 v[178:181], v169 offset:33792
	ds_read_b128 v[182:185], v169 offset:34816
	ds_read_b128 v[186:189], v169 offset:35840
	ds_read_b128 v[190:193], v169 offset:36864
	ds_read_b128 v[194:197], v169 offset:37888
	ds_read_b128 v[198:201], v169 offset:38912
	global_load_lds_dwordx4 v128, s[30:31]
	s_mov_b32 m0, s39
	ds_read_b128 v[202:205], v169 offset:39936
	global_load_lds_dwordx4 v132, s[30:31]
	s_waitcnt lgkmcnt(8)
	s_barrier
	s_waitcnt lgkmcnt(0)
	s_setprio 1
	v_mfma_f32_16x16x32_bf16 v[124:127], v[154:157], v[174:177], v[124:127]
	v_mfma_f32_16x16x32_bf16 v[120:123], v[162:165], v[174:177], v[120:123]
	v_mfma_f32_16x16x32_bf16 v[112:115], v[154:157], v[182:185], v[112:115]
	v_mfma_f32_16x16x32_bf16 v[104:107], v[162:165], v[182:185], v[104:107]
	v_mfma_f32_16x16x32_bf16 v[96:99], v[154:157], v[190:193], v[96:99]
	v_mfma_f32_16x16x32_bf16 v[88:91], v[162:165], v[190:193], v[88:91]
	v_mfma_f32_16x16x32_bf16 v[80:83], v[154:157], v[198:201], v[80:83]
	v_mfma_f32_16x16x32_bf16 v[72:75], v[162:165], v[198:201], v[72:75]
	v_mfma_f32_16x16x32_bf16 v[124:127], v[158:161], v[178:181], v[124:127]
	v_mfma_f32_16x16x32_bf16 v[120:123], v[170:173], v[178:181], v[120:123]
	v_mfma_f32_16x16x32_bf16 v[112:115], v[158:161], v[186:189], v[112:115]
	v_mfma_f32_16x16x32_bf16 v[104:107], v[170:173], v[186:189], v[104:107]
	v_mfma_f32_16x16x32_bf16 v[96:99], v[158:161], v[194:197], v[96:99]
	v_mfma_f32_16x16x32_bf16 v[88:91], v[170:173], v[194:197], v[88:91]
	v_mfma_f32_16x16x32_bf16 v[80:83], v[158:161], v[202:205], v[80:83]
	v_mfma_f32_16x16x32_bf16 v[72:75], v[170:173], v[202:205], v[72:75]
	s_setprio 0
	s_barrier
	s_add_i32 s30, 0, 0x1c000
	s_add_i32 s2, s2, s35
	v_add_u32_e32 v140, s30, v168
	s_mov_b32 m0, s2
	ds_read_b128 v[206:209], v140
	ds_read_b128 v[228:231], v140 offset:1024
	ds_read_b128 v[232:235], v140 offset:2048
	ds_read_b128 v[236:239], v140 offset:3072
	s_add_u32 s100, s0, 0x80
	s_addc_u32 s101, s1, 0
	global_load_lds_dwordx4 v130, s[100:101]
	s_add_i32 m0, s2, 0x2000
	s_nop 0
	global_load_lds_dwordx4 v134, s[100:101]
	s_barrier
	s_waitcnt lgkmcnt(0)
	s_setprio 1
	v_mfma_f32_16x16x32_bf16 v[116:119], v[206:209], v[174:177], v[116:119]
	v_mfma_f32_16x16x32_bf16 v[108:111], v[232:235], v[174:177], v[108:111]
	v_mfma_f32_16x16x32_bf16 v[100:103], v[206:209], v[182:185], v[100:103]
	v_mfma_f32_16x16x32_bf16 v[92:95], v[232:235], v[182:185], v[92:95]
	v_mfma_f32_16x16x32_bf16 v[84:87], v[206:209], v[190:193], v[84:87]
	v_mfma_f32_16x16x32_bf16 v[76:79], v[232:235], v[190:193], v[76:79]
	v_mfma_f32_16x16x32_bf16 v[68:71], v[206:209], v[198:201], v[68:71]
	v_mfma_f32_16x16x32_bf16 v[64:67], v[232:235], v[198:201], v[64:67]
	v_mfma_f32_16x16x32_bf16 v[116:119], v[228:231], v[178:181], v[116:119]
	v_mfma_f32_16x16x32_bf16 v[108:111], v[236:239], v[178:181], v[108:111]
	v_mfma_f32_16x16x32_bf16 v[100:103], v[228:231], v[186:189], v[100:103]
	v_mfma_f32_16x16x32_bf16 v[92:95], v[236:239], v[186:189], v[92:95]
	v_mfma_f32_16x16x32_bf16 v[84:87], v[228:231], v[194:197], v[84:87]
	v_mfma_f32_16x16x32_bf16 v[76:79], v[236:239], v[194:197], v[76:79]
	v_mfma_f32_16x16x32_bf16 v[68:71], v[228:231], v[202:205], v[68:71]
	v_mfma_f32_16x16x32_bf16 v[64:67], v[236:239], v[202:205], v[64:67]
	s_setprio 0
	s_mov_b32 m0, s44
	v_lshl_add_u64 v[166:167], v[240:241], 0, s[82:83]
	s_barrier
	ds_read_b128 v[174:177], v169 offset:49152
	ds_read_b128 v[178:181], v169 offset:50176
	ds_read_b128 v[182:185], v169 offset:51200
	ds_read_b128 v[186:189], v169 offset:52224
	ds_read_b128 v[190:193], v169 offset:53248
	ds_read_b128 v[194:197], v169 offset:54272
	ds_read_b128 v[198:201], v169 offset:55296
	ds_read_b128 v[202:205], v169 offset:56320
	global_load_lds_dwordx4 v[166:167], off
	v_lshl_add_u64 v[166:167], v[242:243], 0, s[82:83]
	s_mov_b32 m0, s45
	s_nop 0
	global_load_lds_dwordx4 v[166:167], off
	s_barrier
	s_waitcnt lgkmcnt(0)
	s_setprio 1
	v_mfma_f32_16x16x32_bf16 v[60:63], v[154:157], v[174:177], v[60:63]
	v_mfma_f32_16x16x32_bf16 v[56:59], v[162:165], v[174:177], v[56:59]
	v_mfma_f32_16x16x32_bf16 v[48:51], v[154:157], v[182:185], v[48:51]
	v_mfma_f32_16x16x32_bf16 v[40:43], v[162:165], v[182:185], v[40:43]
	v_mfma_f32_16x16x32_bf16 v[32:35], v[154:157], v[190:193], v[32:35]
	v_mfma_f32_16x16x32_bf16 v[24:27], v[162:165], v[190:193], v[24:27]
	v_mfma_f32_16x16x32_bf16 v[16:19], v[154:157], v[198:201], v[16:19]
	v_mfma_f32_16x16x32_bf16 v[8:11], v[162:165], v[198:201], v[8:11]
	v_mfma_f32_16x16x32_bf16 v[60:63], v[158:161], v[178:181], v[60:63]
	v_mfma_f32_16x16x32_bf16 v[56:59], v[170:173], v[178:181], v[56:59]
	v_mfma_f32_16x16x32_bf16 v[48:51], v[158:161], v[186:189], v[48:51]
	v_mfma_f32_16x16x32_bf16 v[40:43], v[170:173], v[186:189], v[40:43]
	v_mfma_f32_16x16x32_bf16 v[32:35], v[158:161], v[194:197], v[32:35]
	v_mfma_f32_16x16x32_bf16 v[24:27], v[170:173], v[194:197], v[24:27]
	v_mfma_f32_16x16x32_bf16 v[16:19], v[158:161], v[202:205], v[16:19]
	v_mfma_f32_16x16x32_bf16 v[8:11], v[170:173], v[202:205], v[8:11]
	s_setprio 0
	s_barrier
	s_add_i32 s2, s30, s35
	s_mov_b32 m0, s2
	s_add_u32 s0, s0, 0x40080
	s_addc_u32 s1, s1, 0
	global_load_lds_dwordx4 v130, s[0:1]
	s_add_i32 m0, s2, 0x2000
	s_nop 0
	global_load_lds_dwordx4 v134, s[0:1]
	s_waitcnt vmcnt(6)
	s_barrier
	s_setprio 1
	v_mfma_f32_16x16x32_bf16 v[52:55], v[206:209], v[174:177], v[52:55]
	v_mfma_f32_16x16x32_bf16 v[44:47], v[232:235], v[174:177], v[44:47]
	v_mfma_f32_16x16x32_bf16 v[36:39], v[206:209], v[182:185], v[36:39]
	v_mfma_f32_16x16x32_bf16 v[28:31], v[232:235], v[182:185], v[28:31]
	v_mfma_f32_16x16x32_bf16 v[20:23], v[206:209], v[190:193], v[20:23]
	v_mfma_f32_16x16x32_bf16 v[12:15], v[232:235], v[190:193], v[12:15]
	v_mfma_f32_16x16x32_bf16 v[4:7], v[206:209], v[198:201], v[4:7]
	v_mfma_f32_16x16x32_bf16 v[0:3], v[232:235], v[198:201], v[0:3]
	v_mfma_f32_16x16x32_bf16 v[52:55], v[228:231], v[178:181], v[52:55]
	v_mfma_f32_16x16x32_bf16 v[44:47], v[236:239], v[178:181], v[44:47]
	v_mfma_f32_16x16x32_bf16 v[36:39], v[228:231], v[186:189], v[36:39]
	v_mfma_f32_16x16x32_bf16 v[28:31], v[236:239], v[186:189], v[28:31]
	v_mfma_f32_16x16x32_bf16 v[20:23], v[228:231], v[194:197], v[20:23]
	v_mfma_f32_16x16x32_bf16 v[12:15], v[236:239], v[194:197], v[12:15]
	v_mfma_f32_16x16x32_bf16 v[4:7], v[228:231], v[202:205], v[4:7]
	v_mfma_f32_16x16x32_bf16 v[0:3], v[236:239], v[202:205], v[0:3]
	s_setprio 0
	s_add_i32 s21, s21, 2
	s_add_u32 s17, s17, 0x100
	s_addc_u32 s19, s19, 0
	s_add_u32 s8, s8, 0x100
	s_addc_u32 s9, s9, 0
	s_cmp_gt_u32 s21, 13
	s_barrier
	s_cbranch_scc0 .LBB0_507
	v_mbcnt_lo_u32_b32 v154, -1, 0
	v_mbcnt_hi_u32_b32 v154, -1, v154
	s_lshl_b32 s19, s16, 8
	v_and_b32_e32 v140, 15, v154
	v_ashrrev_i32_e32 v154, 1, v154
	s_cmp_lt_i32 s48, 8
	v_and_b32_e32 v170, -8, v154
	s_mov_b64 s[0:1], -1
	s_cbranch_scc0 .LBB0_552
	s_ashr_i32 s2, s48, 1
	s_mov_b32 s30, 0x3e38aa3b
	s_cmp_lt_u32 s48, 2
	s_mov_b64 s[8:9], s[24:25]
	s_cbranch_scc1 .LBB0_519
	s_cmp_lt_i32 s2, 2
	s_cbranch_scc1 .LBB0_514
	s_cmp_eq_u32 s2, 2
	s_cbranch_scc0 .LBB0_513
	s_mov_b64 s[0:1], 0
